# gen9: fp6 K tile image re-laid (key-half pairs share a 16-byte piece: 9 ds_read_b128 per tile), next tile's K fragments fetched during the PV MFMAs, trip barrier moved ahead of them, row-sum update de
# speedup vs baseline: 1.0215x; 1.0215x over previous
; DEVINL int tidx(const Params& p) { int l; asm volatile("v_mbcnt_lo_u32_b32 %0, -1, 0\n\tv_mbcnt_hi_u32_b32 %0, -1, %0" : "=v"(l)); return p.tid0 + l; }
; DEVINL unsigned char* wsp(const Params& p) { unsigned char* w = p.ws; asm volatile("" : "+s"(w)); return w; }
; DEVINL float bflo(unsigned u) { return __uint_as_float(u << 16); }
; DEVINL float bfhi(unsigned u) { return __uint_as_float(u & 0xffff0000u); }
; DEVINL void kpe_image(const Params& p, int tile, int lanen) {
;   const bf16_t* KPE = (const bf16_t*)(wsp(p) + OFF_KPE); char* KP8 = (char*)(wsp(p) + OFF_KP8);
;   const bf16_t* src = KPE + (size_t)tile * 4096 + lanen * 8;
;   float f[64];
; #pragma unroll
;   for (int kc = 0; kc < 8; ++kc) { const u32x4 w = *reinterpret_cast<const u32x4*>(src + kc * 512);
; #pragma unroll
;     for (int j = 0; j < 4; ++j) { f[kc * 8 + 2 * j] = bflo(w[j]); f[kc * 8 + 2 * j + 1] = bfhi(w[j]); } }
;   float ss = 0.f;
; #pragma unroll
;   for (int d = 0; d < 64; ++d) ss += f[d] * f[d];
;   const float r = rsqrtf(ss * (1.f / 64.f) + EPS);
;   const float pos = (float)(tile * 64 + lanen);
;   f32x16 a0, b0, a1, b1;
; #pragma unroll
;   for (int i = 0; i < 32; ++i) {
;     const float x1 = f[i] * r * p.kpe_w[i], x2 = f[i + 32] * r * p.kpe_w[i + 32];
;     const float invf = exp2f(-(float)i * (13.287712379549449f / 32.f));
;     const float ang = pos * invf;
;     const float k = rintf(ang * 0.15915494309189535f);
;     float rr = fmaf(-k, 6.2831855f, ang); rr = fmaf(-k, -1.7484555e-7f, rr);
;     const float c = __cosf(rr), s = __sinf(rr);
;     const float y1 = x1 * c - x2 * s, y2 = x2 * c + x1 * s;
;     if (i < 16) { a0[i] = y1; a1[i] = y2; } else { b0[i - 16] = y1; b1[i - 16] = y2; }
;   }
; DEVINL void phase_gemm1(const Params& p, char* lds) {
;     ...
;       { const int tid = tidx(p), w = tid >> 6; if (w < 4) kpe_image(p, pm * 4 + w, tid & 63); }
.LBB0_360:
	s_or_b64 exec, exec, s[4:5]
	s_waitcnt vmcnt(0)
	s_waitcnt vmcnt(0) lgkmcnt(0)
	s_barrier
	v_mbcnt_lo_u32_b32 v0, -1, 0
	v_mbcnt_hi_u32_b32 v0, -1, v0
	s_nop 0
	v_add_u32_e32 v0, s3, v0
	v_ashrrev_i32_e32 v1, 6, v0
	v_cmp_gt_i32_e32 vcc, 4, v1
	s_and_saveexec_b64 s[4:5], vcc
	s_cbranch_execz .LBB0_362
	v_lshl_add_u32 v66, s30, 2, v1
	v_and_b32_e32 v12, 63, v0
	v_lshlrev_b32_e32 v128, 3, v12
	v_lshlrev_b32_e32 v64, 4, v12
	v_lshl_or_b32 v12, v66, 6, v12
	v_cvt_f32_i32_e32 v32, v12
	v_ashrrev_i32_e32 v67, 31, v66
	s_mov_b64 s[8:9], s[72:73]
	v_lshlrev_b64 v[0:1], 13, v[66:67]
	v_mul_f32_e32 v33, 0x3c23d70b, v32
	v_mul_f32_e32 v34, 0.15915494, v33
	v_rndne_f32_e32 v34, v34
	v_fmac_f32_e32 v33, 0xc0c90fdb, v34
	v_fmac_f32_e32 v33, 0x343bbd2e, v34
	v_mul_f32_e32 v33, 0.15915494, v33
	v_sin_f32_e32 v50, v33
	v_cos_f32_e32 v48, v33
	v_mul_f32_e32 v33, 0x3bf5b9af, v32
	v_mul_f32_e32 v34, 0.15915494, v33
	v_rndne_f32_e32 v34, v34
	v_fmac_f32_e32 v33, 0xc0c90fdb, v34
	v_fmac_f32_e32 v33, 0x343bbd2e, v34
	v_mul_f32_e32 v33, 0.15915494, v33
	v_sin_f32_e32 v51, v33
	v_cos_f32_e32 v49, v33
	v_mul_f32_e32 v33, 0x3bb8449d, v32
	v_mul_f32_e32 v34, 0.15915494, v33
	v_rndne_f32_e32 v34, v34
	v_fmac_f32_e32 v33, 0xc0c90fdb, v34
	v_fmac_f32_e32 v33, 0x343bbd2e, v34
	v_mul_f32_e32 v33, 0.15915494, v33
	v_sin_f32_e32 v54, v33
	v_cos_f32_e32 v52, v33
	v_mul_f32_e32 v33, 0x3b8a2e7a, v32
	v_mul_f32_e32 v34, 0.15915494, v33
	v_rndne_f32_e32 v34, v34
	v_fmac_f32_e32 v33, 0xc0c90fdb, v34
	v_fmac_f32_e32 v33, 0x343bbd2e, v34
	v_mul_f32_e32 v33, 0.15915494, v33
	v_sin_f32_e32 v55, v33
	v_cos_f32_e32 v53, v33
	v_mul_f32_e32 v33, 0x3b4f3e39, v32
	v_mul_f32_e32 v34, 0.15915494, v33
	v_rndne_f32_e32 v34, v34
	v_fmac_f32_e32 v33, 0xc0c90fdb, v34
	v_fmac_f32_e32 v33, 0x343bbd2e, v34
	v_mul_f32_e32 v33, 0.15915494, v33
	v_sin_f32_e32 v58, v33
	v_cos_f32_e32 v56, v33
	v_mul_f32_e32 v33, 0x3b1b690c, v32
	v_mul_f32_e32 v34, 0.15915494, v33
	v_rndne_f32_e32 v34, v34
	v_fmac_f32_e32 v33, 0xc0c90fdb, v34
	v_fmac_f32_e32 v33, 0x343bbd2e, v34
	v_mul_f32_e32 v33, 0.15915494, v33
	v_sin_f32_e32 v59, v33
	v_cos_f32_e32 v57, v33
	v_mul_f32_e32 v33, 0x3ae9152f, v32
	v_mul_f32_e32 v34, 0.15915494, v33
	v_rndne_f32_e32 v34, v34
	v_fmac_f32_e32 v33, 0xc0c90fdb, v34
	v_fmac_f32_e32 v33, 0x343bbd2e, v34
	v_mul_f32_e32 v33, 0.15915494, v33
	v_sin_f32_e32 v68, v33
	v_cos_f32_e32 v60, v33
	v_mul_f32_e32 v33, 0x3aaec991, v32
	v_mul_f32_e32 v34, 0.15915494, v33
	v_rndne_f32_e32 v34, v34
	v_fmac_f32_e32 v33, 0xc0c90fdb, v34
	v_fmac_f32_e32 v33, 0x343bbd2e, v34
	v_mul_f32_e32 v33, 0.15915494, v33
	v_sin_f32_e32 v69, v33
	v_cos_f32_e32 v61, v33
	v_mul_f32_e32 v33, 0x3a831270, v32
	v_mul_f32_e32 v34, 0.15915494, v33
	v_rndne_f32_e32 v34, v34
	v_fmac_f32_e32 v33, 0xc0c90fdb, v34
	v_fmac_f32_e32 v33, 0x343bbd2e, v34
	v_mul_f32_e32 v33, 0.15915494, v33
	v_sin_f32_e32 v76, v33
	v_cos_f32_e32 v72, v33
	v_mul_f32_e32 v33, 0x3a44948c, v32
	v_mul_f32_e32 v34, 0.15915494, v33
	v_rndne_f32_e32 v34, v34
	v_fmac_f32_e32 v33, 0xc0c90fdb, v34
	v_fmac_f32_e32 v33, 0x343bbd2e, v34
	v_mul_f32_e32 v33, 0.15915494, v33
	v_sin_f32_e32 v77, v33
	v_cos_f32_e32 v73, v33
	v_mul_f32_e32 v33, 0x3a136a15, v32
	v_mul_f32_e32 v34, 0.15915494, v33
	v_mov_b32_e32 v65, v129
	v_lshl_add_u64 v[0:1], s[8:9], 0, v[0:1]
	v_rndne_f32_e32 v34, v34
	v_lshl_add_u64 v[4:5], v[0:1], 0, v[64:65]
	s_mov_b64 s[8:9], 0x5d0400
	v_fmac_f32_e32 v33, 0xc0c90fdb, v34
	v_lshl_add_u64 v[0:1], v[4:5], 0, s[8:9]
	s_mov_b32 s8, 0x5d0000
	v_fmac_f32_e32 v33, 0x343bbd2e, v34
	v_add_co_u32_e32 v2, vcc, s8, v4
	v_mul_f32_e32 v33, 0.15915494, v33
	s_mov_b64 s[6:7], s[72:73]
	v_addc_co_u32_e32 v3, vcc, 0, v5, vcc
	v_sin_f32_e32 v84, v33
	v_cos_f32_e32 v80, v33
	v_mul_f32_e32 v33, 0x39dd172a, v32
	flat_load_dwordx4 v[16:19], v[0:1] offset:1024
	flat_load_dwordx4 v[8:11], v[0:1] offset:2048
	flat_load_dwordx4 v[24:27], v[2:3] offset:1024
	s_nop 0
	flat_load_dwordx4 v[0:3], v[0:1] offset:3072
	v_mul_f32_e32 v34, 0.15915494, v33
	v_rndne_f32_e32 v34, v34
	v_fmac_f32_e32 v33, 0xc0c90fdb, v34
	v_fmac_f32_e32 v33, 0x343bbd2e, v34
	v_mul_f32_e32 v33, 0.15915494, v33
	v_sin_f32_e32 v85, v33
	v_cos_f32_e32 v81, v33
	v_mul_f32_e32 v33, 0x39a5cb61, v32
	v_mul_f32_e32 v34, 0.15915494, v33
	v_rndne_f32_e32 v34, v34
	v_fmac_f32_e32 v33, 0xc0c90fdb, v34
	v_fmac_f32_e32 v33, 0x343bbd2e, v34
	v_mul_f32_e32 v33, 0.15915494, v33
	v_sin_f32_e32 v92, v33
	v_cos_f32_e32 v88, v33
	v_mul_f32_e32 v33, 0x3978a814, v32
	v_mul_f32_e32 v34, 0.15915494, v33
	v_rndne_f32_e32 v34, v34
	v_fmac_f32_e32 v33, 0xc0c90fdb, v34
	v_fmac_f32_e32 v33, 0x343bbd2e, v34
	v_mul_f32_e32 v33, 0.15915494, v33
	v_sin_f32_e32 v93, v33
	v_cos_f32_e32 v89, v33
	v_mul_f32_e32 v33, 0x393a7759, v32
	v_mul_f32_e32 v34, 0.15915494, v33
	v_rndne_f32_e32 v34, v34
	v_fmac_f32_e32 v33, 0xc0c90fdb, v34
	v_fmac_f32_e32 v33, 0x343bbd2e, v34
	v_mul_f32_e32 v33, 0.15915494, v33
	v_sin_f32_e32 v100, v33
	v_cos_f32_e32 v96, v33
	v_mul_f32_e32 v33, 0x390bd475, v32
	v_mul_f32_e32 v34, 0.15915494, v33
	v_rndne_f32_e32 v34, v34
	v_fmac_f32_e32 v33, 0xc0c90fdb, v34
	v_fmac_f32_e32 v33, 0x343bbd2e, v34
	s_mov_b32 s8, 0x5d1000
	v_mul_f32_e32 v33, 0.15915494, v33
	v_add_co_u32_e32 v6, vcc, s8, v4
	v_sin_f32_e32 v101, v33
	v_cos_f32_e32 v97, v33
	v_mul_f32_e32 v33, 0.15915494, v32
	v_addc_co_u32_e32 v7, vcc, 0, v5, vcc
	v_rndne_f32_e32 v33, v33
	flat_load_dwordx4 v[28:31], v[6:7] offset:1024
	flat_load_dwordx4 v[20:23], v[6:7] offset:2048
	v_fmamk_f32 v34, v33, 0xc0c90fdb, v32
	v_fmac_f32_e32 v34, 0x343bbd2e, v33
	v_mul_f32_e32 v33, 0.15915494, v34
	v_sin_f32_e32 v70, v33
	v_cos_f32_e32 v62, v33
	v_mul_f32_e32 v33, 0x3f3ff911, v32
; DEVINL float bflo(unsigned u) { return __uint_as_float(u << 16); }
; DEVINL float bfhi(unsigned u) { return __uint_as_float(u & 0xffff0000u); }
; DEVINL void kpe_image(const Params& p, int tile, int lanen) {
;     ...
;   for (int kc = 0; kc < 8; ++kc) { const u32x4 w = *reinterpret_cast<const u32x4*>(src + kc * 512);
; #pragma unroll
;     for (int j = 0; j < 4; ++j) { f[kc * 8 + 2 * j] = bflo(w[j]); f[kc * 8 + 2 * j + 1] = bfhi(w[j]); } }
;   float ss = 0.f;
; #pragma unroll
;   for (int d = 0; d < 64; ++d) ss += f[d] * f[d];
;   const float r = rsqrtf(ss * (1.f / 64.f) + EPS);
;   const float pos = (float)(tile * 64 + lanen);
;   f32x16 a0, b0, a1, b1;
; #pragma unroll
;   for (int i = 0; i < 32; ++i) {
;     const float x1 = f[i] * r * p.kpe_w[i], x2 = f[i + 32] * r * p.kpe_w[i + 32];
;     const float invf = exp2f(-(float)i * (13.287712379549449f / 32.f));
;     const float ang = pos * invf;
;     const float k = rintf(ang * 0.15915494309189535f);
;     float rr = fmaf(-k, 6.2831855f, ang); rr = fmaf(-k, -1.7484555e-7f, rr);
;     const float c = __cosf(rr), s = __sinf(rr);
	v_mul_f32_e32 v34, 0.15915494, v33
	v_rndne_f32_e32 v34, v34
	v_fmac_f32_e32 v33, 0xc0c90fdb, v34
	v_fmac_f32_e32 v33, 0x343bbd2e, v34
	v_mul_f32_e32 v33, 0.15915494, v33
	v_sin_f32_e32 v71, v33
	v_cos_f32_e32 v63, v33
	v_mul_f32_e32 v33, 0x3f0ff59a, v32
	v_mul_f32_e32 v34, 0.15915494, v33
	v_rndne_f32_e32 v34, v34
	v_fmac_f32_e32 v33, 0xc0c90fdb, v34
	s_mov_b32 s8, 0x5d2000
	v_fmac_f32_e32 v33, 0x343bbd2e, v34
	v_add_co_u32_e32 v4, vcc, s8, v4
	v_mul_f32_e32 v33, 0.15915494, v33
	s_nop 0
	v_addc_co_u32_e32 v5, vcc, 0, v5, vcc
	v_sin_f32_e32 v78, v33
	v_cos_f32_e32 v74, v33
	v_mul_f32_e32 v33, 0x3ed7e89b, v32
	flat_load_dwordx4 v[12:15], v[6:7] offset:3072
	s_nop 0
	flat_load_dwordx4 v[4:7], v[4:5]
	v_mul_f32_e32 v34, 0.15915494, v33
	v_rndne_f32_e32 v34, v34
	v_fmac_f32_e32 v33, 0xc0c90fdb, v34
	v_fmac_f32_e32 v33, 0x343bbd2e, v34
	v_mul_f32_e32 v33, 0.15915494, v33
	v_sin_f32_e32 v79, v33
	v_cos_f32_e32 v75, v33
	v_mul_f32_e32 v33, 0x3ea1e89b, v32
	v_mul_f32_e32 v34, 0.15915494, v33
	v_rndne_f32_e32 v34, v34
	v_fmac_f32_e32 v33, 0xc0c90fdb, v34
	v_fmac_f32_e32 v33, 0x343bbd2e, v34
	v_mul_f32_e32 v33, 0.15915494, v33
	v_sin_f32_e32 v86, v33
	v_cos_f32_e32 v82, v33
	v_mul_f32_e32 v33, 0x3e72d424, v32
	v_mul_f32_e32 v34, 0.15915494, v33
	v_rndne_f32_e32 v34, v34
	v_fmac_f32_e32 v33, 0xc0c90fdb, v34
	v_fmac_f32_e32 v33, 0x343bbd2e, v34
	v_mul_f32_e32 v33, 0.15915494, v33
	v_sin_f32_e32 v87, v33
	v_cos_f32_e32 v83, v33
	v_mul_f32_e32 v33, 0x3e361888, v32
	v_mul_f32_e32 v34, 0.15915494, v33
	v_rndne_f32_e32 v34, v34
	v_fmac_f32_e32 v33, 0xc0c90fdb, v34
	v_fmac_f32_e32 v33, 0x343bbd2e, v34
	v_mul_f32_e32 v33, 0.15915494, v33
	v_sin_f32_e32 v94, v33
	v_cos_f32_e32 v90, v33
	v_mul_f32_e32 v33, 0x3e088d77, v32
	v_mul_f32_e32 v34, 0.15915494, v33
	v_rndne_f32_e32 v34, v34
	v_fmac_f32_e32 v33, 0xc0c90fdb, v34
	v_fmac_f32_e32 v33, 0x343bbd2e, v34
	v_mul_f32_e32 v33, 0.15915494, v33
	v_sin_f32_e32 v95, v33
	v_cos_f32_e32 v91, v33
	v_mul_f32_e32 v33, 0x3dcccccd, v32
	v_mul_f32_e32 v34, 0.15915494, v33
	v_rndne_f32_e32 v34, v34
	v_fmac_f32_e32 v33, 0xc0c90fdb, v34
	s_waitcnt vmcnt(0) lgkmcnt(0)
	v_lshlrev_b32_e32 v116, 16, v24
	v_and_b32_e32 v117, 0xffff0000, v24
	v_fmac_f32_e32 v33, 0x343bbd2e, v34
	v_pk_mul_f32 v[152:153], v[116:117], v[116:117]
	v_lshlrev_b32_e32 v120, 16, v25
	v_and_b32_e32 v121, 0xffff0000, v25
	v_mul_f32_e32 v33, 0.15915494, v33
	v_pk_mul_f32 v[172:173], v[120:121], v[120:121]
	v_add_f32_e32 v67, v152, v153
	v_sin_f32_e32 v102, v33
	v_cos_f32_e32 v98, v33
	v_mul_f32_e32 v33, 0x3d99940e, v32
	v_lshlrev_b32_e32 v124, 16, v26
	v_and_b32_e32 v125, 0xffff0000, v26
	v_add_f32_e32 v67, v172, v67
	v_mul_f32_e32 v34, 0.15915494, v33
	v_pk_mul_f32 v[176:177], v[124:125], v[124:125]
	v_add_f32_e32 v67, v173, v67
	v_rndne_f32_e32 v34, v34
	v_lshlrev_b32_e32 v130, 16, v27
	v_and_b32_e32 v131, 0xffff0000, v27
	v_add_f32_e32 v67, v176, v67
	v_fmac_f32_e32 v33, 0xc0c90fdb, v34
	v_pk_mul_f32 v[180:181], v[130:131], v[130:131]
	v_add_f32_e32 v67, v177, v67
	v_fmac_f32_e32 v33, 0x343bbd2e, v34
	v_lshlrev_b32_e32 v134, 16, v16
	v_and_b32_e32 v135, 0xffff0000, v16
	v_add_f32_e32 v67, v180, v67
	v_mul_f32_e32 v33, 0.15915494, v33
	v_pk_mul_f32 v[184:185], v[134:135], v[134:135]
	v_add_f32_e32 v67, v181, v67
	v_sin_f32_e32 v103, v33
	v_cos_f32_e32 v99, v33
	v_mul_f32_e32 v33, 0x3d6655c4, v32
	v_lshlrev_b32_e32 v138, 16, v17
	v_and_b32_e32 v139, 0xffff0000, v17
	v_add_f32_e32 v67, v184, v67
	v_mul_f32_e32 v34, 0.15915494, v33
	v_pk_mul_f32 v[188:189], v[138:139], v[138:139]
	v_add_f32_e32 v67, v185, v67
	v_rndne_f32_e32 v34, v34
	v_lshlrev_b32_e32 v142, 16, v18
	v_and_b32_e32 v143, 0xffff0000, v18
	v_add_f32_e32 v67, v188, v67
	v_fmac_f32_e32 v33, 0xc0c90fdb, v34
	v_pk_mul_f32 v[192:193], v[142:143], v[142:143]
	v_add_f32_e32 v67, v189, v67
	v_fmac_f32_e32 v33, 0x343bbd2e, v34
	v_lshlrev_b32_e32 v146, 16, v19
	v_and_b32_e32 v147, 0xffff0000, v19
	v_add_f32_e32 v67, v192, v67
	v_mul_f32_e32 v33, 0.15915494, v33
	v_pk_mul_f32 v[196:197], v[146:147], v[146:147]
	v_add_f32_e32 v67, v193, v67
	v_sin_f32_e32 v106, v33
	v_cos_f32_e32 v104, v33
	v_mul_f32_e32 v33, 0x3d2cba18, v32
	v_lshlrev_b32_e32 v200, 16, v8
	v_and_b32_e32 v201, 0xffff0000, v8
	v_add_f32_e32 v67, v196, v67
	v_mul_f32_e32 v34, 0.15915494, v33
	v_pk_mul_f32 v[204:205], v[200:201], v[200:201]
	v_add_f32_e32 v67, v197, v67
	v_rndne_f32_e32 v34, v34
	v_lshlrev_b32_e32 v8, 16, v9
	v_and_b32_e32 v9, 0xffff0000, v9
	v_add_f32_e32 v67, v204, v67
	v_fmac_f32_e32 v33, 0xc0c90fdb, v34
	v_pk_mul_f32 v[208:209], v[8:9], v[8:9]
	v_add_f32_e32 v67, v205, v67
	v_fmac_f32_e32 v33, 0x343bbd2e, v34
	v_lshlrev_b32_e32 v212, 16, v10
	v_and_b32_e32 v213, 0xffff0000, v10
	v_add_f32_e32 v67, v208, v67
	v_mul_f32_e32 v33, 0.15915494, v33
	v_pk_mul_f32 v[216:217], v[212:213], v[212:213]
	v_add_f32_e32 v67, v209, v67
	v_sin_f32_e32 v107, v33
	v_cos_f32_e32 v105, v33
	v_mul_f32_e32 v33, 0x3d0186e3, v32
	v_lshlrev_b32_e32 v10, 16, v11
	v_and_b32_e32 v11, 0xffff0000, v11
	v_add_f32_e32 v67, v216, v67
	v_mul_f32_e32 v34, 0.15915494, v33
	v_pk_mul_f32 v[220:221], v[10:11], v[10:11]
	v_add_f32_e32 v67, v217, v67
	v_rndne_f32_e32 v34, v34
	v_lshlrev_b32_e32 v224, 16, v0
	v_and_b32_e32 v225, 0xffff0000, v0
	v_add_f32_e32 v67, v220, v67
	v_fmac_f32_e32 v33, 0xc0c90fdb, v34
	v_pk_mul_f32 v[228:229], v[224:225], v[224:225]
	v_add_f32_e32 v67, v221, v67
	v_fmac_f32_e32 v33, 0x343bbd2e, v34
	v_lshlrev_b32_e32 v0, 16, v1
	v_and_b32_e32 v1, 0xffff0000, v1
	v_add_f32_e32 v67, v228, v67
	v_mul_f32_e32 v33, 0.15915494, v33
	v_pk_mul_f32 v[232:233], v[0:1], v[0:1]
	v_add_f32_e32 v67, v229, v67
	v_sin_f32_e32 v110, v33
	v_cos_f32_e32 v108, v33
; DEVINL float bflo(unsigned u) { return __uint_as_float(u << 16); }
; DEVINL float bfhi(unsigned u) { return __uint_as_float(u & 0xffff0000u); }
; DEVINL void kpe_image(const Params& p, int tile, int lanen) {
;     ...
;   for (int kc = 0; kc < 8; ++kc) { const u32x4 w = *reinterpret_cast<const u32x4*>(src + kc * 512);
; #pragma unroll
;     for (int j = 0; j < 4; ++j) { f[kc * 8 + 2 * j] = bflo(w[j]); f[kc * 8 + 2 * j + 1] = bfhi(w[j]); } }
;   float ss = 0.f;
; #pragma unroll
;   for (int d = 0; d < 64; ++d) ss += f[d] * f[d];
;   const float r = rsqrtf(ss * (1.f / 64.f) + EPS);
;   const float pos = (float)(tile * 64 + lanen);
;   f32x16 a0, b0, a1, b1;
; #pragma unroll
;   for (int i = 0; i < 32; ++i) {
;     const float x1 = f[i] * r * p.kpe_w[i], x2 = f[i + 32] * r * p.kpe_w[i + 32];
;     const float invf = exp2f(-(float)i * (13.287712379549449f / 32.f));
;     const float ang = pos * invf;
;     const float k = rintf(ang * 0.15915494309189535f);
;     float rr = fmaf(-k, 6.2831855f, ang); rr = fmaf(-k, -1.7484555e-7f, rr);
;     const float c = __cosf(rr), s = __sinf(rr);
	v_mul_f32_e32 v33, 0x3cc2434f, v32
	v_lshlrev_b32_e32 v236, 16, v2
	v_and_b32_e32 v237, 0xffff0000, v2
	v_add_f32_e32 v67, v232, v67
	v_mul_f32_e32 v34, 0.15915494, v33
	v_pk_mul_f32 v[240:241], v[236:237], v[236:237]
	v_add_f32_e32 v67, v233, v67
	v_rndne_f32_e32 v34, v34
	v_lshlrev_b32_e32 v2, 16, v3
	v_and_b32_e32 v3, 0xffff0000, v3
	v_add_f32_e32 v67, v240, v67
	v_fmac_f32_e32 v33, 0xc0c90fdb, v34
	v_pk_mul_f32 v[244:245], v[2:3], v[2:3]
	v_add_f32_e32 v67, v241, v67
	v_fmac_f32_e32 v33, 0x343bbd2e, v34
	v_lshlrev_b32_e32 v118, 16, v28
	v_and_b32_e32 v119, 0xffff0000, v28
	v_add_f32_e32 v67, v244, v67
	v_mul_f32_e32 v33, 0.15915494, v33
	v_pk_mul_f32 v[150:151], v[118:119], v[118:119]
	v_add_f32_e32 v67, v245, v67
	v_sin_f32_e32 v111, v33
	v_cos_f32_e32 v109, v33
	v_mul_f32_e32 v33, 0x3c91ad3a, v32
	v_lshlrev_b32_e32 v122, 16, v29
	v_and_b32_e32 v123, 0xffff0000, v29
	v_add_f32_e32 v67, v150, v67
	v_mul_f32_e32 v34, 0.15915494, v33
	v_pk_mul_f32 v[174:175], v[122:123], v[122:123]
	v_add_f32_e32 v67, v151, v67
	v_rndne_f32_e32 v34, v34
	v_lshlrev_b32_e32 v126, 16, v30
	v_and_b32_e32 v127, 0xffff0000, v30
	v_add_f32_e32 v67, v174, v67
	v_fmac_f32_e32 v33, 0xc0c90fdb, v34
	v_pk_mul_f32 v[178:179], v[126:127], v[126:127]
	v_add_f32_e32 v67, v175, v67
	v_fmac_f32_e32 v33, 0x343bbd2e, v34
	v_lshlrev_b32_e32 v132, 16, v31
	v_and_b32_e32 v133, 0xffff0000, v31
	v_add_f32_e32 v67, v178, v67
	v_mul_f32_e32 v33, 0.15915494, v33
	v_mul_f32_e32 v32, 0x3c5a7bf5, v32
	v_pk_mul_f32 v[182:183], v[132:133], v[132:133]
	v_add_f32_e32 v67, v179, v67
	v_sin_f32_e32 v114, v33
	v_cos_f32_e32 v112, v33
	v_mul_f32_e32 v33, 0.15915494, v32
	v_lshlrev_b32_e32 v136, 16, v20
	v_and_b32_e32 v137, 0xffff0000, v20
	v_add_f32_e32 v67, v182, v67
	v_rndne_f32_e32 v33, v33
	v_pk_mul_f32 v[186:187], v[136:137], v[136:137]
	v_add_f32_e32 v67, v183, v67
	v_fmac_f32_e32 v32, 0xc0c90fdb, v33
	v_lshlrev_b32_e32 v140, 16, v21
	v_and_b32_e32 v141, 0xffff0000, v21
	v_add_f32_e32 v67, v186, v67
	v_fmac_f32_e32 v32, 0x343bbd2e, v33
	v_pk_mul_f32 v[190:191], v[140:141], v[140:141]
	v_add_f32_e32 v67, v187, v67
	v_mul_f32_e32 v32, 0.15915494, v32
	v_lshlrev_b32_e32 v144, 16, v22
	v_and_b32_e32 v145, 0xffff0000, v22
	v_add_f32_e32 v67, v190, v67
	v_sin_f32_e32 v115, v32
	v_cos_f32_e32 v113, v32
	global_load_dwordx4 v[32:35], v129, s[58:59] offset:16
	global_load_dwordx4 v[36:39], v129, s[58:59]
	global_load_dwordx4 v[40:43], v129, s[58:59] offset:144
	global_load_dwordx4 v[44:47], v129, s[58:59] offset:128
	v_pk_mul_f32 v[194:195], v[144:145], v[144:145]
	v_lshlrev_b32_e32 v148, 16, v23
	v_and_b32_e32 v149, 0xffff0000, v23
	global_load_dwordx4 v[16:19], v129, s[58:59] offset:112
	global_load_dwordx4 v[20:23], v129, s[58:59] offset:96
	global_load_dwordx4 v[24:27], v129, s[58:59] offset:80
	global_load_dwordx4 v[28:31], v129, s[58:59] offset:64
	global_load_dwordx4 v[156:159], v129, s[58:59] offset:240
	global_load_dwordx4 v[160:163], v129, s[58:59] offset:224
	global_load_dwordx4 v[164:167], v129, s[58:59] offset:208
	global_load_dwordx4 v[168:171], v129, s[58:59] offset:192
	v_add_f32_e32 v67, v191, v67
	v_add_f32_e32 v67, v194, v67
	v_pk_mul_f32 v[198:199], v[148:149], v[148:149]
	v_add_f32_e32 v67, v195, v67
	v_lshlrev_b32_e32 v202, 16, v12
	v_and_b32_e32 v203, 0xffff0000, v12
	v_add_f32_e32 v67, v198, v67
	v_pk_mul_f32 v[206:207], v[202:203], v[202:203]
	v_add_f32_e32 v67, v199, v67
	v_lshlrev_b32_e32 v12, 16, v13
	v_and_b32_e32 v13, 0xffff0000, v13
	v_add_f32_e32 v67, v206, v67
	v_pk_mul_f32 v[210:211], v[12:13], v[12:13]
	v_add_f32_e32 v67, v207, v67
	v_lshlrev_b32_e32 v214, 16, v14
	v_and_b32_e32 v215, 0xffff0000, v14
	v_add_f32_e32 v67, v210, v67
	v_pk_mul_f32 v[218:219], v[214:215], v[214:215]
	v_add_f32_e32 v67, v211, v67
	v_lshlrev_b32_e32 v14, 16, v15
	v_and_b32_e32 v15, 0xffff0000, v15
	v_add_f32_e32 v67, v218, v67
	v_pk_mul_f32 v[222:223], v[14:15], v[14:15]
	v_add_f32_e32 v67, v219, v67
	v_lshlrev_b32_e32 v226, 16, v4
	v_and_b32_e32 v227, 0xffff0000, v4
	v_add_f32_e32 v67, v222, v67
	v_pk_mul_f32 v[230:231], v[226:227], v[226:227]
	v_add_f32_e32 v67, v223, v67
	v_lshlrev_b32_e32 v4, 16, v5
	v_and_b32_e32 v5, 0xffff0000, v5
	v_add_f32_e32 v67, v230, v67
	v_pk_mul_f32 v[234:235], v[4:5], v[4:5]
	v_add_f32_e32 v67, v231, v67
	v_lshlrev_b32_e32 v238, 16, v6
	v_and_b32_e32 v239, 0xffff0000, v6
	v_add_f32_e32 v67, v234, v67
	v_pk_mul_f32 v[242:243], v[238:239], v[238:239]
	v_add_f32_e32 v67, v235, v67
	v_lshlrev_b32_e32 v6, 16, v7
	v_and_b32_e32 v7, 0xffff0000, v7
	v_add_f32_e32 v67, v242, v67
	v_pk_mul_f32 v[152:153], v[6:7], v[6:7]
	v_add_f32_e32 v67, v243, v67
	v_add_f32_e32 v67, v152, v67
	v_add_f32_e32 v67, v153, v67
	v_fmamk_f32 v67, v67, 0x3c800000, v154
	s_mov_b32 s8, 0x800000
	v_mul_f32_e32 v150, 0x4b800000, v67
	v_cmp_gt_f32_e32 vcc, s8, v67
	s_nop 1
	v_cndmask_b32_e32 v67, v67, v150, vcc
	global_load_dwordx4 v[150:153], v129, s[58:59] offset:48
	global_load_dwordx4 v[172:175], v129, s[58:59] offset:32
	global_load_dwordx4 v[176:179], v129, s[58:59] offset:176
	global_load_dwordx4 v[180:183], v129, s[58:59] offset:160
	v_rsq_f32_e32 v67, v67
	s_nop 0
	v_mul_f32_e32 v184, 0x45800000, v67
	v_cndmask_b32_e32 v184, v67, v184, vcc
	v_pk_mul_f32 v[8:9], v[184:185], v[8:9] op_sel_hi:[0,1]
	v_pk_mul_f32 v[186:187], v[184:185], v[200:201] op_sel_hi:[0,1]
	v_pk_mul_f32 v[0:1], v[184:185], v[0:1] op_sel_hi:[0,1]
	s_waitcnt vmcnt(8)
	v_pk_mul_f32 v[30:31], v[30:31], v[8:9]
	v_pk_mul_f32 v[8:9], v[184:185], v[12:13] op_sel_hi:[0,1]
	v_pk_mul_f32 v[28:29], v[28:29], v[186:187]
	v_pk_mul_f32 v[186:187], v[184:185], v[202:203] op_sel_hi:[0,1]
	s_waitcnt vmcnt(4)
; DEVINL void kpe_image(const Params& p, int tile, int lanen) {
;     ...
;     const float x1 = f[i] * r * p.kpe_w[i], x2 = f[i + 32] * r * p.kpe_w[i + 32];
;     const float invf = exp2f(-(float)i * (13.287712379549449f / 32.f));
;     const float ang = pos * invf;
;     const float k = rintf(ang * 0.15915494309189535f);
;     float rr = fmaf(-k, 6.2831855f, ang); rr = fmaf(-k, -1.7484555e-7f, rr);
;     const float c = __cosf(rr), s = __sinf(rr);
;     const float y1 = x1 * c - x2 * s, y2 = x2 * c + x1 * s;
;     if (i < 16) { a0[i] = y1; a1[i] = y2; } else { b0[i - 16] = y1; b1[i - 16] = y2; }
	v_pk_mul_f32 v[170:171], v[170:171], v[8:9]
	v_pk_mul_f32 v[8:9], v[184:185], v[212:213] op_sel_hi:[0,1]
	v_pk_mul_f32 v[24:25], v[24:25], v[8:9]
	v_pk_mul_f32 v[8:9], v[184:185], v[214:215] op_sel_hi:[0,1]
	v_pk_mul_f32 v[164:165], v[164:165], v[8:9]
	v_pk_mul_f32 v[8:9], v[184:185], v[10:11] op_sel_hi:[0,1]
	v_pk_mul_f32 v[26:27], v[26:27], v[8:9]
	v_pk_mul_f32 v[8:9], v[184:185], v[14:15] op_sel_hi:[0,1]
	v_pk_mul_f32 v[166:167], v[166:167], v[8:9]
	v_pk_mul_f32 v[8:9], v[184:185], v[224:225] op_sel_hi:[0,1]
	v_pk_mul_f32 v[168:169], v[168:169], v[186:187]
	v_pk_mul_f32 v[186:187], v[20:21], v[8:9]
	v_pk_mul_f32 v[8:9], v[184:185], v[226:227] op_sel_hi:[0,1]
	v_pk_mul_f32 v[20:21], v[160:161], v[8:9]
	v_pk_mul_f32 v[160:161], v[22:23], v[0:1]
	v_pk_mul_f32 v[0:1], v[184:185], v[4:5] op_sel_hi:[0,1]
	v_pk_mul_f32 v[22:23], v[162:163], v[0:1]
	v_pk_mul_f32 v[0:1], v[184:185], v[236:237] op_sel_hi:[0,1]
	v_pk_mul_f32 v[162:163], v[16:17], v[0:1]
	v_pk_mul_f32 v[0:1], v[184:185], v[238:239] op_sel_hi:[0,1]
	v_pk_mul_f32 v[16:17], v[156:157], v[0:1]
	v_pk_mul_f32 v[0:1], v[184:185], v[2:3] op_sel_hi:[0,1]
	v_pk_mul_f32 v[156:157], v[18:19], v[0:1]
	v_pk_mul_f32 v[0:1], v[184:185], v[6:7] op_sel_hi:[0,1]
	v_pk_mul_f32 v[18:19], v[158:159], v[0:1]
	v_pk_mul_f32 v[0:1], v[48:49], v[168:169]
	v_pk_mul_f32 v[12:13], v[88:89], v[16:17]
	v_pk_fma_f32 v[0:1], v[50:51], v[28:29], v[0:1]
	v_pk_mul_f32 v[50:51], v[50:51], v[168:169]
	v_pk_fma_f32 v[12:13], v[92:93], v[162:163], v[12:13]
	v_pk_mul_f32 v[92:93], v[92:93], v[16:17]
	v_pk_fma_f32 v[16:17], v[48:49], v[28:29], v[50:51] neg_lo:[0,0,1] neg_hi:[0,0,1]
	v_pk_mul_f32 v[48:49], v[184:185], v[116:117] op_sel_hi:[0,1]
	v_pk_mul_f32 v[2:3], v[52:53], v[170:171]
	v_pk_mul_f32 v[48:49], v[36:37], v[48:49]
	v_pk_mul_f32 v[36:37], v[184:185], v[118:119] op_sel_hi:[0,1]
	v_pk_mul_f32 v[14:15], v[96:97], v[18:19]
	v_pk_fma_f32 v[2:3], v[54:55], v[30:31], v[2:3]
	v_pk_mul_f32 v[54:55], v[54:55], v[170:171]
	v_pk_mul_f32 v[50:51], v[44:45], v[36:37]
	v_pk_mul_f32 v[36:37], v[184:185], v[120:121] op_sel_hi:[0,1]
	v_pk_mul_f32 v[4:5], v[56:57], v[164:165]
	v_pk_fma_f32 v[14:15], v[100:101], v[156:157], v[14:15]
	v_pk_mul_f32 v[100:101], v[100:101], v[18:19]
	v_pk_fma_f32 v[18:19], v[52:53], v[30:31], v[54:55] neg_lo:[0,0,1] neg_hi:[0,0,1]
	v_pk_mul_f32 v[52:53], v[38:39], v[36:37]
	v_pk_mul_f32 v[36:37], v[184:185], v[122:123] op_sel_hi:[0,1]
	v_pk_mul_f32 v[8:9], v[72:73], v[20:21]
	v_pk_fma_f32 v[4:5], v[58:59], v[24:25], v[4:5]
	v_pk_mul_f32 v[58:59], v[58:59], v[164:165]
	v_pk_mul_f32 v[54:55], v[46:47], v[36:37]
	v_pk_mul_f32 v[36:37], v[184:185], v[124:125] op_sel_hi:[0,1]
	v_pk_mul_f32 v[6:7], v[60:61], v[166:167]
	v_pk_fma_f32 v[8:9], v[76:77], v[186:187], v[8:9]
	v_pk_mul_f32 v[76:77], v[76:77], v[20:21]
	v_pk_fma_f32 v[20:21], v[56:57], v[24:25], v[58:59] neg_lo:[0,0,1] neg_hi:[0,0,1]
	v_pk_mul_f32 v[56:57], v[32:33], v[36:37]
	v_pk_mul_f32 v[32:33], v[184:185], v[126:127] op_sel_hi:[0,1]
	v_pk_mul_f32 v[10:11], v[80:81], v[22:23]
	v_pk_fma_f32 v[6:7], v[68:69], v[26:27], v[6:7]
	v_pk_mul_f32 v[68:69], v[68:69], v[166:167]
	v_pk_mul_f32 v[58:59], v[40:41], v[32:33]
	v_pk_mul_f32 v[32:33], v[184:185], v[130:131] op_sel_hi:[0,1]
	v_pk_fma_f32 v[10:11], v[84:85], v[160:161], v[10:11]
	v_pk_mul_f32 v[84:85], v[84:85], v[22:23]
	v_pk_fma_f32 v[22:23], v[60:61], v[26:27], v[68:69] neg_lo:[0,0,1] neg_hi:[0,0,1]
	v_pk_mul_f32 v[60:61], v[34:35], v[32:33]
	v_pk_mul_f32 v[32:33], v[184:185], v[132:133] op_sel_hi:[0,1]
	v_pk_mul_f32 v[68:69], v[42:43], v[32:33]
	v_pk_mul_f32 v[32:33], v[184:185], v[134:135] op_sel_hi:[0,1]
	v_pk_fma_f32 v[24:25], v[72:73], v[186:187], v[76:77] neg_lo:[0,0,1] neg_hi:[0,0,1]
	s_waitcnt vmcnt(2)
	v_pk_mul_f32 v[72:73], v[172:173], v[32:33]
	v_pk_mul_f32 v[32:33], v[184:185], v[136:137] op_sel_hi:[0,1]
	s_waitcnt vmcnt(0)
; DEVINL i32x6 pk6(const f32x16& a, const f32x16& b) { return __builtin_amdgcn_cvt_scalef32_2xpk16_fp6_f32(a, b, 1.0f); }
; DEVINL void kpe_image(const Params& p, int tile, int lanen) {
;     ...
;   for (int i = 0; i < 32; ++i) {
;     const float x1 = f[i] * r * p.kpe_w[i], x2 = f[i + 32] * r * p.kpe_w[i + 32];
;     const float invf = exp2f(-(float)i * (13.287712379549449f / 32.f));
;     const float ang = pos * invf;
;     const float k = rintf(ang * 0.15915494309189535f);
;     float rr = fmaf(-k, 6.2831855f, ang); rr = fmaf(-k, -1.7484555e-7f, rr);
;     const float c = __cosf(rr), s = __sinf(rr);
;     const float y1 = x1 * c - x2 * s, y2 = x2 * c + x1 * s;
;     if (i < 16) { a0[i] = y1; a1[i] = y2; } else { b0[i - 16] = y1; b1[i - 16] = y2; }
;   }
;   char* dst = KP8 + (size_t)tile * 3072;
;   const i32x6 w0 = pk6(a0, b0), w1 = pk6(a1, b1);
;   u32x4 wa0 = {(unsigned)w0[0], (unsigned)w0[1], (unsigned)w0[2], (unsigned)w0[3]}, wa1 = {(unsigned)w1[0], (unsigned)w1[1], (unsigned)w1[2], (unsigned)w1[3]};
;   u32x2 wb0 = {(unsigned)w0[4], (unsigned)w0[5]}, wb1 = {(unsigned)w1[4], (unsigned)w1[5]};
;   *reinterpret_cast<u32x4*>(dst + lanen * 16) = wa0; *reinterpret_cast<u32x4*>(dst + 1024 + lanen * 16) = wa1;
;   *reinterpret_cast<u32x2*>(dst + 2048 + lanen * 8) = wb0; *reinterpret_cast<u32x2*>(dst + 2048 + 512 + lanen * 8) = wb1;
	v_pk_mul_f32 v[76:77], v[180:181], v[32:33]
	v_pk_mul_f32 v[32:33], v[184:185], v[138:139] op_sel_hi:[0,1]
	v_pk_fma_f32 v[26:27], v[80:81], v[160:161], v[84:85] neg_lo:[0,0,1] neg_hi:[0,0,1]
	v_pk_mul_f32 v[80:81], v[174:175], v[32:33]
	v_pk_mul_f32 v[32:33], v[184:185], v[140:141] op_sel_hi:[0,1]
	v_pk_mul_f32 v[84:85], v[182:183], v[32:33]
	v_pk_mul_f32 v[32:33], v[184:185], v[142:143] op_sel_hi:[0,1]
	v_pk_fma_f32 v[28:29], v[88:89], v[162:163], v[92:93] neg_lo:[0,0,1] neg_hi:[0,0,1]
	v_pk_mul_f32 v[88:89], v[150:151], v[32:33]
	v_pk_mul_f32 v[32:33], v[184:185], v[144:145] op_sel_hi:[0,1]
	v_pk_mul_f32 v[92:93], v[176:177], v[32:33]
	v_pk_mul_f32 v[32:33], v[184:185], v[146:147] op_sel_hi:[0,1]
	v_pk_fma_f32 v[30:31], v[96:97], v[156:157], v[100:101] neg_lo:[0,0,1] neg_hi:[0,0,1]
	v_pk_mul_f32 v[96:97], v[152:153], v[32:33]
	v_pk_mul_f32 v[32:33], v[184:185], v[148:149] op_sel_hi:[0,1]
	v_pk_mul_f32 v[100:101], v[178:179], v[32:33]
	v_pk_mul_f32 v[32:33], v[62:63], v[50:51]
	v_pk_mul_f32 v[34:35], v[74:75], v[54:55]
	v_pk_mul_f32 v[38:39], v[90:91], v[68:69]
	v_pk_mul_f32 v[50:51], v[70:71], v[50:51]
	v_pk_mul_f32 v[54:55], v[78:79], v[54:55]
	v_pk_mul_f32 v[68:69], v[94:95], v[68:69]
	v_pk_fma_f32 v[32:33], v[70:71], v[48:49], v[32:33]
	v_pk_fma_f32 v[48:49], v[62:63], v[48:49], v[50:51] neg_lo:[0,0,1] neg_hi:[0,0,1]
	v_pk_fma_f32 v[50:51], v[74:75], v[52:53], v[54:55] neg_lo:[0,0,1] neg_hi:[0,0,1]
	v_pk_fma_f32 v[54:55], v[90:91], v[60:61], v[68:69] neg_lo:[0,0,1] neg_hi:[0,0,1]
	v_mov_b64_e32 v[68:69], s[6:7]
	s_movk_i32 s6, 0xc00
	v_mad_i64_i32 v[66:67], s[6:7], v66, s6, v[68:69]
	v_pk_mul_f32 v[36:37], v[82:83], v[58:59]
	v_pk_mul_f32 v[40:41], v[98:99], v[76:77]
	v_pk_mul_f32 v[42:43], v[104:105], v[84:85]
	v_pk_mul_f32 v[44:45], v[108:109], v[92:93]
	v_pk_mul_f32 v[46:47], v[112:113], v[100:101]
	v_pk_fma_f32 v[34:35], v[78:79], v[52:53], v[34:35]
	v_pk_mul_f32 v[58:59], v[86:87], v[58:59]
	v_pk_mul_f32 v[70:71], v[102:103], v[76:77]
	v_pk_mul_f32 v[76:77], v[106:107], v[84:85]
	v_pk_mul_f32 v[78:79], v[110:111], v[92:93]
	v_pk_mul_f32 v[84:85], v[114:115], v[100:101]
	s_mov_b64 s[6:7], 0xfa58400
	v_pk_fma_f32 v[36:37], v[86:87], v[56:57], v[36:37]
	v_pk_fma_f32 v[38:39], v[94:95], v[60:61], v[38:39]
	v_pk_fma_f32 v[40:41], v[102:103], v[72:73], v[40:41]
	v_pk_fma_f32 v[42:43], v[106:107], v[80:81], v[42:43]
	v_pk_fma_f32 v[44:45], v[110:111], v[88:89], v[44:45]
	v_pk_fma_f32 v[46:47], v[114:115], v[96:97], v[46:47]
	v_pk_fma_f32 v[52:53], v[82:83], v[56:57], v[58:59] neg_lo:[0,0,1] neg_hi:[0,0,1]
	v_pk_fma_f32 v[56:57], v[98:99], v[72:73], v[70:71] neg_lo:[0,0,1] neg_hi:[0,0,1]
	v_pk_fma_f32 v[58:59], v[104:105], v[80:81], v[76:77] neg_lo:[0,0,1] neg_hi:[0,0,1]
	v_pk_fma_f32 v[60:61], v[108:109], v[88:89], v[78:79] neg_lo:[0,0,1] neg_hi:[0,0,1]
	v_pk_fma_f32 v[62:63], v[112:113], v[96:97], v[84:85] neg_lo:[0,0,1] neg_hi:[0,0,1]
	v_lshl_add_u64 v[66:67], v[66:67], 0, s[6:7]
	v_cvt_scalef32_2xpk16_fp6_f32 v[16:21], v[48:63], v[16:31], 1.0
	v_cvt_scalef32_2xpk16_fp6_f32 v[0:5], v[32:47], v[0:15], 1.0
	v_lshl_add_u64 v[6:7], v[66:67], 0, v[64:65]
	v_lshrrev_b32_e32 v33, 9, v64
	v_mul_u32_u24_e32 v33, 0x1f8, v33
	v_sub_u32_e32 v32, v64, v33
	v_mov_b32_e32 v33, 0
	v_lshl_add_u64 v[32:33], v[66:67], 0, v[32:33]
	s_mov_b64 s[100:101], exec
	s_mov_b32 s98, -1
	s_mov_b32 s99, 0
	s_and_b64 exec, s[100:101], s[98:99]
	flat_store_dwordx4 v[6:7], v[16:19]
	flat_store_dwordx4 v[6:7], v[0:3] offset:1024
	flat_store_dwordx2 v[32:33], v[20:21] offset:2048
	flat_store_dwordx2 v[32:33], v[4:5] offset:2560
	s_andn2_b64 exec, s[100:101], s[98:99]
	flat_store_dwordx4 v[6:7], v[18:21]
	flat_store_dwordx4 v[6:7], v[2:5] offset:1024
	flat_store_dwordx2 v[32:33], v[16:17] offset:2048
	flat_store_dwordx2 v[32:33], v[0:1] offset:2560
	s_mov_b64 exec, s[100:101]

; DEVINL unsigned cvtpk(float lo, float hi) { unsigned r; asm("v_cvt_pk_bf16_f32 %0, %1, %2" : "=v"(r) : "v"(lo), "v"(hi)); return r; }
; template <bool SWAP, class Epi>
; DEVINL void gemm_tile(const Params& p, const bf16_t* __restrict__ A0, const bf16_t* __restrict__ A1, int ksplit, int lda,
;                       const bf16_t* __restrict__ Bt, int ldb, int nt, char* shmc, Epi epi) {
;     ...
;   for (int ai = 0; ai < 2; ++ai)
; #pragma unroll
;     for (int bj = 0; bj < 2; ++bj)
; #pragma unroll
;       for (int m = 0; m < 4; ++m)
; #pragma unroll
;         for (int n = 0; n < 2; ++n) {
;           if (SWAP) epi(ai * HALF + wr * 64 + m * 16 + fr, bj * HALF + wc * 32 + n * 16 + fq * 4, acc[ai][bj][m][n]);
;           else      epi(ai * HALF + wr * 64 + m * 16 + fq * 4, bj * HALF + wc * 32 + n * 16 + fr, acc[ai][bj][m][n]);
;         }
; DEVINL void phase_gemm2(const Params& p, char* lds) {
;     ...
;       gemm_tile<true>(p, A, A, 1 << 30, 512, WukvT + (size_t)pn * 256 * KVR, KVR, KVR / BK, lds, [=](int row, int col, f32x4 v) {
;         const float s = rs[row];
;         u32x2 w = {cvtpk(v[0] * s, v[1] * s), cvtpk(v[2] * s, v[3] * s)};
;         const int t = grow0 + row, tile = t >> 6, k = t & 63, h = pn * 2 + (col >> 7), d = col & 127;
;         *reinterpret_cast<u32x2*>(KN + (size_t)h * LP * 128 + ((size_t)(tile * 16 + (d >> 3)) * 64 + k) * 8 + (d & 7)) = w;
;       });
.LBB0_462:
	s_or_b64 exec, exec, s[4:5]
	v_lshlrev_b32_e32 v136, 6, v130
	v_or_b32_e32 v138, v136, v132
	s_add_i32 s5, 0, 0x20000
	v_lshl_add_u32 v139, v138, 2, s5
	ds_read_b32 v140, v139
	v_lshlrev_b32_e32 v128, 3, v133
	v_lshlrev_b32_e32 v130, 2, v133
	v_and_b32_e32 v128, 8, v128
	v_lshl_add_u64 v[134:135], s[10:11], 0, v[128:129]
	v_lshl_or_b32 v137, v131, 5, v130
	v_add_u32_e32 v128, s16, v136
	s_waitcnt lgkmcnt(0)
	v_mul_f32_e32 v124, v124, v140
	v_mul_f32_e32 v125, v125, v140
	v_ashrrev_i32_e32 v141, 2, v128
	v_cvt_pk_bf16_f32 v124, v124, v125
	v_mul_f32_e32 v125, v126, v140
	v_mul_f32_e32 v126, v127, v140
	v_lshrrev_b32_e32 v140, 3, v137
	s_lshl_b32 s4, s28, 1
	v_cvt_pk_bf16_f32 v125, v125, v126
	v_or_b32_e32 v126, v140, v141
	v_mad_i64_i32 v[130:131], s[28:29], s4, v229, v[134:135]
	v_lshlrev_b32_e32 v128, 4, v132
	v_ashrrev_i32_e32 v127, 31, v126
	v_lshl_add_u64 v[132:133], v[130:131], 0, v[128:129]
	v_lshlrev_b64 v[126:127], 10, v[126:127]
	v_lshl_add_u64 v[136:137], v[132:133], 0, v[126:127]
	flat_store_dwordx2 v[136:137], v[124:125]
	ds_read_b32 v124, v139
	v_or_b32_e32 v136, 2, v140
	s_waitcnt lgkmcnt(0)
	v_mul_f32_e32 v120, v120, v124
	v_mul_f32_e32 v121, v121, v124
	v_cvt_pk_bf16_f32 v120, v120, v121
	v_mul_f32_e32 v121, v122, v124
	v_mul_f32_e32 v122, v123, v124
	v_cvt_pk_bf16_f32 v121, v121, v122
	v_or_b32_e32 v122, v136, v141
	v_ashrrev_i32_e32 v123, 31, v122
	v_lshlrev_b64 v[122:123], 10, v[122:123]
	v_lshl_add_u64 v[124:125], v[132:133], 0, v[122:123]
	flat_store_dwordx2 v[124:125], v[120:121]
	v_or_b32_e32 v120, 16, v138
	v_lshl_add_u32 v137, v120, 2, s5
	ds_read_b32 v141, v137
	v_lshlrev_b32_e32 v120, 4, v120
	v_and_b32_e32 v120, 0x1f0, v120
	v_mov_b32_e32 v121, v129
	v_lshl_add_u64 v[124:125], v[130:131], 0, v[120:121]
	s_waitcnt lgkmcnt(0)
	v_mul_f32_e32 v116, v116, v141
	v_mul_f32_e32 v117, v117, v141
	v_cvt_pk_bf16_f32 v116, v116, v117
	v_mul_f32_e32 v117, v118, v141
	v_mul_f32_e32 v118, v119, v141
	v_cvt_pk_bf16_f32 v117, v117, v118
	v_lshl_add_u64 v[118:119], v[124:125], 0, v[126:127]
	flat_store_dwordx2 v[118:119], v[116:117]
	ds_read_b32 v116, v137
	s_waitcnt lgkmcnt(0)
	v_mul_f32_e32 v112, v112, v116
	v_mul_f32_e32 v113, v113, v116
	v_cvt_pk_bf16_f32 v112, v112, v113
	v_mul_f32_e32 v113, v114, v116
	v_mul_f32_e32 v114, v115, v116
	v_cvt_pk_bf16_f32 v113, v113, v114
	v_lshl_add_u64 v[114:115], v[124:125], 0, v[122:123]
	flat_store_dwordx2 v[114:115], v[112:113]
	v_or_b32_e32 v112, 32, v138
	v_lshl_add_u32 v116, v112, 2, s5
	ds_read_b32 v117, v116
	v_lshlrev_b32_e32 v112, 4, v112
	v_and_b32_e32 v112, 0x2f0, v112
	v_mov_b32_e32 v113, v129
	v_lshl_add_u64 v[114:115], v[130:131], 0, v[112:113]
	s_waitcnt lgkmcnt(0)
	v_mul_f32_e32 v108, v108, v117
	v_mul_f32_e32 v109, v109, v117
	v_cvt_pk_bf16_f32 v108, v108, v109
	v_mul_f32_e32 v109, v110, v117
	v_mul_f32_e32 v110, v111, v117
	v_cvt_pk_bf16_f32 v109, v109, v110
	v_lshl_add_u64 v[110:111], v[114:115], 0, v[126:127]
	flat_store_dwordx2 v[110:111], v[108:109]
	ds_read_b32 v108, v116
	s_waitcnt lgkmcnt(0)
	v_mul_f32_e32 v104, v104, v108
	v_mul_f32_e32 v105, v105, v108
	v_cvt_pk_bf16_f32 v104, v104, v105
	v_mul_f32_e32 v105, v106, v108
	v_mul_f32_e32 v106, v107, v108
	v_cvt_pk_bf16_f32 v105, v105, v106
	v_lshl_add_u64 v[106:107], v[114:115], 0, v[122:123]
	flat_store_dwordx2 v[106:107], v[104:105]
	v_or_b32_e32 v104, 48, v138
	v_lshl_add_u32 v108, v104, 2, s5
	ds_read_b32 v109, v108
	v_lshlrev_b32_e32 v104, 4, v104
	v_and_b32_e32 v104, 0x3f0, v104
	v_mov_b32_e32 v105, v129
	v_lshl_add_u64 v[106:107], v[130:131], 0, v[104:105]
	s_waitcnt lgkmcnt(0)
	v_mul_f32_e32 v100, v100, v109
	v_mul_f32_e32 v101, v101, v109
	v_cvt_pk_bf16_f32 v100, v100, v101
	v_mul_f32_e32 v101, v102, v109
	v_mul_f32_e32 v102, v103, v109
	v_cvt_pk_bf16_f32 v101, v101, v102
	v_lshl_add_u64 v[102:103], v[106:107], 0, v[126:127]
	flat_store_dwordx2 v[102:103], v[100:101]
	ds_read_b32 v100, v108
	s_or_b32 s5, s4, 1
	s_waitcnt lgkmcnt(0)
	v_mul_f32_e32 v96, v96, v100
	v_mul_f32_e32 v97, v97, v100
	v_cvt_pk_bf16_f32 v96, v96, v97
	v_mul_f32_e32 v97, v98, v100
	v_mul_f32_e32 v98, v99, v100
	v_cvt_pk_bf16_f32 v97, v97, v98
	v_lshl_add_u64 v[98:99], v[106:107], 0, v[122:123]
	flat_store_dwordx2 v[98:99], v[96:97]
	ds_read_b32 v100, v139
	v_mad_i64_i32 v[96:97], s[28:29], s5, v229, v[134:135]
	v_lshl_add_u64 v[98:99], v[96:97], 0, v[128:129]
	s_mov_b64 s[28:29], s[72:73]
	s_waitcnt lgkmcnt(0)
	v_mul_f32_e32 v92, v92, v100
	v_mul_f32_e32 v93, v93, v100
	v_cvt_pk_bf16_f32 v92, v92, v93
	v_mul_f32_e32 v93, v94, v100
	v_mul_f32_e32 v94, v95, v100
	v_cvt_pk_bf16_f32 v93, v93, v94
	v_lshl_add_u64 v[94:95], v[98:99], 0, v[126:127]
	flat_store_dwordx2 v[94:95], v[92:93]
	ds_read_b32 v92, v139
	s_waitcnt lgkmcnt(0)
	v_mul_f32_e32 v88, v88, v92
	v_mul_f32_e32 v89, v89, v92
	v_cvt_pk_bf16_f32 v88, v88, v89
	v_mul_f32_e32 v89, v90, v92
	v_mul_f32_e32 v90, v91, v92
	v_cvt_pk_bf16_f32 v89, v89, v90
	v_lshl_add_u64 v[90:91], v[98:99], 0, v[122:123]
	flat_store_dwordx2 v[90:91], v[88:89]
	ds_read_b32 v90, v137
	v_lshl_add_u64 v[88:89], v[96:97], 0, v[120:121]
	s_waitcnt lgkmcnt(0)
	v_mul_f32_e32 v84, v84, v90
	v_mul_f32_e32 v85, v85, v90
	v_cvt_pk_bf16_f32 v84, v84, v85
	v_mul_f32_e32 v85, v86, v90
	v_mul_f32_e32 v86, v87, v90
	v_cvt_pk_bf16_f32 v85, v85, v86
	v_lshl_add_u64 v[86:87], v[88:89], 0, v[126:127]
	flat_store_dwordx2 v[86:87], v[84:85]
	ds_read_b32 v84, v137
	s_waitcnt lgkmcnt(0)
	v_mul_f32_e32 v80, v80, v84
	v_mul_f32_e32 v81, v81, v84
	v_cvt_pk_bf16_f32 v80, v80, v81
	v_mul_f32_e32 v81, v82, v84
	v_mul_f32_e32 v82, v83, v84
	v_cvt_pk_bf16_f32 v81, v81, v82
	v_lshl_add_u64 v[82:83], v[88:89], 0, v[122:123]
	flat_store_dwordx2 v[82:83], v[80:81]
	ds_read_b32 v82, v116
	v_lshl_add_u64 v[80:81], v[96:97], 0, v[112:113]
	s_waitcnt lgkmcnt(0)
; DEVINL unsigned cvtpk(float lo, float hi) { unsigned r; asm("v_cvt_pk_bf16_f32 %0, %1, %2" : "=v"(r) : "v"(lo), "v"(hi)); return r; }
; template <bool SWAP, class Epi>
; DEVINL void gemm_tile(const Params& p, const bf16_t* __restrict__ A0, const bf16_t* __restrict__ A1, int ksplit, int lda,
;                       const bf16_t* __restrict__ Bt, int ldb, int nt, char* shmc, Epi epi) {
;     ...
;   for (int ai = 0; ai < 2; ++ai)
; #pragma unroll
;     for (int bj = 0; bj < 2; ++bj)
; #pragma unroll
;       for (int m = 0; m < 4; ++m)
; #pragma unroll
;         for (int n = 0; n < 2; ++n) {
;           if (SWAP) epi(ai * HALF + wr * 64 + m * 16 + fr, bj * HALF + wc * 32 + n * 16 + fq * 4, acc[ai][bj][m][n]);
;           else      epi(ai * HALF + wr * 64 + m * 16 + fq * 4, bj * HALF + wc * 32 + n * 16 + fr, acc[ai][bj][m][n]);
;         }
; DEVINL void phase_gemm2(const Params& p, char* lds) {
;     ...
;       gemm_tile<true>(p, A, A, 1 << 30, 512, WukvT + (size_t)pn * 256 * KVR, KVR, KVR / BK, lds, [=](int row, int col, f32x4 v) {
;         const float s = rs[row];
;         u32x2 w = {cvtpk(v[0] * s, v[1] * s), cvtpk(v[2] * s, v[3] * s)};
;         const int t = grow0 + row, tile = t >> 6, k = t & 63, h = pn * 2 + (col >> 7), d = col & 127;
;         *reinterpret_cast<u32x2*>(KN + (size_t)h * LP * 128 + ((size_t)(tile * 16 + (d >> 3)) * 64 + k) * 8 + (d & 7)) = w;
;       });
	v_mul_f32_e32 v76, v76, v82
	v_mul_f32_e32 v77, v77, v82
	v_cvt_pk_bf16_f32 v76, v76, v77
	v_mul_f32_e32 v77, v78, v82
	v_mul_f32_e32 v78, v79, v82
	v_cvt_pk_bf16_f32 v77, v77, v78
	v_lshl_add_u64 v[78:79], v[80:81], 0, v[126:127]
	flat_store_dwordx2 v[78:79], v[76:77]
	ds_read_b32 v76, v116
	s_waitcnt lgkmcnt(0)
	v_mul_f32_e32 v72, v72, v76
	v_mul_f32_e32 v73, v73, v76
	v_cvt_pk_bf16_f32 v72, v72, v73
	v_mul_f32_e32 v73, v74, v76
	v_mul_f32_e32 v74, v75, v76
	v_cvt_pk_bf16_f32 v73, v73, v74
	v_lshl_add_u64 v[74:75], v[80:81], 0, v[122:123]
	flat_store_dwordx2 v[74:75], v[72:73]
	ds_read_b32 v74, v108
	v_lshl_add_u64 v[72:73], v[96:97], 0, v[104:105]
	s_waitcnt lgkmcnt(0)
	v_mul_f32_e32 v68, v68, v74
	v_mul_f32_e32 v69, v69, v74
	v_cvt_pk_bf16_f32 v68, v68, v69
	v_mul_f32_e32 v69, v70, v74
	v_mul_f32_e32 v70, v71, v74
	v_cvt_pk_bf16_f32 v69, v69, v70
	v_lshl_add_u64 v[70:71], v[72:73], 0, v[126:127]
	flat_store_dwordx2 v[70:71], v[68:69]
	ds_read_b32 v68, v108
	s_waitcnt lgkmcnt(0)
	v_mul_f32_e32 v64, v64, v68
	v_mul_f32_e32 v65, v65, v68
	v_cvt_pk_bf16_f32 v64, v64, v65
	v_mul_f32_e32 v65, v66, v68
	v_mul_f32_e32 v66, v67, v68
	v_cvt_pk_bf16_f32 v65, v65, v66
	v_lshl_add_u64 v[66:67], v[72:73], 0, v[122:123]
	flat_store_dwordx2 v[66:67], v[64:65]
	ds_read_b32 v64, v139 offset:512
	v_add_u32_e32 v65, s16, v138
	v_add_u32_e32 v65, 0x80, v65
	v_ashrrev_i32_e32 v65, 2, v65
	v_and_b32_e32 v66, -16, v65
	s_waitcnt lgkmcnt(0)
	v_mul_f32_e32 v60, v60, v64
	v_mul_f32_e32 v61, v61, v64
	v_cvt_pk_bf16_f32 v60, v60, v61
	v_mul_f32_e32 v61, v62, v64
	v_mul_f32_e32 v62, v63, v64
	v_cvt_pk_bf16_f32 v61, v61, v62
	v_or_b32_e32 v62, v66, v140
	v_ashrrev_i32_e32 v63, 31, v62
	v_lshlrev_b64 v[62:63], 10, v[62:63]
	v_lshl_add_u64 v[64:65], v[132:133], 0, v[62:63]
	flat_store_dwordx2 v[64:65], v[60:61]
	ds_read_b32 v60, v139 offset:512
	s_waitcnt lgkmcnt(0)
	v_mul_f32_e32 v56, v56, v60
	v_mul_f32_e32 v57, v57, v60
	v_cvt_pk_bf16_f32 v56, v56, v57
	v_mul_f32_e32 v57, v58, v60
	v_mul_f32_e32 v58, v59, v60
	v_cvt_pk_bf16_f32 v57, v57, v58
	v_or_b32_e32 v58, v66, v136
	v_ashrrev_i32_e32 v59, 31, v58
	v_lshlrev_b64 v[58:59], 10, v[58:59]
	v_lshl_add_u64 v[60:61], v[132:133], 0, v[58:59]
	flat_store_dwordx2 v[60:61], v[56:57]
	ds_read_b32 v60, v139 offset:576
	v_add_u32_e32 v56, 0x90, v138
	v_add_u32_e32 v57, s16, v56
	v_ashrrev_i32_e32 v57, 2, v57
	v_and_b32_e32 v64, -16, v57
	s_waitcnt lgkmcnt(0)
	v_mul_f32_e32 v52, v52, v60
	v_mul_f32_e32 v53, v53, v60
	v_cvt_pk_bf16_f32 v52, v52, v53
	v_mul_f32_e32 v53, v54, v60
	v_mul_f32_e32 v54, v55, v60
	v_lshlrev_b32_e32 v56, 4, v56
	v_cvt_pk_bf16_f32 v53, v53, v54
	v_or_b32_e32 v54, v64, v140
	v_and_b32_e32 v128, 0x1f0, v56
	v_ashrrev_i32_e32 v55, 31, v54
	v_lshl_add_u64 v[56:57], v[130:131], 0, v[128:129]
	v_lshlrev_b64 v[54:55], 10, v[54:55]
	v_lshl_add_u64 v[60:61], v[56:57], 0, v[54:55]
	flat_store_dwordx2 v[60:61], v[52:53]
	ds_read_b32 v52, v139 offset:576
	s_waitcnt lgkmcnt(0)
	v_mul_f32_e32 v48, v48, v52
	v_mul_f32_e32 v49, v49, v52
	v_cvt_pk_bf16_f32 v48, v48, v49
	v_mul_f32_e32 v49, v50, v52
	v_mul_f32_e32 v50, v51, v52
	v_cvt_pk_bf16_f32 v49, v49, v50
	v_or_b32_e32 v50, v64, v136
	v_ashrrev_i32_e32 v51, 31, v50
	v_lshlrev_b64 v[50:51], 10, v[50:51]
	v_lshl_add_u64 v[52:53], v[56:57], 0, v[50:51]
	flat_store_dwordx2 v[52:53], v[48:49]
	ds_read_b32 v56, v139 offset:640
	v_add_u32_e32 v48, 0xa0, v138
	v_add_u32_e32 v49, s16, v48
	v_ashrrev_i32_e32 v49, 2, v49
	v_and_b32_e32 v60, -16, v49
	s_waitcnt lgkmcnt(0)
	v_mul_f32_e32 v44, v44, v56
	v_mul_f32_e32 v45, v45, v56
	v_cvt_pk_bf16_f32 v44, v44, v45
	v_mul_f32_e32 v45, v46, v56
	v_mul_f32_e32 v46, v47, v56
	v_lshlrev_b32_e32 v48, 4, v48
	v_cvt_pk_bf16_f32 v45, v45, v46
	v_or_b32_e32 v46, v60, v140
	v_and_b32_e32 v48, 0x2f0, v48
	v_mov_b32_e32 v49, v129
	v_ashrrev_i32_e32 v47, 31, v46
	v_lshl_add_u64 v[52:53], v[130:131], 0, v[48:49]
	v_lshlrev_b64 v[46:47], 10, v[46:47]
	v_lshl_add_u64 v[56:57], v[52:53], 0, v[46:47]
	flat_store_dwordx2 v[56:57], v[44:45]
	ds_read_b32 v44, v139 offset:640
	s_waitcnt lgkmcnt(0)
	v_mul_f32_e32 v40, v40, v44
	v_mul_f32_e32 v41, v41, v44
	v_cvt_pk_bf16_f32 v40, v40, v41
	v_mul_f32_e32 v41, v42, v44
	v_mul_f32_e32 v42, v43, v44
	v_cvt_pk_bf16_f32 v41, v41, v42
	v_or_b32_e32 v42, v60, v136
	v_ashrrev_i32_e32 v43, 31, v42
	v_lshlrev_b64 v[42:43], 10, v[42:43]
	v_lshl_add_u64 v[44:45], v[52:53], 0, v[42:43]
	flat_store_dwordx2 v[44:45], v[40:41]
	ds_read_b32 v52, v139 offset:704
	v_add_u32_e32 v40, 0xb0, v138
	v_add_u32_e32 v41, s16, v40
	v_ashrrev_i32_e32 v41, 2, v41
	v_and_b32_e32 v56, -16, v41
	s_waitcnt lgkmcnt(0)
	v_mul_f32_e32 v36, v36, v52
	v_mul_f32_e32 v37, v37, v52
	v_cvt_pk_bf16_f32 v36, v36, v37
	v_mul_f32_e32 v37, v38, v52
	v_mul_f32_e32 v38, v39, v52
	v_lshlrev_b32_e32 v40, 4, v40
	v_cvt_pk_bf16_f32 v37, v37, v38
	v_or_b32_e32 v38, v56, v140
	v_and_b32_e32 v40, 0x3f0, v40
	v_mov_b32_e32 v41, v129
	v_ashrrev_i32_e32 v39, 31, v38
	v_lshl_add_u64 v[44:45], v[130:131], 0, v[40:41]
	v_lshlrev_b64 v[38:39], 10, v[38:39]
	v_lshl_add_u64 v[52:53], v[44:45], 0, v[38:39]
	flat_store_dwordx2 v[52:53], v[36:37]
	ds_read_b32 v36, v139 offset:704
	s_waitcnt lgkmcnt(0)
	v_mul_f32_e32 v32, v32, v36
	v_mul_f32_e32 v33, v33, v36
	v_cvt_pk_bf16_f32 v32, v32, v33
	v_mul_f32_e32 v33, v34, v36
	v_mul_f32_e32 v34, v35, v36
	v_cvt_pk_bf16_f32 v33, v33, v34
	v_or_b32_e32 v34, v56, v136
	v_ashrrev_i32_e32 v35, 31, v34
	v_lshlrev_b64 v[34:35], 10, v[34:35]
	v_lshl_add_u64 v[36:37], v[44:45], 0, v[34:35]
	flat_store_dwordx2 v[36:37], v[32:33]
	ds_read_b32 v32, v139 offset:512
	s_waitcnt lgkmcnt(0)
; DEVINL int tidx(const Params& p) { int l; asm volatile("v_mbcnt_lo_u32_b32 %0, -1, 0\n\tv_mbcnt_hi_u32_b32 %0, -1, %0" : "=v"(l)); return p.tid0 + l; }
; DEVINL unsigned char* wsp(const Params& p) { unsigned char* w = p.ws; asm volatile("" : "+s"(w)); return w; }
; DEVINL unsigned cvtpk(float lo, float hi) { unsigned r; asm("v_cvt_pk_bf16_f32 %0, %1, %2" : "=v"(r) : "v"(lo), "v"(hi)); return r; }
; DEVINL void knorm_image(const Params& p, int ht, int lanen) {
;   const bf16_t* KN = (const bf16_t*)(wsp(p) + OFF_KN); char* K8 = (char*)(wsp(p) + OFF_K8);
;   const bf16_t* src = KN + (size_t)ht * 8192 + lanen * 8;
;   u32x4 raw[16];
; #pragma unroll
;   for (int kc = 0; kc < 16; ++kc) raw[kc] = *reinterpret_cast<const u32x4*>(src + kc * 512);
; DEVINL void phase_gemm2(const Params& p, char* lds) {
;     ...
;       gemm_tile<true>(p, A, A, 1 << 30, 512, WukvT + (size_t)pn * 256 * KVR, KVR, KVR / BK, lds, [=](int row, int col, f32x4 v) {
;         const float s = rs[row];
;         u32x2 w = {cvtpk(v[0] * s, v[1] * s), cvtpk(v[2] * s, v[3] * s)};
;         const int t = grow0 + row, tile = t >> 6, k = t & 63, h = pn * 2 + (col >> 7), d = col & 127;
;         *reinterpret_cast<u32x2*>(KN + (size_t)h * LP * 128 + ((size_t)(tile * 16 + (d >> 3)) * 64 + k) * 8 + (d & 7)) = w;
;       });
;       asm volatile("s_waitcnt vmcnt(0)" ::: "memory"); __syncthreads();
;       { const int tid = tidx(p), w = tid >> 6; knorm_image(p, (pn * 2 + (w >> 2)) * (LP / 64) + pm * 4 + (w & 3), tid & 63); }
	v_mul_f32_e32 v28, v28, v32
	v_mul_f32_e32 v29, v29, v32
	v_cvt_pk_bf16_f32 v28, v28, v29
	v_mul_f32_e32 v29, v30, v32
	v_mul_f32_e32 v30, v31, v32
	v_cvt_pk_bf16_f32 v29, v29, v30
	v_lshl_add_u64 v[30:31], v[98:99], 0, v[62:63]
	flat_store_dwordx2 v[30:31], v[28:29]
	ds_read_b32 v28, v139 offset:512
	v_mov_b32_e32 v63, v129
	s_waitcnt lgkmcnt(0)
	v_mul_f32_e32 v24, v24, v28
	v_mul_f32_e32 v25, v25, v28
	v_cvt_pk_bf16_f32 v24, v24, v25
	v_mul_f32_e32 v25, v26, v28
	v_mul_f32_e32 v26, v27, v28
	v_cvt_pk_bf16_f32 v25, v25, v26
	v_lshl_add_u64 v[26:27], v[98:99], 0, v[58:59]
	flat_store_dwordx2 v[26:27], v[24:25]
	ds_read_b32 v26, v139 offset:576
	v_lshl_add_u64 v[24:25], v[96:97], 0, v[128:129]
	s_waitcnt lgkmcnt(0)
	v_mul_f32_e32 v20, v20, v26
	v_mul_f32_e32 v21, v21, v26
	v_cvt_pk_bf16_f32 v20, v20, v21
	v_mul_f32_e32 v21, v22, v26
	v_mul_f32_e32 v22, v23, v26
	v_cvt_pk_bf16_f32 v21, v21, v22
	v_lshl_add_u64 v[22:23], v[24:25], 0, v[54:55]
	flat_store_dwordx2 v[22:23], v[20:21]
	ds_read_b32 v20, v139 offset:576
	s_waitcnt lgkmcnt(0)
	v_mul_f32_e32 v16, v16, v20
	v_mul_f32_e32 v17, v17, v20
	v_cvt_pk_bf16_f32 v16, v16, v17
	v_mul_f32_e32 v17, v18, v20
	v_mul_f32_e32 v18, v19, v20
	v_cvt_pk_bf16_f32 v17, v17, v18
	v_lshl_add_u64 v[18:19], v[24:25], 0, v[50:51]
	flat_store_dwordx2 v[18:19], v[16:17]
	ds_read_b32 v18, v139 offset:640
	v_lshl_add_u64 v[16:17], v[96:97], 0, v[48:49]
	s_waitcnt lgkmcnt(0)
	v_mul_f32_e32 v12, v12, v18
	v_mul_f32_e32 v13, v13, v18
	v_cvt_pk_bf16_f32 v12, v12, v13
	v_mul_f32_e32 v13, v14, v18
	v_mul_f32_e32 v14, v15, v18
	v_cvt_pk_bf16_f32 v13, v13, v14
	v_lshl_add_u64 v[14:15], v[16:17], 0, v[46:47]
	flat_store_dwordx2 v[14:15], v[12:13]
	ds_read_b32 v12, v139 offset:640
	s_waitcnt lgkmcnt(0)
	v_mul_f32_e32 v8, v8, v12
	v_mul_f32_e32 v9, v9, v12
	v_cvt_pk_bf16_f32 v8, v8, v9
	v_mul_f32_e32 v9, v10, v12
	v_mul_f32_e32 v10, v11, v12
	v_cvt_pk_bf16_f32 v9, v9, v10
	v_lshl_add_u64 v[10:11], v[16:17], 0, v[42:43]
	flat_store_dwordx2 v[10:11], v[8:9]
	ds_read_b32 v10, v139 offset:704
	v_lshl_add_u64 v[8:9], v[96:97], 0, v[40:41]
	s_waitcnt lgkmcnt(0)
	v_mul_f32_e32 v4, v4, v10
	v_mul_f32_e32 v5, v5, v10
	v_cvt_pk_bf16_f32 v4, v4, v5
	v_mul_f32_e32 v5, v6, v10
	v_mul_f32_e32 v6, v7, v10
	v_cvt_pk_bf16_f32 v5, v5, v6
	v_lshl_add_u64 v[6:7], v[8:9], 0, v[38:39]
	flat_store_dwordx2 v[6:7], v[4:5]
	ds_read_b32 v4, v139 offset:704
	s_waitcnt lgkmcnt(0)
	v_mul_f32_e32 v0, v0, v4
	v_mul_f32_e32 v1, v1, v4
	v_cvt_pk_bf16_f32 v0, v0, v1
	v_mul_f32_e32 v1, v2, v4
	v_mul_f32_e32 v2, v3, v4
	v_cvt_pk_bf16_f32 v1, v1, v2
	v_lshl_add_u64 v[2:3], v[8:9], 0, v[34:35]
	flat_store_dwordx2 v[2:3], v[0:1]
	s_waitcnt vmcnt(0)
	s_waitcnt vmcnt(0) lgkmcnt(0)
	s_barrier
	v_mbcnt_lo_u32_b32 v0, -1, 0
	v_mbcnt_hi_u32_b32 v0, -1, v0
	s_nop 0
	v_add_u32_e32 v0, s3, v0
	v_ashrrev_i32_e32 v2, 8, v0
	v_add_u32_e32 v2, s4, v2
	v_mul_lo_u32 v2, v2, s59
	v_lshrrev_b32_e32 v1, 6, v0
	v_lshl_add_u32 v2, s78, 2, v2
	v_and_or_b32 v12, v1, 3, v2
	v_ashrrev_i32_e32 v13, 31, v12
	v_and_b32_e32 v22, 63, v0
	v_lshlrev_b64 v[0:1], 14, v[12:13]
	v_lshl_add_u64 v[0:1], s[28:29], 0, v[0:1]
	v_lshlrev_b32_e32 v62, 4, v22
	v_lshl_add_u64 v[14:15], v[0:1], 0, v[62:63]
	v_add_co_u32_e32 v16, vcc, s69, v14
	s_mov_b64 s[4:5], s[72:73]
	s_nop 0
	v_addc_co_u32_e32 v17, vcc, 0, v15, vcc
	v_add_co_u32_e32 v0, vcc, s74, v14
	flat_load_dwordx4 v[40:43], v[16:17] offset:3072
	s_nop 0
	v_addc_co_u32_e32 v1, vcc, 0, v15, vcc
	flat_load_dwordx4 v[0:3], v[0:1]
	v_lshl_add_u64 v[18:19], v[14:15], 0, s[8:9]
	flat_load_dwordx4 v[4:7], v[18:19] offset:2048
	flat_load_dwordx4 v[8:11], v[18:19] offset:3072
	v_add_co_u32_e32 v20, vcc, s62, v14
	v_lshrrev_b32_e32 v128, 5, v22
	v_mul_i32_i24_e32 v128, 0xfffffe08, v128
	v_lshl_add_u32 v128, v22, 4, v128
	s_nop 0
	v_addc_co_u32_e32 v21, vcc, 0, v15, vcc
	flat_load_dwordx4 v[64:67], v[20:21] offset:1024
	flat_load_dwordx4 v[68:71], v[18:19] offset:1024
	v_add_co_u32_e32 v18, vcc, s63, v14
	s_waitcnt vmcnt(0) lgkmcnt(0)
	v_lshlrev_b32_e32 v59, 16, v43
	v_addc_co_u32_e32 v19, vcc, 0, v15, vcc
	flat_load_dwordx4 v[72:75], v[18:19] offset:1024
	flat_load_dwordx4 v[76:79], v[18:19] offset:2048
	v_add_co_u32_e32 v14, vcc, s68, v14
	v_and_b32_e32 v57, 0xffff0000, v1
	s_nop 0
	v_addc_co_u32_e32 v15, vcc, 0, v15, vcc
	flat_load_dwordx4 v[80:83], v[18:19] offset:3072
	flat_load_dwordx4 v[122:125], v[14:15]
	flat_load_dwordx4 v[48:51], v[14:15] offset:1024
	flat_load_dwordx4 v[44:47], v[14:15] offset:2048
	flat_load_dwordx4 v[136:139], v[14:15] offset:3072
	flat_load_dwordx4 v[148:151], v[16:17]
	flat_load_dwordx4 v[36:39], v[16:17] offset:1024
	flat_load_dwordx4 v[32:35], v[16:17] offset:2048
	v_and_b32_e32 v56, 0xffff0000, v0
	v_lshlrev_b32_e32 v61, 16, v1
	v_lshlrev_b32_e32 v60, 16, v0
	v_pk_mul_f32 v[0:1], v[56:57], v[56:57]
	v_and_b32_e32 v53, 0xffff0000, v3
	v_and_b32_e32 v52, 0xffff0000, v2
	v_lshlrev_b32_e32 v58, 16, v42
	v_and_b32_e32 v55, 0xffff0000, v43
	v_and_b32_e32 v54, 0xffff0000, v42
	v_pk_fma_f32 v[120:121], v[60:61], v[60:61], v[0:1]
	v_lshlrev_b32_e32 v43, 16, v3
	v_lshlrev_b32_e32 v42, 16, v2
	v_pk_mul_f32 v[0:1], v[52:53], v[52:53]
	v_pk_mul_f32 v[14:15], v[54:55], v[54:55]
	v_pk_fma_f32 v[132:133], v[42:43], v[42:43], v[0:1]
	v_mov_b64_e32 v[0:1], s[4:5]
	v_pk_fma_f32 v[114:115], v[58:59], v[58:59], v[14:15]
	v_mad_i64_i32 v[126:127], s[4:5], v12, s75, v[0:1]
	v_lshlrev_b32_e32 v86, 16, v4
	v_and_b32_e32 v87, 0xffff0000, v4
	global_load_dwordx4 v[16:19], v129, s[56:57] offset:64
	global_load_dwordx4 v[20:23], v129, s[56:57] offset:80
	global_load_dwordx4 v[24:27], v129, s[56:57] offset:96
	global_load_dwordx4 v[28:31], v129, s[56:57] offset:112
; DEVINL float bflo(unsigned u) { return __uint_as_float(u << 16); }
; DEVINL float bfhi(unsigned u) { return __uint_as_float(u & 0xffff0000u); }
; DEVINL void knorm_image(const Params& p, int ht, int lanen) {
;     ...
;   for (int kc = 0; kc < 16; ++kc) raw[kc] = *reinterpret_cast<const u32x4*>(src + kc * 512);
;   float ss = 0.f;
; #pragma unroll
;   for (int kc = 0; kc < 16; ++kc)
; #pragma unroll
;     for (int j = 0; j < 4; ++j) { const float a = bflo(raw[kc][j]), b = bfhi(raw[kc][j]); ss += a * a + b * b; }
;   const float r = rsqrtf(ss * (1.f / 128.f) + EPS);
	v_lshlrev_b32_e32 v92, 16, v5
	v_and_b32_e32 v93, 0xffff0000, v5
	v_lshlrev_b32_e32 v98, 16, v6
	v_and_b32_e32 v99, 0xffff0000, v6
	v_lshlrev_b32_e32 v104, 16, v7
	v_and_b32_e32 v105, 0xffff0000, v7
	v_lshlrev_b32_e32 v108, 16, v8
	v_and_b32_e32 v109, 0xffff0000, v8
	v_lshlrev_b32_e32 v110, 16, v9
	v_and_b32_e32 v111, 0xffff0000, v9
	v_lshlrev_b32_e32 v112, 16, v10
	v_and_b32_e32 v113, 0xffff0000, v10
	v_lshlrev_b32_e32 v118, 16, v11
	v_and_b32_e32 v119, 0xffff0000, v11
	global_load_dwordx4 v[0:3], v129, s[56:57]
	global_load_dwordx4 v[4:7], v129, s[56:57] offset:16
	global_load_dwordx4 v[8:11], v129, s[56:57] offset:32
	global_load_dwordx4 v[12:15], v129, s[56:57] offset:48
	v_lshlrev_b32_e32 v158, 16, v64
	v_and_b32_e32 v159, 0xffff0000, v64
	v_lshlrev_b32_e32 v160, 16, v65
	v_and_b32_e32 v161, 0xffff0000, v65
	v_pk_mul_f32 v[206:207], v[158:159], v[158:159]
	v_pk_mul_f32 v[212:213], v[160:161], v[160:161]
	v_lshlrev_b32_e32 v162, 16, v66
	v_and_b32_e32 v163, 0xffff0000, v66
	v_pk_mul_f32 v[210:211], v[162:163], v[162:163]
	v_lshlrev_b32_e32 v164, 16, v67
	v_and_b32_e32 v165, 0xffff0000, v67
	v_add_f32_e32 v212, v212, v213
	v_add_f32_e32 v213, v206, v207
	v_pk_mul_f32 v[222:223], v[164:165], v[164:165]
	v_lshlrev_b32_e32 v166, 16, v68
	v_and_b32_e32 v167, 0xffff0000, v68
	v_add_f32_e32 v212, v213, v212
	v_add_f32_e32 v213, v210, v211
	v_pk_mul_f32 v[214:215], v[166:167], v[166:167]
	v_lshlrev_b32_e32 v168, 16, v69
	v_and_b32_e32 v169, 0xffff0000, v69
	v_add_f32_e32 v248, v222, v223
	v_add_f32_e32 v212, v213, v212
	v_pk_mul_f32 v[216:217], v[168:169], v[168:169]
	v_lshlrev_b32_e32 v170, 16, v70
	v_and_b32_e32 v171, 0xffff0000, v70
	v_add_f32_e32 v248, v248, v212
	v_add_f32_e32 v214, v214, v215
	v_pk_mul_f32 v[218:219], v[170:171], v[170:171]
	v_lshlrev_b32_e32 v172, 16, v71
	v_and_b32_e32 v173, 0xffff0000, v71
	v_add_f32_e32 v248, v214, v248
	v_add_f32_e32 v216, v216, v217
	v_pk_mul_f32 v[220:221], v[172:173], v[172:173]
	v_add_f32_e32 v248, v216, v248
	v_add_f32_e32 v218, v218, v219
	v_pk_mul_f32 v[174:175], v[86:87], v[86:87]
	v_add_f32_e32 v248, v218, v248
	v_add_f32_e32 v220, v220, v221
	v_pk_mul_f32 v[176:177], v[92:93], v[92:93]
	v_add_f32_e32 v248, v220, v248
	v_add_f32_e32 v174, v174, v175
	v_pk_mul_f32 v[178:179], v[98:99], v[98:99]
	v_add_f32_e32 v248, v174, v248
	v_add_f32_e32 v176, v176, v177
	v_pk_mul_f32 v[180:181], v[104:105], v[104:105]
	v_add_f32_e32 v248, v176, v248
	v_add_f32_e32 v178, v178, v179
	v_pk_mul_f32 v[182:183], v[108:109], v[108:109]
	v_add_f32_e32 v248, v178, v248
	v_add_f32_e32 v180, v180, v181
	v_pk_mul_f32 v[184:185], v[110:111], v[110:111]
	v_add_f32_e32 v248, v180, v248
	v_add_f32_e32 v182, v182, v183
	v_pk_mul_f32 v[186:187], v[112:113], v[112:113]
	v_add_f32_e32 v248, v182, v248
	v_add_f32_e32 v184, v184, v185
	v_pk_mul_f32 v[188:189], v[118:119], v[118:119]
	s_waitcnt vmcnt(0) lgkmcnt(0)
	v_lshlrev_b32_e32 v140, 16, v72
	v_and_b32_e32 v141, 0xffff0000, v72
	v_add_f32_e32 v248, v184, v248
	v_add_f32_e32 v186, v186, v187
	v_pk_mul_f32 v[230:231], v[140:141], v[140:141]
	v_lshlrev_b32_e32 v130, 16, v73
	v_and_b32_e32 v131, 0xffff0000, v73
	v_add_f32_e32 v248, v186, v248
	v_add_f32_e32 v188, v188, v189
	v_pk_mul_f32 v[232:233], v[130:131], v[130:131]
	v_lshlrev_b32_e32 v134, 16, v74
	v_and_b32_e32 v135, 0xffff0000, v74
	v_add_f32_e32 v248, v188, v248
	v_add_f32_e32 v230, v230, v231
	v_pk_mul_f32 v[234:235], v[134:135], v[134:135]
	v_lshlrev_b32_e32 v142, 16, v75
	v_and_b32_e32 v143, 0xffff0000, v75
	v_add_f32_e32 v248, v230, v248
	v_add_f32_e32 v232, v232, v233
	v_pk_mul_f32 v[236:237], v[142:143], v[142:143]
	v_lshlrev_b32_e32 v144, 16, v76
	v_and_b32_e32 v145, 0xffff0000, v76
	v_add_f32_e32 v248, v232, v248
	v_add_f32_e32 v234, v234, v235
	v_pk_mul_f32 v[238:239], v[144:145], v[144:145]
	v_lshlrev_b32_e32 v146, 16, v77
	v_and_b32_e32 v147, 0xffff0000, v77
	v_add_f32_e32 v248, v234, v248
	v_add_f32_e32 v236, v236, v237
	v_pk_mul_f32 v[240:241], v[146:147], v[146:147]
	v_lshlrev_b32_e32 v152, 16, v78
	v_and_b32_e32 v153, 0xffff0000, v78
	v_add_f32_e32 v248, v236, v248
	v_add_f32_e32 v238, v238, v239
	v_pk_mul_f32 v[242:243], v[152:153], v[152:153]
	v_lshlrev_b32_e32 v154, 16, v79
	v_and_b32_e32 v155, 0xffff0000, v79
	v_add_f32_e32 v248, v238, v248
	v_add_f32_e32 v240, v240, v241
	v_lshlrev_b32_e32 v94, 16, v80
	v_and_b32_e32 v95, 0xffff0000, v80
	v_pk_mul_f32 v[244:245], v[154:155], v[154:155]
	v_add_f32_e32 v240, v240, v248
	v_add_f32_e32 v241, v242, v243
	v_pk_mul_f32 v[190:191], v[94:95], v[94:95]
	v_lshlrev_b32_e32 v88, 16, v81
	v_and_b32_e32 v89, 0xffff0000, v81
	v_add_f32_e32 v240, v241, v240
	v_add_f32_e32 v241, v244, v245
	v_pk_mul_f32 v[192:193], v[88:89], v[88:89]
	v_lshlrev_b32_e32 v90, 16, v82
	v_and_b32_e32 v91, 0xffff0000, v82
	v_add_f32_e32 v240, v241, v240
	v_add_f32_e32 v190, v190, v191
	v_pk_mul_f32 v[194:195], v[90:91], v[90:91]
	v_lshlrev_b32_e32 v96, 16, v83
	v_and_b32_e32 v97, 0xffff0000, v83
	v_add_f32_e32 v190, v190, v240
	v_add_f32_e32 v191, v192, v193
	v_pk_mul_f32 v[196:197], v[96:97], v[96:97]
	v_lshlrev_b32_e32 v100, 16, v122
	v_and_b32_e32 v101, 0xffff0000, v122
	v_add_f32_e32 v190, v191, v190
	v_add_f32_e32 v191, v194, v195
	v_pk_mul_f32 v[198:199], v[100:101], v[100:101]
	v_lshlrev_b32_e32 v102, 16, v123
	v_and_b32_e32 v103, 0xffff0000, v123
	v_add_f32_e32 v190, v191, v190
	v_add_f32_e32 v191, v196, v197
	v_pk_mul_f32 v[200:201], v[102:103], v[102:103]
	v_lshlrev_b32_e32 v106, 16, v124
	v_and_b32_e32 v107, 0xffff0000, v124
	v_add_f32_e32 v190, v191, v190
	v_add_f32_e32 v191, v198, v199
	v_pk_mul_f32 v[202:203], v[106:107], v[106:107]
	v_lshlrev_b32_e32 v84, 16, v125
; DEVINL float bflo(unsigned u) { return __uint_as_float(u << 16); }
; DEVINL float bfhi(unsigned u) { return __uint_as_float(u & 0xffff0000u); }
; DEVINL void knorm_image(const Params& p, int ht, int lanen) {
;     ...
;   for (int kc = 0; kc < 16; ++kc) raw[kc] = *reinterpret_cast<const u32x4*>(src + kc * 512);
;   float ss = 0.f;
; #pragma unroll
;   for (int kc = 0; kc < 16; ++kc)
; #pragma unroll
;     for (int j = 0; j < 4; ++j) { const float a = bflo(raw[kc][j]), b = bfhi(raw[kc][j]); ss += a * a + b * b; }
;   const float r = rsqrtf(ss * (1.f / 128.f) + EPS);
;   char* dst = K8 + (size_t)ht * 6144;
; #pragma unroll
;   for (int c = 0; c < 4; ++c) {
;     f32x16 a, b;
	v_and_b32_e32 v85, 0xffff0000, v125
	v_add_f32_e32 v190, v191, v190
	v_add_f32_e32 v191, v200, v201
	v_pk_mul_f32 v[204:205], v[84:85], v[84:85]
	v_lshlrev_b32_e32 v116, 16, v48
	v_and_b32_e32 v117, 0xffff0000, v48
	v_add_f32_e32 v190, v191, v190
	v_add_f32_e32 v191, v202, v203
	v_lshlrev_b32_e32 v124, 16, v49
	v_and_b32_e32 v125, 0xffff0000, v49
	v_pk_mul_f32 v[218:219], v[116:117], v[116:117]
	v_add_f32_e32 v190, v191, v190
	v_add_f32_e32 v191, v204, v205
	v_lshlrev_b32_e32 v122, 16, v50
	v_and_b32_e32 v123, 0xffff0000, v50
	v_pk_mul_f32 v[220:221], v[124:125], v[124:125]
	v_add_f32_e32 v190, v191, v190
	v_add_f32_e32 v191, v218, v219
	v_lshlrev_b32_e32 v66, 16, v138
	v_and_b32_e32 v67, 0xffff0000, v138
	v_lshlrev_b32_e32 v72, 16, v139
	v_and_b32_e32 v73, 0xffff0000, v139
	v_lshlrev_b32_e32 v138, 16, v51
	v_and_b32_e32 v139, 0xffff0000, v51
	v_pk_mul_f32 v[174:175], v[122:123], v[122:123]
	v_add_f32_e32 v190, v191, v190
	v_add_f32_e32 v191, v220, v221
	v_lshlrev_b32_e32 v64, 16, v136
	v_and_b32_e32 v65, 0xffff0000, v136
	v_lshlrev_b32_e32 v68, 16, v137
	v_and_b32_e32 v69, 0xffff0000, v137
	v_lshlrev_b32_e32 v136, 16, v44
	v_and_b32_e32 v137, 0xffff0000, v44
	v_pk_mul_f32 v[176:177], v[138:139], v[138:139]
	v_add_f32_e32 v190, v191, v190
	v_add_f32_e32 v174, v174, v175
	v_lshlrev_b32_e32 v74, 16, v150
	v_and_b32_e32 v75, 0xffff0000, v150
	v_lshlrev_b32_e32 v82, 16, v151
	v_and_b32_e32 v83, 0xffff0000, v151
	v_lshlrev_b32_e32 v150, 16, v45
	v_and_b32_e32 v151, 0xffff0000, v45
	v_pk_mul_f32 v[178:179], v[136:137], v[136:137]
	v_add_f32_e32 v174, v174, v190
	v_add_f32_e32 v175, v176, v177
	v_lshlrev_b32_e32 v70, 16, v148
	v_and_b32_e32 v71, 0xffff0000, v148
	v_lshlrev_b32_e32 v76, 16, v149
	v_and_b32_e32 v77, 0xffff0000, v149
	v_lshlrev_b32_e32 v148, 16, v46
	v_and_b32_e32 v149, 0xffff0000, v46
	v_pk_mul_f32 v[180:181], v[150:151], v[150:151]
	v_add_f32_e32 v174, v175, v174
	v_add_f32_e32 v175, v178, v179
	v_lshlrev_b32_e32 v156, 16, v47
	v_and_b32_e32 v157, 0xffff0000, v47
	v_and_b32_e32 v49, 0xffff0000, v40
	v_and_b32_e32 v45, 0xffff0000, v41
	v_pk_mul_f32 v[182:183], v[148:149], v[148:149]
	v_add_f32_e32 v174, v175, v174
	v_add_f32_e32 v175, v180, v181
	v_lshlrev_b32_e32 v48, 16, v40
	v_lshlrev_b32_e32 v44, 16, v41
	v_mov_b32_e32 v246, v45
	v_mov_b32_e32 v247, v49
	v_pk_mul_f32 v[184:185], v[156:157], v[156:157]
	v_add_f32_e32 v174, v175, v174
	v_add_f32_e32 v175, v182, v183
	v_pk_mul_f32 v[208:209], v[64:65], v[64:65]
	v_lshlrev_b32_e32 v40, 16, v36
	v_and_b32_e32 v41, 0xffff0000, v36
	v_lshlrev_b32_e32 v46, 16, v37
	v_and_b32_e32 v47, 0xffff0000, v37
	v_lshlrev_b32_e32 v36, 16, v38
	v_and_b32_e32 v37, 0xffff0000, v38
	v_lshlrev_b32_e32 v50, 16, v39
	v_and_b32_e32 v51, 0xffff0000, v39
	v_lshlrev_b32_e32 v38, 16, v32
	v_and_b32_e32 v39, 0xffff0000, v32
	v_lshlrev_b32_e32 v80, 16, v33
	v_and_b32_e32 v81, 0xffff0000, v33
	v_lshlrev_b32_e32 v79, 16, v34
	v_and_b32_e32 v33, 0xffff0000, v34
	v_lshlrev_b32_e32 v78, 16, v35
	v_and_b32_e32 v32, 0xffff0000, v35
	v_mov_b32_e32 v34, v44
	v_mov_b32_e32 v35, v48
	v_pk_mul_f32 v[246:247], v[246:247], v[246:247]
	v_add_f32_e32 v174, v175, v174
	v_add_f32_e32 v175, v184, v185
	v_pk_fma_f32 v[34:35], v[34:35], v[34:35], v[246:247]
	v_pk_mul_f32 v[246:247], v[68:69], v[68:69]
	v_add_f32_e32 v174, v175, v174
	v_add_f32_e32 v175, v208, v209
	v_pk_mul_f32 v[222:223], v[66:67], v[66:67]
	v_add_f32_e32 v174, v175, v174
	v_add_f32_e32 v175, v246, v247
	v_pk_mul_f32 v[206:207], v[72:73], v[72:73]
	v_add_f32_e32 v174, v175, v174
	v_add_f32_e32 v175, v222, v223
	v_pk_mul_f32 v[210:211], v[70:71], v[70:71]
	v_add_f32_e32 v174, v175, v174
	v_add_f32_e32 v175, v206, v207
	v_pk_mul_f32 v[212:213], v[76:77], v[76:77]
	v_add_f32_e32 v174, v175, v174
	v_add_f32_e32 v175, v210, v211
	v_pk_mul_f32 v[214:215], v[74:75], v[74:75]
	v_add_f32_e32 v174, v175, v174
	v_add_f32_e32 v175, v212, v213
	v_pk_mul_f32 v[216:217], v[82:83], v[82:83]
	v_add_f32_e32 v174, v175, v174
	v_add_f32_e32 v175, v214, v215
	v_pk_mul_f32 v[186:187], v[40:41], v[40:41]
	v_add_f32_e32 v174, v175, v174
	v_add_f32_e32 v175, v216, v217
	v_pk_mul_f32 v[188:189], v[46:47], v[46:47]
	v_add_f32_e32 v174, v175, v174
	v_add_f32_e32 v175, v186, v187
	v_pk_mul_f32 v[230:231], v[36:37], v[36:37]
	v_add_f32_e32 v174, v175, v174
	v_add_f32_e32 v175, v188, v189
	v_pk_mul_f32 v[232:233], v[50:51], v[50:51]
	v_add_f32_e32 v174, v175, v174
	v_add_f32_e32 v175, v230, v231
	v_pk_mul_f32 v[234:235], v[38:39], v[38:39]
	v_add_f32_e32 v174, v175, v174
	v_add_f32_e32 v175, v232, v233
	v_pk_mul_f32 v[236:237], v[80:81], v[80:81]
	v_add_f32_e32 v174, v175, v174
	v_add_f32_e32 v175, v234, v235
	v_pk_mul_f32 v[238:239], v[32:33], v[32:33]
	v_add_f32_e32 v174, v175, v174
	v_add_f32_e32 v175, v236, v237
	v_pk_fma_f32 v[238:239], v[78:79], v[78:79], v[238:239]
	v_add_f32_e32 v174, v175, v174
	v_add_f32_e32 v174, v239, v174
	v_add_f32_e32 v174, v238, v174
	v_add_f32_e32 v35, v35, v174
	v_add_f32_e32 v34, v34, v35
	v_add_f32_e32 v34, v114, v34
	v_add_f32_e32 v34, v115, v34
	v_add_f32_e32 v34, v120, v34
	v_add_f32_e32 v34, v121, v34
	v_add_f32_e32 v34, v132, v34
	v_add_f32_e32 v34, v133, v34
	v_fmamk_f32 v34, v34, 0x3c000000, v227
	v_mul_f32_e32 v35, 0x4b800000, v34
	v_cmp_gt_f32_e32 vcc, s46, v34
	v_lshl_add_u64 v[114:115], v[126:127], 0, s[24:25]
	s_nop 0
	v_cndmask_b32_e32 v34, v34, v35, vcc
	v_rsq_f32_e32 v120, v34
	v_lshl_add_u64 v[34:35], v[114:115], 0, v[62:63]
	v_lshl_add_u64 v[114:115], v[114:115], 0, v[128:129]
	v_mul_f32_e32 v62, 0x45800000, v120
	v_cndmask_b32_e32 v62, v120, v62, vcc
	v_pk_mul_f32 v[120:121], v[62:63], v[158:159] op_sel_hi:[0,1]
; DEVINL i32x6 pk6(const f32x16& a, const f32x16& b) { return __builtin_amdgcn_cvt_scalef32_2xpk16_fp6_f32(a, b, 1.0f); }
; DEVINL float bflo(unsigned u) { return __uint_as_float(u << 16); }
; DEVINL float bfhi(unsigned u) { return __uint_as_float(u & 0xffff0000u); }
; DEVINL void knorm_image(const Params& p, int ht, int lanen) {
;     ...
; #pragma unroll
;   for (int c = 0; c < 4; ++c) {
;     f32x16 a, b;
; #pragma unroll
;     for (int q = 0; q < 2; ++q)
; #pragma unroll
;       for (int j = 0; j < 4; ++j) {
;         const int kca = c * 4 + q, kcb = c * 4 + 2 + q, da = kca * 8 + 2 * j, db = kcb * 8 + 2 * j;
;         a[q * 8 + 2 * j] = bflo(raw[kca][j]) * r * p.kn_w[da]; a[q * 8 + 2 * j + 1] = bfhi(raw[kca][j]) * r * p.kn_w[da + 1];
;         b[q * 8 + 2 * j] = bflo(raw[kcb][j]) * r * p.kn_w[db]; b[q * 8 + 2 * j + 1] = bfhi(raw[kcb][j]) * r * p.kn_w[db + 1];
;       }
;     const i32x6 w = pk6(a, b);
;     u32x4 wa = {(unsigned)w[0], (unsigned)w[1], (unsigned)w[2], (unsigned)w[3]}; u32x2 wb = {(unsigned)w[4], (unsigned)w[5]};
;     *reinterpret_cast<u32x4*>(dst + c * 1024 + lanen * 16) = wa;
;     *reinterpret_cast<u32x2*>(dst + 4096 + c * 512 + lanen * 8) = wb;
;   }
	v_pk_mul_f32 v[126:127], v[62:63], v[160:161] op_sel_hi:[0,1]
	v_pk_mul_f32 v[132:133], v[62:63], v[162:163] op_sel_hi:[0,1]
	v_pk_mul_f32 v[158:159], v[62:63], v[164:165] op_sel_hi:[0,1]
	v_pk_mul_f32 v[160:161], v[62:63], v[166:167] op_sel_hi:[0,1]
	v_pk_mul_f32 v[162:163], v[62:63], v[168:169] op_sel_hi:[0,1]
	v_pk_mul_f32 v[164:165], v[62:63], v[170:171] op_sel_hi:[0,1]
	v_pk_mul_f32 v[166:167], v[62:63], v[172:173] op_sel_hi:[0,1]
	v_pk_mul_f32 v[86:87], v[62:63], v[86:87] op_sel_hi:[0,1]
	v_pk_mul_f32 v[92:93], v[62:63], v[92:93] op_sel_hi:[0,1]
	v_pk_mul_f32 v[98:99], v[62:63], v[98:99] op_sel_hi:[0,1]
	v_pk_mul_f32 v[104:105], v[62:63], v[104:105] op_sel_hi:[0,1]
	v_pk_mul_f32 v[108:109], v[62:63], v[108:109] op_sel_hi:[0,1]
	v_pk_mul_f32 v[110:111], v[62:63], v[110:111] op_sel_hi:[0,1]
	v_pk_mul_f32 v[112:113], v[62:63], v[112:113] op_sel_hi:[0,1]
	v_pk_mul_f32 v[118:119], v[62:63], v[118:119] op_sel_hi:[0,1]
	v_pk_mul_f32 v[14:15], v[14:15], v[166:167]
	v_pk_mul_f32 v[12:13], v[12:13], v[164:165]
	v_pk_mul_f32 v[10:11], v[10:11], v[162:163]
	v_pk_mul_f32 v[8:9], v[8:9], v[160:161]
	v_pk_mul_f32 v[6:7], v[6:7], v[158:159]
	v_pk_mul_f32 v[4:5], v[4:5], v[132:133]
	v_pk_mul_f32 v[2:3], v[2:3], v[126:127]
	v_pk_mul_f32 v[0:1], v[0:1], v[120:121]
	v_pk_mul_f32 v[30:31], v[30:31], v[118:119]
	v_pk_mul_f32 v[28:29], v[28:29], v[112:113]
	v_pk_mul_f32 v[26:27], v[26:27], v[110:111]
	v_pk_mul_f32 v[24:25], v[24:25], v[108:109]
	v_pk_mul_f32 v[22:23], v[22:23], v[104:105]
	v_pk_mul_f32 v[20:21], v[20:21], v[98:99]
	v_pk_mul_f32 v[18:19], v[18:19], v[92:93]
	v_pk_mul_f32 v[16:17], v[16:17], v[86:87]
	v_lshl_add_u64 v[86:87], v[114:115], 0, s[26:27]
	v_cvt_scalef32_2xpk16_fp6_f32 v[0:5], v[0:15], v[16:31], 1.0
	s_mov_b64 s[100:101], exec
	s_mov_b32 s98, -1
	s_mov_b32 s99, 0
	s_and_b64 exec, s[100:101], s[98:99]
	flat_store_dwordx4 v[34:35], v[0:3]
	flat_store_dwordx2 v[86:87], v[4:5]
	s_andn2_b64 exec, s[100:101], s[98:99]
	flat_store_dwordx4 v[34:35], v[2:5]
	flat_store_dwordx2 v[86:87], v[0:1]
	s_mov_b64 exec, s[100:101]
	v_pk_mul_f32 v[92:93], v[62:63], v[140:141] op_sel_hi:[0,1]
	v_pk_mul_f32 v[94:95], v[62:63], v[94:95] op_sel_hi:[0,1]
	v_pk_mul_f32 v[98:99], v[62:63], v[130:131] op_sel_hi:[0,1]
	s_nop 0
	global_load_dwordx4 v[0:3], v129, s[56:57] offset:128
	s_nop 0
	global_load_dwordx4 v[4:7], v129, s[56:57] offset:144
	global_load_dwordx4 v[8:11], v129, s[56:57] offset:160
	global_load_dwordx4 v[12:15], v129, s[56:57] offset:176
	global_load_dwordx4 v[16:19], v129, s[56:57] offset:192
	global_load_dwordx4 v[20:23], v129, s[56:57] offset:208
	global_load_dwordx4 v[24:27], v129, s[56:57] offset:224
	global_load_dwordx4 v[28:31], v129, s[56:57] offset:240
	v_pk_mul_f32 v[88:89], v[62:63], v[88:89] op_sel_hi:[0,1]
	v_pk_mul_f32 v[104:105], v[62:63], v[134:135] op_sel_hi:[0,1]
	v_pk_mul_f32 v[90:91], v[62:63], v[90:91] op_sel_hi:[0,1]
	v_pk_mul_f32 v[108:109], v[62:63], v[142:143] op_sel_hi:[0,1]
	v_pk_mul_f32 v[96:97], v[62:63], v[96:97] op_sel_hi:[0,1]
	v_pk_mul_f32 v[110:111], v[62:63], v[144:145] op_sel_hi:[0,1]
	v_pk_mul_f32 v[100:101], v[62:63], v[100:101] op_sel_hi:[0,1]
	v_pk_mul_f32 v[112:113], v[62:63], v[146:147] op_sel_hi:[0,1]
	v_pk_mul_f32 v[102:103], v[62:63], v[102:103] op_sel_hi:[0,1]
	v_pk_mul_f32 v[114:115], v[62:63], v[152:153] op_sel_hi:[0,1]
	v_pk_mul_f32 v[106:107], v[62:63], v[106:107] op_sel_hi:[0,1]
	v_pk_mul_f32 v[118:119], v[62:63], v[154:155] op_sel_hi:[0,1]
	v_pk_mul_f32 v[84:85], v[62:63], v[84:85] op_sel_hi:[0,1]
	v_pk_mul_f32 v[40:41], v[62:63], v[40:41] op_sel_hi:[0,1]
	v_pk_mul_f32 v[36:37], v[62:63], v[36:37] op_sel_hi:[0,1]
	s_waitcnt vmcnt(0)
	v_pk_mul_f32 v[0:1], v[0:1], v[92:93]
	v_pk_mul_f32 v[2:3], v[2:3], v[98:99]
	v_pk_mul_f32 v[4:5], v[4:5], v[104:105]
	v_pk_mul_f32 v[6:7], v[6:7], v[108:109]
	v_pk_mul_f32 v[8:9], v[8:9], v[110:111]
	v_pk_mul_f32 v[10:11], v[10:11], v[112:113]
	v_pk_mul_f32 v[12:13], v[12:13], v[114:115]
	v_pk_mul_f32 v[14:15], v[118:119], v[14:15]
	v_pk_mul_f32 v[16:17], v[16:17], v[94:95]
	v_pk_mul_f32 v[18:19], v[18:19], v[88:89]
	v_pk_mul_f32 v[20:21], v[20:21], v[90:91]
	v_pk_mul_f32 v[22:23], v[22:23], v[96:97]
	v_pk_mul_f32 v[24:25], v[24:25], v[100:101]
	v_pk_mul_f32 v[26:27], v[26:27], v[102:103]
	v_pk_mul_f32 v[28:29], v[106:107], v[28:29]
	v_pk_mul_f32 v[30:31], v[84:85], v[30:31]
	v_pk_mul_f32 v[84:85], v[62:63], v[116:117] op_sel_hi:[0,1]
	v_cvt_scalef32_2xpk16_fp6_f32 v[0:5], v[0:15], v[16:31], 1.0
	s_mov_b64 s[100:101], exec
	s_mov_b32 s98, -1
	s_mov_b32 s99, 0
	s_and_b64 exec, s[100:101], s[98:99]
	flat_store_dwordx4 v[34:35], v[0:3] offset:1024
	flat_store_dwordx2 v[86:87], v[4:5] offset:512
	s_andn2_b64 exec, s[100:101], s[98:99]
	flat_store_dwordx4 v[34:35], v[2:5] offset:1024
	flat_store_dwordx2 v[86:87], v[0:1] offset:512
	s_mov_b64 exec, s[100:101]
	global_load_dwordx4 v[0:3], v129, s[56:57] offset:304
	s_nop 0
	global_load_dwordx4 v[4:7], v129, s[56:57] offset:288
	global_load_dwordx4 v[14:17], v129, s[56:57] offset:272
	global_load_dwordx4 v[18:21], v129, s[56:57] offset:256
	global_load_dwordx4 v[24:27], v129, s[56:57] offset:368
	global_load_dwordx4 v[88:91], v129, s[56:57] offset:352
	global_load_dwordx4 v[92:95], v129, s[56:57] offset:336
	global_load_dwordx4 v[96:99], v129, s[56:57] offset:320
	v_pk_mul_f32 v[22:23], v[62:63], v[124:125] op_sel_hi:[0,1]
	v_pk_mul_f32 v[28:29], v[62:63], v[138:139] op_sel_hi:[0,1]
	v_pk_mul_f32 v[10:11], v[62:63], v[150:151] op_sel_hi:[0,1]
	v_pk_mul_f32 v[30:31], v[62:63], v[156:157] op_sel_hi:[0,1]
	v_pk_mul_f32 v[100:101], v[62:63], v[122:123] op_sel_hi:[0,1]
	v_pk_mul_f32 v[8:9], v[62:63], v[136:137] op_sel_hi:[0,1]
	v_pk_mul_f32 v[12:13], v[62:63], v[148:149] op_sel_hi:[0,1]
	s_waitcnt vmcnt(0)
; DEVINL i32x6 pk6(const f32x16& a, const f32x16& b) { return __builtin_amdgcn_cvt_scalef32_2xpk16_fp6_f32(a, b, 1.0f); }
; DEVINL float bflo(unsigned u) { return __uint_as_float(u << 16); }
; DEVINL float bfhi(unsigned u) { return __uint_as_float(u & 0xffff0000u); }
; DEVINL void knorm_image(const Params& p, int ht, int lanen) {
;     ...
; #pragma unroll
;   for (int c = 0; c < 4; ++c) {
;     f32x16 a, b;
; #pragma unroll
;     for (int q = 0; q < 2; ++q)
; #pragma unroll
;       for (int j = 0; j < 4; ++j) {
;         const int kca = c * 4 + q, kcb = c * 4 + 2 + q, da = kca * 8 + 2 * j, db = kcb * 8 + 2 * j;
;         a[q * 8 + 2 * j] = bflo(raw[kca][j]) * r * p.kn_w[da]; a[q * 8 + 2 * j + 1] = bfhi(raw[kca][j]) * r * p.kn_w[da + 1];
;         b[q * 8 + 2 * j] = bflo(raw[kcb][j]) * r * p.kn_w[db]; b[q * 8 + 2 * j + 1] = bfhi(raw[kcb][j]) * r * p.kn_w[db + 1];
;       }
;     const i32x6 w = pk6(a, b);
;     u32x4 wa = {(unsigned)w[0], (unsigned)w[1], (unsigned)w[2], (unsigned)w[3]}; u32x2 wb = {(unsigned)w[4], (unsigned)w[5]};
;     *reinterpret_cast<u32x4*>(dst + c * 1024 + lanen * 16) = wa;
;     *reinterpret_cast<u32x2*>(dst + 4096 + c * 512 + lanen * 8) = wb;
;   }
	v_pk_mul_f32 v[12:13], v[12:13], v[0:1]
	v_pk_mul_f32 v[8:9], v[8:9], v[4:5]
	v_pk_mul_f32 v[4:5], v[100:101], v[14:15]
	v_pk_mul_f32 v[0:1], v[84:85], v[18:19]
	v_pk_mul_f32 v[14:15], v[30:31], v[2:3]
	v_pk_mul_f32 v[10:11], v[10:11], v[6:7]
	v_pk_mul_f32 v[6:7], v[28:29], v[16:17]
	v_pk_mul_f32 v[2:3], v[22:23], v[20:21]
	v_pk_mul_f32 v[18:19], v[62:63], v[68:69] op_sel_hi:[0,1]
	v_pk_mul_f32 v[22:23], v[62:63], v[72:73] op_sel_hi:[0,1]
	v_pk_mul_f32 v[68:69], v[62:63], v[76:77] op_sel_hi:[0,1]
	v_pk_mul_f32 v[30:31], v[62:63], v[82:83] op_sel_hi:[0,1]
	v_pk_mul_f32 v[16:17], v[62:63], v[64:65] op_sel_hi:[0,1]
	v_pk_mul_f32 v[20:21], v[62:63], v[66:67] op_sel_hi:[0,1]
	v_pk_mul_f32 v[64:65], v[62:63], v[70:71] op_sel_hi:[0,1]
	v_pk_mul_f32 v[28:29], v[62:63], v[74:75] op_sel_hi:[0,1]
	v_pk_mul_f32 v[28:29], v[28:29], v[24:25]
	v_pk_mul_f32 v[24:25], v[64:65], v[88:89]
	v_pk_mul_f32 v[20:21], v[20:21], v[92:93]
	v_pk_mul_f32 v[16:17], v[16:17], v[96:97]
	v_pk_mul_f32 v[30:31], v[30:31], v[26:27]
	v_pk_mul_f32 v[26:27], v[68:69], v[90:91]
	v_pk_mul_f32 v[22:23], v[22:23], v[94:95]
	v_pk_mul_f32 v[18:19], v[18:19], v[98:99]
	s_nop 0
	v_cvt_scalef32_2xpk16_fp6_f32 v[0:5], v[0:15], v[16:31], 1.0
	s_mov_b64 s[100:101], exec
	s_mov_b32 s98, -1
	s_mov_b32 s99, 0
	s_and_b64 exec, s[100:101], s[98:99]
	flat_store_dwordx4 v[34:35], v[0:3] offset:2048
	flat_store_dwordx2 v[86:87], v[4:5] offset:1024
	s_andn2_b64 exec, s[100:101], s[98:99]
	flat_store_dwordx4 v[34:35], v[2:5] offset:2048
	flat_store_dwordx2 v[86:87], v[0:1] offset:1024
	s_mov_b64 exec, s[100:101]
	global_load_dwordx4 v[0:3], v129, s[56:57] offset:448
	s_nop 0
	global_load_dwordx4 v[4:7], v129, s[56:57] offset:464
	global_load_dwordx4 v[8:11], v129, s[56:57] offset:480
	global_load_dwordx4 v[12:15], v129, s[56:57] offset:496
	global_load_dwordx4 v[16:19], v129, s[56:57] offset:432
	global_load_dwordx4 v[20:23], v129, s[56:57] offset:416
	global_load_dwordx4 v[64:67], v129, s[56:57] offset:400
	global_load_dwordx4 v[68:71], v129, s[56:57] offset:384
	v_mov_b32_e32 v24, v58
	v_mov_b32_e32 v25, v54
	v_mov_b32_e32 v54, v59
	v_pk_mul_f32 v[24:25], v[62:63], v[24:25] op_sel_hi:[0,1]
	v_mov_b32_e32 v26, v60
	v_mov_b32_e32 v27, v56
	v_mov_b32_e32 v56, v61
	v_mov_b32_e32 v28, v42
	v_mov_b32_e32 v29, v52
	v_pk_mul_f32 v[30:31], v[62:63], v[48:49] op_sel_hi:[0,1]
	v_mov_b32_e32 v52, v43
	s_waitcnt vmcnt(0)
	v_pk_mul_f32 v[0:1], v[30:31], v[0:1]
	v_pk_mul_f32 v[4:5], v[24:25], v[4:5]
	v_pk_mul_f32 v[24:25], v[62:63], v[54:55] op_sel_hi:[0,1]
	v_pk_mul_f32 v[6:7], v[24:25], v[6:7]
	v_pk_mul_f32 v[24:25], v[62:63], v[26:27] op_sel_hi:[0,1]
	v_pk_mul_f32 v[8:9], v[24:25], v[8:9]
	v_pk_mul_f32 v[24:25], v[62:63], v[56:57] op_sel_hi:[0,1]
	v_pk_mul_f32 v[10:11], v[24:25], v[10:11]
	v_pk_mul_f32 v[24:25], v[62:63], v[28:29] op_sel_hi:[0,1]
	v_pk_mul_f32 v[30:31], v[62:63], v[44:45] op_sel_hi:[0,1]
	v_pk_mul_f32 v[12:13], v[24:25], v[12:13]
	v_mov_b32_e32 v24, v78
	v_mov_b32_e32 v25, v32
	v_mov_b32_e32 v32, v79
	v_pk_mul_f32 v[2:3], v[30:31], v[2:3]
	v_pk_mul_f32 v[44:45], v[62:63], v[46:47] op_sel_hi:[0,1]
	v_pk_mul_f32 v[46:47], v[62:63], v[50:51] op_sel_hi:[0,1]
	v_pk_mul_f32 v[26:27], v[62:63], v[80:81] op_sel_hi:[0,1]
	v_pk_mul_f32 v[30:31], v[62:63], v[24:25] op_sel_hi:[0,1]
	v_pk_mul_f32 v[24:25], v[62:63], v[38:39] op_sel_hi:[0,1]
	v_pk_mul_f32 v[28:29], v[62:63], v[32:33] op_sel_hi:[0,1]
	v_pk_mul_f32 v[32:33], v[62:63], v[52:53] op_sel_hi:[0,1]
	v_pk_mul_f32 v[28:29], v[28:29], v[16:17]
	v_pk_mul_f32 v[24:25], v[24:25], v[20:21]
	v_pk_mul_f32 v[20:21], v[36:37], v[64:65]
	v_pk_mul_f32 v[16:17], v[40:41], v[68:69]
	v_pk_mul_f32 v[30:31], v[30:31], v[18:19]
	v_pk_mul_f32 v[26:27], v[26:27], v[22:23]
	v_pk_mul_f32 v[22:23], v[46:47], v[66:67]
	v_pk_mul_f32 v[18:19], v[44:45], v[70:71]
	v_pk_mul_f32 v[14:15], v[32:33], v[14:15]
	s_nop 0
	v_cvt_scalef32_2xpk16_fp6_f32 v[0:5], v[16:31], v[0:15], 1.0
	s_mov_b64 s[100:101], exec
	s_mov_b32 s98, -1
	s_mov_b32 s99, 0
	s_and_b64 exec, s[100:101], s[98:99]
	flat_store_dwordx4 v[34:35], v[0:3] offset:3072
	flat_store_dwordx2 v[86:87], v[4:5] offset:1536
	s_andn2_b64 exec, s[100:101], s[98:99]
	flat_store_dwordx4 v[34:35], v[2:5] offset:3072
	flat_store_dwordx2 v[86:87], v[0:1] offset:1536
	s_mov_b64 exec, s[100:101]

; #define SBAR() __builtin_amdgcn_sched_barrier(0)
; DEVINL i32x8 mk6(int a, int b, int c, int d, int e, int f) { i32x8 r = __builtin_nondeterministic_value(r); r[0] = a; r[1] = b; r[2] = c; r[3] = d; r[4] = e; r[5] = f; return r; }
; #define MFMA6(A, B, C) __builtin_amdgcn_mfma_scale_f32_32x32x64_f8f6f4(A, B, C, 2, 2, 0, 0x7f7f7f7f, 0, 0x7f7f7f7f)
; #define ISSUE_K(j) do { const int _t = (j) < NT ? (j) : NT - 1; char* _d = K_lds + ((j) & 3) * SHM_K8; if (wid < 6) GLDS(K8 + (size_t)_t * 6144 + t16u, _d + tid16); \
;     if (wid < 3) GLDS(Kp8 + (size_t)_t * 3072 + t16u, _d + 6144 + tid16); } while (0)
; #define TILE_SYNC() do { asm volatile("s_waitcnt vmcnt(0)" ::: "memory"); __syncthreads(); } while (0)
; template <bool FUSE>
; DEVINL void qkt(f32x16& p0, f32x16& p1, const char* Ks, const i32x8* q8, int r32, int hi, f32x16& e1) {
;   p0 = f32x16{}; p1 = f32x16{};
;   const char* ka = Ks + hi * 1024 + r32 * 16; const char* kb = Ks + 4096 + hi * 512 + r32 * 8;
;   const char* ra = Ks + 6144 + hi * 1024 + r32 * 16; const char* rb = Ks + 6144 + 2048 + hi * 512 + r32 * 8;
;   u32x4 fa[3][2]; u32x2 fb[3][2];
;     ...
;   QK_LD(0, 0);
; #pragma unroll
;   for (int t = 0; t < 3; ++t) {
;     if (t + 1 < 3) QK_LD(t + 1, (t + 1) % 3);
;     const i32x8 a0 = mk6((int)fa[t][0][0], (int)fa[t][0][1], (int)fa[t][0][2], (int)fa[t][0][3], (int)fb[t][0][0], (int)fb[t][0][1]);
;     const i32x8 a1 = mk6((int)fa[t][1][0], (int)fa[t][1][1], (int)fa[t][1][2], (int)fa[t][1][3], (int)fb[t][1][0], (int)fb[t][1][1]);
;     p0 = MFMA6(a0, q8[t], p0);
;     if (FUSE) {
; #pragma unroll
;       for (int r = 0; r < 3; ++r) { const int rr = t * 6 + r; if (rr < 16) e1[rr] = __builtin_amdgcn_exp2f(e1[rr]); }
;     }
;     p1 = MFMA6(a1, q8[t], p1);
;     if (FUSE) {
; #pragma unroll
;       for (int r = 3; r < 6; ++r) { const int rr = t * 6 + r; if (rr < 16) e1[rr] = __builtin_amdgcn_exp2f(e1[rr]); }
;     }
;     SBAR();
;   }
; DEVINL void mla_block(const Params& p, const bf16_t* __restrict__ Qn, const bf16_t* __restrict__ Qr, const char* __restrict__ K8, const char* __restrict__ Kp8,
;                       const char* __restrict__ V8, const bf16_t* __restrict__ Gb, bf16_t* __restrict__ Yb, char* lds, int pos0) {
;     ...
;   ISSUE_K(0); ISSUE_K(1); ISSUE_K(2); ISSUE_V(0); ISSUE_V(1); TILE_SYNC();
;   qkt<false>(pA0, pA1, KS(0), q8, r32, hi, pA1); partialSM(pA0, pA1, m_reg, mnA, alA, 64, hi);
.LBB0_559:
	s_or_b64 exec, exec, s[8:9]
	s_mul_i32 s8, s75, 0x208000
	s_add_u32 s14, s58, s8
	v_add_u32_e32 v0, 0x9000, v172
	s_addc_u32 s15, s59, 0
	v_readfirstlane_b32 s9, v0
	v_add_u32_e32 v2, 0xb000, v172
	v_lshl_add_u64 v[140:141], s[14:15], 0, v[138:139]
	s_mov_b32 m0, s9
	v_readfirstlane_b32 s9, v2
	global_load_lds_dwordx4 v[140:141], off
	v_lshl_add_u64 v[0:1], v[140:141], 0, s[48:49]
	s_mov_b32 m0, s9
	v_lshlrev_b32_e32 v170, 9, v48
	global_load_lds_dwordx4 v[0:1], off
	v_and_b32_e32 v0, 0x3fffffc0, v166
	v_lshl_add_u32 v171, v0, 2, s68
	v_add_u32_e32 v0, 0, v170
	v_lshlrev_b32_e32 v176, 4, v167
	v_lshlrev_b32_e32 v175, 4, v167
	v_add_u32_e32 v49, v0, v176
	v_add3_u32 v173, v0, v170, v175
	v_add_u32_e32 v0, 0x1000, v49
	s_waitcnt vmcnt(0)
	s_waitcnt vmcnt(0) lgkmcnt(0)
	s_barrier
	ds_read_b128 v[4:7], v0
	ds_read_b128 v[50:53], v173 offset:2048
	ds_read_b128 v[58:61], v173 offset:2560
	ds_read_b128 v[200:203], v0 offset:1024
	ds_read_b128 v[18:21], v173 offset:512
	ds_read_b128 v[0:3], v173
	s_waitcnt lgkmcnt(5)
	v_mov_b32_e32 v16, v6
	v_mov_b32_e32 v17, v7
	s_waitcnt lgkmcnt(0)
	v_mfma_scale_f32_32x32x64_f8f6f4 v[32:47], v[0:5], v[120:125], 0, v162, v143 op_sel_hi:[0,0,0] cbsz:2 blgp:2
	s_mov_b32 s12, s13
	s_mov_b32 s14, s13
	s_mov_b32 s15, s13
	s_mov_b32 s16, s13
	s_mov_b32 s17, s13
	s_mov_b32 s18, s13
	s_mov_b32 s19, s13
	v_mfma_scale_f32_32x32x64_f8f6f4 v[16:31], v[16:21], v[120:125], 0, v162, v143 op_sel_hi:[0,0,0] cbsz:2 blgp:2
	s_mov_b32 s20, s13
	s_mov_b32 s21, s13
	s_mov_b32 s22, s13
	s_mov_b32 s23, s13
	s_mov_b32 s24, s13
	s_mov_b32 s25, s13
	s_mov_b32 s26, s13
	s_mov_b32 s27, s13
	v_mov_b64_e32 v[0:1], s[12:13]
	v_and_b32_e32 v169, 63, v166
	v_lshlrev_b32_e32 v174, 10, v48
	s_mov_b32 s53, 4
	v_mov_b64_e32 v[2:3], s[14:15]
	v_mov_b64_e32 v[4:5], s[16:17]
	v_mov_b64_e32 v[6:7], s[18:19]
	v_mov_b64_e32 v[8:9], s[20:21]
	v_mov_b64_e32 v[10:11], s[22:23]
	v_mov_b64_e32 v[12:13], s[24:25]
	v_mov_b64_e32 v[14:15], s[26:27]
	v_mov_b32_e32 v54, v200
	v_mov_b32_e32 v55, v201
	v_mov_b32_e32 v56, v202
	v_mov_b32_e32 v57, v203
	v_add_u32_e32 v49, 0x2000, v49
	v_mfma_scale_f32_32x32x64_f8f6f4 v[32:47], v[50:55], v[126:131], v[32:47], v162, v143 op_sel_hi:[0,0,0] cbsz:2 blgp:2
	ds_read_b128 v[50:53], v173 offset:6144
	ds_read_b128 v[64:67], v173 offset:6656
	ds_read_b128 v[204:207], v49
	v_mfma_scale_f32_32x32x64_f8f6f4 v[16:31], v[56:61], v[126:131], v[16:31], v162, v143 op_sel_hi:[0,0,0] cbsz:2 blgp:2
	s_waitcnt lgkmcnt(0)
; DEVINL int crow(int r, int hi) { return (r & 3) + 8 * (r >> 2) + 4 * hi; }
; #define SBAR() __builtin_amdgcn_sched_barrier(0)
; DEVINL void partialSM(f32x16& p0, f32x16& p1, float& m_reg, float& mn, float& alpha, int kvalid, int hi) {
;   constexpr float C = MLA_SCALE * 1.4426950408889634f;
;   if (kvalid < 64) {
; #pragma unroll
;     for (int r = 0; r < 16; ++r) { if (crow(r, hi) >= kvalid) p0[r] = -1e30f; if (32 + crow(r, hi) >= kvalid) p1[r] = -1e30f; }
;   }
;   float pmax = p0[0];
; #pragma unroll
;   for (int r = 1; r < 16; ++r) pmax = fmaxf(pmax, p0[r]);
; #pragma unroll
;   for (int r = 0; r < 16; ++r) pmax = fmaxf(pmax, p1[r]);
;   { auto rr = __builtin_amdgcn_permlane32_swap(__float_as_uint(pmax), __float_as_uint(pmax), false, false);
;     pmax = fmaxf(__uint_as_float(rr[0]), __uint_as_float(rr[1])); }
;   if (__builtin_expect(__all(pmax - m_reg <= THR / MLA_SCALE), 1)) { mn = m_reg; alpha = 1.f; }
;   else { mn = fmaxf(m_reg, pmax); alpha = __builtin_amdgcn_exp2f((m_reg - mn) * C); m_reg = mn; }
;   const float mnC = PSHIFT - mn * C;
;   const f32x2 C2 = {C, C}, M2 = {mnC, mnC};
; #pragma unroll
;   for (int r = 0; r < 16; r += 2) { f32x2 v = {p0[r], p0[r + 1]}; v = __builtin_elementwise_fma(v, C2, M2); p0[r] = v[0]; p0[r + 1] = v[1]; }
; #pragma unroll
;   for (int r = 0; r < 16; r += 2) { f32x2 v = {p1[r], p1[r + 1]}; v = __builtin_elementwise_fma(v, C2, M2); p1[r] = v[0]; p1[r + 1] = v[1]; }
; #pragma unroll
;   for (int r = 0; r < 16; ++r) p0[r] = __builtin_amdgcn_exp2f(p0[r]);
; DEVINL void mla_block(const Params& p, const bf16_t* __restrict__ Qn, const bf16_t* __restrict__ Qr, const char* __restrict__ K8, const char* __restrict__ Kp8,
;                       const char* __restrict__ V8, const bf16_t* __restrict__ Gb, bf16_t* __restrict__ Yb, char* lds, int pos0) {
;     ...
;   f32x16 pA0, pA1, pB0, pB1; float mnA, mnB, alA, alB; i32x8 pa; VFrag vf; constexpr int NT = NT_MLA;
;   const i32x8 ones8 = {0x38383838, 0x38383838, 0x38383838, 0x38383838, 0x38383838, 0x38383838, 0x38383838, 0x38383838};
;   f32x16 lsum;
;     ...
;   ISSUE_K(0); ISSUE_K(1); ISSUE_K(2); ISSUE_V(0); ISSUE_V(1); TILE_SYNC();
;   qkt<false>(pA0, pA1, KS(0), q8, r32, hi, pA1); partialSM(pA0, pA1, m_reg, mnA, alA, 64, hi);
;   for (int j = 1; j + 1 < NT; j += 2) {
;     ISSUE_K(j + 2); ISSUE_K(j + 3); ISSUE_V(j + 1); ISSUE_V(j + 2); SBAR();
	v_mov_b32_e32 v54, v204
	v_mov_b32_e32 v55, v205
	v_mov_b32_e32 v62, v206
	v_mov_b32_e32 v63, v207
	v_mfma_scale_f32_32x32x64_f8f6f4 v[32:47], v[50:55], v[132:137], v[32:47], v162, v143 op_sel_hi:[0,0,0] cbsz:2 blgp:2
	s_nop 0
	v_mfma_scale_f32_32x32x64_f8f6f4 v[16:31], v[62:67], v[132:137], v[16:31], v162, v143 op_sel_hi:[0,0,0] cbsz:2 blgp:2
	s_nop 9
	v_max_f32_e32 v49, v33, v33
	v_max_f32_e32 v50, v32, v32
	v_max_f32_e32 v49, v50, v49
	v_max3_f32 v49, v49, v34, v35
	v_max3_f32 v49, v49, v36, v37
	v_max3_f32 v49, v49, v38, v39
	v_max3_f32 v49, v49, v40, v41
	v_max3_f32 v49, v49, v42, v43
	v_max3_f32 v49, v49, v44, v45
	v_max3_f32 v49, v49, v46, v47
	v_max3_f32 v49, v49, v16, v17
	v_max3_f32 v49, v49, v18, v19
	v_max3_f32 v49, v49, v20, v21
	v_max3_f32 v49, v49, v22, v23
	v_max3_f32 v49, v49, v24, v25
	v_max3_f32 v49, v49, v26, v27
	v_max3_f32 v49, v49, v28, v29
	v_max3_f32 v49, v49, v30, v31
	v_mov_b32_e32 v50, v49
	s_nop 1
	v_permlane32_swap_b32_e32 v49, v50
	v_max_f32_e32 v50, v50, v50
	v_max_f32_e32 v49, v49, v49
	v_max_f32_e32 v49, v49, v50
	v_add_f32_e32 v50, 0x7149f2ca, v49
	v_max_f32_e32 v49, 0xf149f2ca, v49
	v_sub_f32_e32 v51, 0xf149f2ca, v49
	v_mul_f32_e32 v51, 1.0, v51
	v_cmp_ge_f32_e32 vcc, s69, v50
	v_exp_f32_e32 v51, v51
	s_cmp_eq_u64 vcc, exec
	s_cselect_b64 vcc, -1, 0
	v_cndmask_b32_e32 v181, v49, v163, vcc
	v_fmamk_f32 v50, v181, 0xbf800000, v164
	v_pk_fma_f32 v[32:33], v[32:33], s[50:51], v[50:51] op_sel_hi:[1,0,0]
	v_pk_fma_f32 v[34:35], v[34:35], s[50:51], v[50:51] op_sel_hi:[1,0,0]
	v_pk_fma_f32 v[36:37], v[36:37], s[50:51], v[50:51] op_sel_hi:[1,0,0]
	v_pk_fma_f32 v[38:39], v[38:39], s[50:51], v[50:51] op_sel_hi:[1,0,0]
	v_pk_fma_f32 v[40:41], v[40:41], s[50:51], v[50:51] op_sel_hi:[1,0,0]
	v_pk_fma_f32 v[42:43], v[42:43], s[50:51], v[50:51] op_sel_hi:[1,0,0]
	v_pk_fma_f32 v[44:45], v[44:45], s[50:51], v[50:51] op_sel_hi:[1,0,0]
	v_pk_fma_f32 v[46:47], v[46:47], s[50:51], v[50:51] op_sel_hi:[1,0,0]
	v_exp_f32_e32 v65, v32
	v_exp_f32_e32 v197, v33
	v_exp_f32_e32 v187, v34
	v_exp_f32_e32 v189, v35
	v_exp_f32_e32 v195, v36
	v_exp_f32_e32 v196, v37
	v_exp_f32_e32 v191, v38
	v_exp_f32_e32 v192, v39
	v_exp_f32_e32 v193, v40
	v_exp_f32_e32 v194, v41
	v_exp_f32_e32 v183, v42
	v_exp_f32_e32 v184, v43
	v_exp_f32_e32 v188, v44
	v_exp_f32_e32 v190, v45
	v_exp_f32_e32 v185, v46
	v_exp_f32_e32 v186, v47
	s_add_u32 s8, s30, s8
	v_cndmask_b32_e64 v179, v51, 1.0, vcc
	v_pk_fma_f32 v[148:149], v[30:31], s[50:51], v[50:51] op_sel_hi:[1,0,0]
	v_pk_fma_f32 v[150:151], v[28:29], s[50:51], v[50:51] op_sel_hi:[1,0,0]
	v_pk_fma_f32 v[152:153], v[26:27], s[50:51], v[50:51] op_sel_hi:[1,0,0]
	v_pk_fma_f32 v[154:155], v[24:25], s[50:51], v[50:51] op_sel_hi:[1,0,0]
	v_pk_fma_f32 v[156:157], v[22:23], s[50:51], v[50:51] op_sel_hi:[1,0,0]
	v_pk_fma_f32 v[82:83], v[20:21], s[50:51], v[50:51] op_sel_hi:[1,0,0]
	v_pk_fma_f32 v[158:159], v[18:19], s[50:51], v[50:51] op_sel_hi:[1,0,0]
	v_pk_fma_f32 v[160:161], v[16:17], s[50:51], v[50:51] op_sel_hi:[1,0,0]
	v_lshlrev_b32_e32 v177, 4, v48
	s_addc_u32 s9, s31, 0
	v_mov_b64_e32 v[62:63], v[14:15]
	v_mov_b64_e32 v[30:31], v[14:15]
	v_mov_b64_e32 v[46:47], v[14:15]
	v_lshl_add_u64 v[144:145], s[34:35], 0, v[138:139]
	v_cmp_gt_u32_e64 s[6:7], 32, v169
	v_lshl_add_u32 v178, v167, 2, v171
	v_lshl_add_u64 v[146:147], s[8:9], 0, v[138:139]
	v_mov_b32_e32 v180, 0
	s_mov_b64 s[14:15], 0x89dc400
	v_mov_b64_e32 v[60:61], v[12:13]
	v_mov_b64_e32 v[58:59], v[10:11]
	v_mov_b64_e32 v[56:57], v[8:9]
	v_mov_b64_e32 v[54:55], v[6:7]
	v_mov_b64_e32 v[52:53], v[4:5]
	v_mov_b64_e32 v[50:51], v[2:3]
	v_mov_b64_e32 v[48:49], v[0:1]
	v_mov_b64_e32 v[28:29], v[12:13]
	v_mov_b64_e32 v[26:27], v[10:11]
	v_mov_b64_e32 v[24:25], v[8:9]
	v_mov_b64_e32 v[22:23], v[6:7]
	v_mov_b64_e32 v[20:21], v[4:5]
	v_mov_b64_e32 v[18:19], v[2:3]
	v_mov_b64_e32 v[16:17], v[0:1]
	v_mov_b64_e32 v[44:45], v[12:13]
	v_mov_b64_e32 v[42:43], v[10:11]
	v_mov_b64_e32 v[40:41], v[8:9]
	v_mov_b64_e32 v[38:39], v[6:7]
	v_mov_b64_e32 v[36:37], v[4:5]
	v_mov_b64_e32 v[34:35], v[2:3]
	v_mov_b64_e32 v[32:33], v[0:1]
	v_lshrrev_b32_e32 v175, 4, v169
	v_and_b32_e32 v175, 1, v175
	v_bfe_u32 v174, v169, 2, 2
	v_cmp_eq_u32_e64 s[8:9], v174, v175
	v_mov_b32_e32 v174, 0x38383838
	s_nop 1
	v_cndmask_b32_e64 v232, 0, v174, s[8:9]
	v_mov_b32_e32 v233, v232
	v_mov_b32_e32 v234, v232
	v_mov_b32_e32 v235, v232
	v_mov_b32_e32 v236, v232
	v_mov_b32_e32 v237, v232
	v_mov_b32_e32 v238, v232
	v_mov_b32_e32 v239, v232
	v_add_u32_e32 v176, v170, v176
	v_add_u32_e32 v176, 0x1000, v176
	v_mov_b32_e32 v64, v65
	v_mov_b32_e32 v84, v82
	v_mov_b32_e32 v85, v83
	v_mov_b32_e32 v65, v197
	v_mov_b32_e32 v66, v187
	v_mov_b32_e32 v67, v189
	v_mov_b32_e32 v68, v195
	v_mov_b32_e32 v69, v196
	v_mov_b32_e32 v70, v191
	v_mov_b32_e32 v71, v192
	v_mov_b32_e32 v72, v193
	v_mov_b32_e32 v73, v194
	v_mov_b32_e32 v74, v183
	v_mov_b32_e32 v75, v184
	v_mov_b32_e32 v76, v188
	v_mov_b32_e32 v77, v190
	v_mov_b32_e32 v78, v185
	v_mov_b32_e32 v79, v186
	v_mov_b32_e32 v80, v160
	v_mov_b32_e32 v81, v161
	v_mov_b32_e32 v82, v158
	v_mov_b32_e32 v83, v159
	v_mov_b32_e32 v86, v156
	v_mov_b32_e32 v87, v157
	v_mov_b32_e32 v88, v154
	v_mov_b32_e32 v89, v155
	v_mov_b32_e32 v90, v152
	v_mov_b32_e32 v91, v153
	v_mov_b32_e32 v92, v150
	v_mov_b32_e32 v93, v151
	v_mov_b32_e32 v94, v148
	v_mov_b32_e32 v95, v149
	s_lshl_b32 s78, s3, 4
	s_add_i32 s79, s78, 0x9000
	s_mul_i32 s80, s75, 0x186000
	s_add_u32 s80, s56, s80
	s_addc_u32 s81, s57, 0
	s_mov_b64 s[82:83], s[34:35]
	s_mul_i32 s84, s75, 0x208000
	s_add_u32 s84, s58, s84
	s_addc_u32 s85, s59, 0
	v_lshlrev_b32_e32 v231, 4, v169
	v_fmamk_f32 v230, v181, 0xbf800000, v164
	v_add_u32_e32 v140, 0x8000, v173
	v_mov_b32_e32 v240, v230
	v_mov_b32_e32 v241, v230
	v_mov_b32_e32 v242, v230
	v_mov_b32_e32 v243, v230
	v_mov_b32_e32 v244, v230
	v_mov_b32_e32 v245, v230
	v_mov_b32_e32 v246, v230
	v_mov_b32_e32 v247, v230
	v_mov_b32_e32 v248, v230
	v_mov_b32_e32 v249, v230
	v_mov_b32_e32 v250, v230
	v_mov_b32_e32 v251, v230
	v_mov_b32_e32 v252, v230
	v_mov_b32_e32 v253, v230
	v_mov_b32_e32 v254, v230
	v_mov_b32_e32 v255, v230
	v_mov_b32_e32 v144, 0
	v_mov_b32_e32 v226, 1.0
	ds_read_b128 v[104:107], v173 offset:9216
	ds_read_b128 v[108:111], v176 offset:9216
	ds_read_b128 v[112:115], v173 offset:9728
	ds_read_b128 v[148:151], v173 offset:11264
	ds_read_b128 v[152:155], v176 offset:10240
	ds_read_b128 v[156:159], v173 offset:11776
	ds_read_b128 v[214:217], v173 offset:15360
	ds_read_b128 v[218:221], v176 offset:13312
	ds_read_b128 v[222:225], v173 offset:15872
	s_cmp_ge_u32 s3, 0x100
	s_cbranch_scc1 .Lprio_skip
	s_setprio 2

; DEVINL void pv_psm(f32x16* o, const VFrag& f, const i32x8& pa, f32x16& lsum, const i32x8& ones8,
;                    f32x16& p0, f32x16& p1, float& m_reg, float& mn, float& alpha, int kvalid, int hi) {
;   constexpr float C = MLA_SCALE * 1.4426950408889634f;
;     ...
;   if (kvalid < 64) {
; #pragma unroll
;     for (int r = 0; r < 16; ++r) { if (crow(r, hi) >= kvalid) p0[r] = -1e30f; if (32 + crow(r, hi) >= kvalid) p1[r] = -1e30f; }
;   }
;   PVM(0);
;   float pmax = p0[0];
; #pragma unroll
;   for (int r = 1; r < 16; ++r) pmax = fmaxf(pmax, p0[r]);
;   SBAR();
;   PVM(1);
; #pragma unroll
;   for (int r = 0; r < 16; ++r) pmax = fmaxf(pmax, p1[r]);
;   { auto rr = __builtin_amdgcn_permlane32_swap(__float_as_uint(pmax), __float_as_uint(pmax), false, false);
;     pmax = fmaxf(__uint_as_float(rr[0]), __uint_as_float(rr[1])); }
;   SBAR();
;   PVM(2);
;   if (__builtin_expect(__all(pmax - m_reg <= THR / MLA_SCALE), 1)) { mn = m_reg; alpha = 1.f; }
;   else { mn = fmaxf(m_reg, pmax); alpha = __builtin_amdgcn_exp2f((m_reg - mn) * C); m_reg = mn; }
;   const float mnC = PSHIFT - mn * C;
;   const f32x2 C2 = {C, C}, M2 = {mnC, mnC};
; #pragma unroll
;   for (int r = 0; r < 16; r += 2) { f32x2 v = {p0[r], p0[r + 1]}; v = __builtin_elementwise_fma(v, C2, M2); p0[r] = v[0]; p0[r + 1] = v[1]; }
;   SBAR();
;   PVM(3);
; #pragma unroll
;   for (int r = 0; r < 16; r += 2) { f32x2 v = {p1[r], p1[r + 1]}; v = __builtin_elementwise_fma(v, C2, M2); p1[r] = v[0]; p1[r + 1] = v[1]; }
; #pragma unroll
;   for (int r = 0; r < 8; ++r) p0[r] = __builtin_amdgcn_exp2f(p0[r]);
;   SBAR();
;   lsum = MFMA8(ones8, pa, (f32x16{}));
; #pragma unroll
;   for (int r = 8; r < 16; ++r) p0[r] = __builtin_amdgcn_exp2f(p0[r]);
; DEVINL void mla_block(const Params& p, const bf16_t* __restrict__ Qn, const bf16_t* __restrict__ Qr, const char* __restrict__ K8, const char* __restrict__ Kp8,
;                       const char* __restrict__ V8, const bf16_t* __restrict__ Gb, bf16_t* __restrict__ Yb, char* lds, int pos0) {
;     ...
;   for (int j = 1; j + 1 < NT; j += 2) {
;     ISSUE_K(j + 2); ISSUE_K(j + 3); ISSUE_V(j + 1); ISSUE_V(j + 2); SBAR();
;     qkt<true>(pB0, pB1, KS(j), q8, r32, hi, pA1);
;     pv_load(vf, VS(j - 1), r32, hi); SBAR();
;     finishSM<true>(pA0, pA1, alA, l_reg, pa); SBAR();
;     pv_psm(o, vf, pa, lsum, ones8, pB0, pB1, m_reg, mnB, alB, 64, hi);
;     LUPD(alA); RESC(alB); SBAR();
.Ldma_done:
	v_exp_f32_e32 v80, v80
	v_exp_f32_e32 v81, v81
	s_waitcnt lgkmcnt(6)
	v_mfma_scale_f32_32x32x64_f8f6f4 v[182:197], v[104:109], v[120:125], v[240:255], v162, v143 op_sel_hi:[0,0,0] cbsz:2 blgp:2
	v_exp_f32_e32 v82, v82
	v_exp_f32_e32 v83, v83
	v_exp_f32_e32 v84, v84
	v_exp_f32_e32 v85, v85
	v_mfma_scale_f32_32x32x64_f8f6f4 v[198:213], v[110:115], v[120:125], v[240:255], v162, v143 op_sel_hi:[0,0,0] cbsz:2 blgp:2
	ds_read_b128 v[104:107], v140 offset:4096
	ds_read_b128 v[108:111], v140 offset:4608
	ds_read_b128 v[112:115], v140 offset:6144
	ds_read_b128 v[116:119], v140 offset:6656
	v_exp_f32_e32 v86, v86
	s_waitcnt lgkmcnt(7)
	v_mfma_scale_f32_32x32x64_f8f6f4 v[182:197], v[148:153], v[126:131], v[182:197], v162, v143 op_sel_hi:[0,0,0] cbsz:2 blgp:2
	v_exp_f32_e32 v87, v87
	v_exp_f32_e32 v88, v88
	v_exp_f32_e32 v89, v89
	v_exp_f32_e32 v90, v90
	v_fma_f32 v180, v226, v180, v144
	v_mfma_scale_f32_32x32x64_f8f6f4 v[198:213], v[154:159], v[126:131], v[198:213], v162, v143 op_sel_hi:[0,0,0] cbsz:2 blgp:2
	ds_read_b128 v[148:151], v140 offset:8192
	ds_read_b128 v[152:155], v140 offset:8704
	v_exp_f32_e32 v91, v91
	v_exp_f32_e32 v92, v92
	s_waitcnt lgkmcnt(6)
	v_mfma_scale_f32_32x32x64_f8f6f4 v[182:197], v[214:219], v[132:137], v[182:197], v162, v143 op_sel_hi:[0,0,0] cbsz:2 blgp:2
	v_exp_f32_e32 v93, v93
	v_exp_f32_e32 v94, v94
	v_exp_f32_e32 v95, v95
	v_cvt_pk_fp8_f32 v96, v64, v65
	v_cvt_pk_fp8_f32 v97, v68, v69
	v_mfma_scale_f32_32x32x64_f8f6f4 v[198:213], v[220:225], v[132:137], v[198:213], v162, v143 op_sel_hi:[0,0,0] cbsz:2 blgp:2
	ds_read_b128 v[214:217], v140 offset:10240
	ds_read_b128 v[218:221], v140 offset:10752
	v_cvt_pk_fp8_f32 v98, v72, v73
	v_cvt_pk_fp8_f32 v99, v76, v77
	v_cvt_pk_fp8_f32 v96, v66, v67 op_sel:[0,0,1]
	v_cvt_pk_fp8_f32 v97, v70, v71 op_sel:[0,0,1]
	v_cvt_pk_fp8_f32 v98, v74, v75 op_sel:[0,0,1]
	v_cvt_pk_fp8_f32 v99, v78, v79 op_sel:[0,0,1]
	v_cvt_pk_fp8_f32 v100, v80, v81
	v_cvt_pk_fp8_f32 v101, v84, v85
	v_cvt_pk_fp8_f32 v102, v88, v89
	v_cvt_pk_fp8_f32 v103, v92, v93
	v_cvt_pk_fp8_f32 v100, v82, v83 op_sel:[0,0,1]
	v_cvt_pk_fp8_f32 v101, v86, v87 op_sel:[0,0,1]
	v_cvt_pk_fp8_f32 v102, v90, v91 op_sel:[0,0,1]
	v_cvt_pk_fp8_f32 v103, v94, v95 op_sel:[0,0,1]
	s_waitcnt lgkmcnt(2)
	s_nop 0
	v_mfma_f32_32x32x64_f8f6f4 v[0:15], v[96:103], v[104:111], v[0:15]
	v_max_f32_e32 v229, v182, v183
	v_max3_f32 v229, v229, v184, v185
	v_max3_f32 v229, v229, v186, v187
	v_max3_f32 v229, v229, v188, v189
	v_max3_f32 v229, v229, v190, v191
	v_max3_f32 v229, v229, v192, v193
	v_max3_f32 v229, v229, v194, v195
	v_max3_f32 v229, v229, v196, v197
	v_mfma_f32_32x32x64_f8f6f4 v[48:63], v[96:103], v[112:119], v[48:63]
	v_max3_f32 v229, v229, v198, v199
	v_max3_f32 v229, v229, v200, v201
	v_max3_f32 v229, v229, v202, v203
	v_max3_f32 v229, v229, v204, v205
	v_max3_f32 v229, v229, v206, v207
	v_max3_f32 v229, v229, v208, v209
	v_max3_f32 v229, v229, v210, v211
	v_max3_f32 v229, v229, v212, v213
	v_mov_b32_e32 v160, v229
	s_nop 1
	v_permlane32_swap_b32_e32 v229, v160
	v_max_f32_e32 v229, v229, v160
	v_cmp_ge_f32_e32 vcc, s69, v229
	s_cmp_eq_u64 vcc, exec
	v_mov_b32_e32 v226, 1.0
	s_cbranch_scc0 .Lslow_a0
	ds_read_b128 v[104:107], v173 offset:18432
	ds_read_b128 v[108:111], v176 offset:18432
	ds_read_b128 v[112:115], v173 offset:18944
	v_mfma_f32_32x32x64_f8f6f4 v[16:31], v[96:103], v[148:155], v[16:31]
	v_exp_f32_e32 v182, v182
	v_exp_f32_e32 v183, v183
	v_exp_f32_e32 v184, v184
	v_exp_f32_e32 v185, v185
	v_exp_f32_e32 v186, v186
	v_exp_f32_e32 v187, v187
	ds_read_b128 v[148:151], v173 offset:20480
	ds_read_b128 v[152:155], v176 offset:19456
	ds_read_b128 v[156:159], v173 offset:20992
	s_waitcnt lgkmcnt(6)
	v_mfma_f32_32x32x64_f8f6f4 v[32:47], v[96:103], v[214:221], v[32:47]
	v_exp_f32_e32 v188, v188
	v_exp_f32_e32 v189, v189
	v_exp_f32_e32 v190, v190
	v_exp_f32_e32 v191, v191
	v_exp_f32_e32 v192, v192
	v_exp_f32_e32 v193, v193
	ds_read_b128 v[214:217], v173 offset:24576
	ds_read_b128 v[218:221], v176 offset:22528
	ds_read_b128 v[222:225], v173 offset:25088
	v_mfma_f32_16x16x128_f8f6f4 v[144:147], v[232:239], v[96:103], 0
	v_exp_f32_e32 v194, v194
	v_exp_f32_e32 v195, v195
	v_exp_f32_e32 v196, v196
	v_exp_f32_e32 v197, v197
; #define SBAR() __builtin_amdgcn_sched_barrier(0)
; DEVINL void pv_psm(f32x16* o, const VFrag& f, const i32x8& pa, f32x16& lsum, const i32x8& ones8,
;                    f32x16& p0, f32x16& p1, float& m_reg, float& mn, float& alpha, int kvalid, int hi) {
;   constexpr float C = MLA_SCALE * 1.4426950408889634f;
;     ...
;   if (kvalid < 64) {
; #pragma unroll
;     for (int r = 0; r < 16; ++r) { if (crow(r, hi) >= kvalid) p0[r] = -1e30f; if (32 + crow(r, hi) >= kvalid) p1[r] = -1e30f; }
;   }
;   PVM(0);
;   float pmax = p0[0];
; #pragma unroll
;   for (int r = 1; r < 16; ++r) pmax = fmaxf(pmax, p0[r]);
;   SBAR();
;   PVM(1);
; #pragma unroll
;   for (int r = 0; r < 16; ++r) pmax = fmaxf(pmax, p1[r]);
;   { auto rr = __builtin_amdgcn_permlane32_swap(__float_as_uint(pmax), __float_as_uint(pmax), false, false);
;     pmax = fmaxf(__uint_as_float(rr[0]), __uint_as_float(rr[1])); }
;   SBAR();
;   PVM(2);
;   if (__builtin_expect(__all(pmax - m_reg <= THR / MLA_SCALE), 1)) { mn = m_reg; alpha = 1.f; }
;   else { mn = fmaxf(m_reg, pmax); alpha = __builtin_amdgcn_exp2f((m_reg - mn) * C); m_reg = mn; }
;   const float mnC = PSHIFT - mn * C;
;   const f32x2 C2 = {C, C}, M2 = {mnC, mnC};
; #pragma unroll
;   for (int r = 0; r < 16; r += 2) { f32x2 v = {p0[r], p0[r + 1]}; v = __builtin_elementwise_fma(v, C2, M2); p0[r] = v[0]; p0[r + 1] = v[1]; }
;   SBAR();
;   PVM(3);
; #pragma unroll
;   for (int r = 0; r < 16; r += 2) { f32x2 v = {p1[r], p1[r + 1]}; v = __builtin_elementwise_fma(v, C2, M2); p1[r] = v[0]; p1[r + 1] = v[1]; }
; #pragma unroll
;   for (int r = 0; r < 8; ++r) p0[r] = __builtin_amdgcn_exp2f(p0[r]);
;   SBAR();
;   lsum = MFMA8(ones8, pa, (f32x16{}));
; #pragma unroll
;   for (int r = 8; r < 16; ++r) p0[r] = __builtin_amdgcn_exp2f(p0[r]);
;   SBAR();
;     ...
; }
; DEVINL void mla_block(const Params& p, const bf16_t* __restrict__ Qn, const bf16_t* __restrict__ Qr, const char* __restrict__ K8, const char* __restrict__ Kp8,
;                       const char* __restrict__ V8, const bf16_t* __restrict__ Gb, bf16_t* __restrict__ Yb, char* lds, int pos0) {
;     ...
;     qkt<true>(pA0, pA1, KS(j + 1), q8, r32, hi, pB1);
;     pv_load(vf, VS(j), r32, hi); SBAR();
;     finishSM<true>(pB0, pB1, alB, l_reg, pa); SBAR();
;     { const float alPrev = alB; pv_psm(o, vf, pa, lsum, ones8, pA0, pA1, m_reg, mnA, alA, L - (j + 1) * KVBLK, hi); LUPD(alPrev); }
;     TILE_SYNC(); RESC(alA);
.Ljoin_a0:
	v_exp_f32_e32 v198, v198
	v_exp_f32_e32 v199, v199
	s_waitcnt lgkmcnt(6)
	v_mfma_scale_f32_32x32x64_f8f6f4 v[64:79], v[104:109], v[120:125], v[240:255], v162, v143 op_sel_hi:[0,0,0] cbsz:2 blgp:2
	v_exp_f32_e32 v200, v200
	v_exp_f32_e32 v201, v201
	v_exp_f32_e32 v202, v202
	v_exp_f32_e32 v203, v203
	v_mfma_scale_f32_32x32x64_f8f6f4 v[80:95], v[110:115], v[120:125], v[240:255], v162, v143 op_sel_hi:[0,0,0] cbsz:2 blgp:2
	ds_read_b128 v[104:107], v140 offset:12288
	ds_read_b128 v[108:111], v140 offset:12800
	ds_read_b128 v[112:115], v140 offset:14336
	ds_read_b128 v[116:119], v140 offset:14848
	v_exp_f32_e32 v204, v204
	s_waitcnt lgkmcnt(7)
	v_mfma_scale_f32_32x32x64_f8f6f4 v[64:79], v[148:153], v[126:131], v[64:79], v162, v143 op_sel_hi:[0,0,0] cbsz:2 blgp:2
	v_exp_f32_e32 v205, v205
	v_exp_f32_e32 v206, v206
	v_exp_f32_e32 v207, v207
	v_exp_f32_e32 v208, v208
	v_fma_f32 v180, v179, v180, v144
	v_mfma_scale_f32_32x32x64_f8f6f4 v[80:95], v[154:159], v[126:131], v[80:95], v162, v143 op_sel_hi:[0,0,0] cbsz:2 blgp:2
	ds_read_b128 v[148:151], v140 offset:16384
	ds_read_b128 v[152:155], v140 offset:16896
	v_exp_f32_e32 v209, v209
	v_exp_f32_e32 v210, v210
	s_waitcnt lgkmcnt(6)
	v_mfma_scale_f32_32x32x64_f8f6f4 v[64:79], v[214:219], v[132:137], v[64:79], v162, v143 op_sel_hi:[0,0,0] cbsz:2 blgp:2
	v_exp_f32_e32 v211, v211
	v_exp_f32_e32 v212, v212
	v_exp_f32_e32 v213, v213
	v_cvt_pk_fp8_f32 v96, v182, v183
	v_cvt_pk_fp8_f32 v97, v186, v187
	v_mfma_scale_f32_32x32x64_f8f6f4 v[80:95], v[220:225], v[132:137], v[80:95], v162, v143 op_sel_hi:[0,0,0] cbsz:2 blgp:2
	ds_read_b128 v[214:217], v140 offset:18432
	ds_read_b128 v[218:221], v140 offset:18944
	v_cvt_pk_fp8_f32 v98, v190, v191
	v_cvt_pk_fp8_f32 v99, v194, v195
	v_cvt_pk_fp8_f32 v96, v184, v185 op_sel:[0,0,1]
	v_cvt_pk_fp8_f32 v97, v188, v189 op_sel:[0,0,1]
	v_cvt_pk_fp8_f32 v98, v192, v193 op_sel:[0,0,1]
	v_cvt_pk_fp8_f32 v99, v196, v197 op_sel:[0,0,1]
	v_cvt_pk_fp8_f32 v100, v198, v199
	v_cvt_pk_fp8_f32 v101, v202, v203
	v_cvt_pk_fp8_f32 v102, v206, v207
	v_cvt_pk_fp8_f32 v103, v210, v211
	v_cvt_pk_fp8_f32 v100, v200, v201 op_sel:[0,0,1]
	v_cvt_pk_fp8_f32 v101, v204, v205 op_sel:[0,0,1]
	v_cvt_pk_fp8_f32 v102, v208, v209 op_sel:[0,0,1]
	v_cvt_pk_fp8_f32 v103, v212, v213 op_sel:[0,0,1]
	s_waitcnt lgkmcnt(2)
	s_nop 0
	v_mfma_f32_32x32x64_f8f6f4 v[0:15], v[96:103], v[104:111], v[0:15]
	v_max_f32_e32 v229, v64, v65
	v_max3_f32 v229, v229, v66, v67
	v_max3_f32 v229, v229, v68, v69
	v_max3_f32 v229, v229, v70, v71
	v_max3_f32 v229, v229, v72, v73
	v_max3_f32 v229, v229, v74, v75
	v_max3_f32 v229, v229, v76, v77
	v_max3_f32 v229, v229, v78, v79
	v_mfma_f32_32x32x64_f8f6f4 v[48:63], v[96:103], v[112:119], v[48:63]
	v_max3_f32 v229, v229, v80, v81
	v_max3_f32 v229, v229, v82, v83
	v_max3_f32 v229, v229, v84, v85
	v_max3_f32 v229, v229, v86, v87
	v_max3_f32 v229, v229, v88, v89
	v_max3_f32 v229, v229, v90, v91
	v_max3_f32 v229, v229, v92, v93
	v_max3_f32 v229, v229, v94, v95
	v_mov_b32_e32 v160, v229
	s_nop 1
	v_permlane32_swap_b32_e32 v229, v160
	v_max_f32_e32 v229, v229, v160
	v_cmp_ge_f32_e32 vcc, s69, v229
	s_cmp_eq_u64 vcc, exec
	v_mov_b32_e32 v228, 1.0
	s_cbranch_scc0 .Lslow_b0
	s_waitcnt vmcnt(0) lgkmcnt(0)
	s_barrier
	ds_read_b128 v[104:107], v173 offset:27648
	ds_read_b128 v[108:111], v176 offset:27648
	ds_read_b128 v[112:115], v173 offset:28160
	v_mfma_f32_32x32x64_f8f6f4 v[16:31], v[96:103], v[148:155], v[16:31]
	v_exp_f32_e32 v64, v64
	v_exp_f32_e32 v65, v65
	v_exp_f32_e32 v66, v66
	v_exp_f32_e32 v67, v67
	v_exp_f32_e32 v68, v68
	v_exp_f32_e32 v69, v69
	ds_read_b128 v[148:151], v173 offset:29696
	ds_read_b128 v[152:155], v176 offset:28672
	ds_read_b128 v[156:159], v173 offset:30208
	v_mfma_f32_32x32x64_f8f6f4 v[32:47], v[96:103], v[214:221], v[32:47]
	v_exp_f32_e32 v70, v70
	v_exp_f32_e32 v71, v71
	v_exp_f32_e32 v72, v72
	v_exp_f32_e32 v73, v73
	v_exp_f32_e32 v74, v74
	v_exp_f32_e32 v75, v75
	ds_read_b128 v[214:217], v173 offset:33792
	ds_read_b128 v[218:221], v176 offset:31744
	ds_read_b128 v[222:225], v173 offset:34304
	v_mfma_f32_16x16x128_f8f6f4 v[144:147], v[232:239], v[96:103], 0
	v_exp_f32_e32 v76, v76
	v_exp_f32_e32 v77, v77
	v_exp_f32_e32 v78, v78
	v_exp_f32_e32 v79, v79
.Ljoin_b0:
	s_add_i32 s53, s53, 2
	v_mov_b32_e32 v179, v228

; #define SBAR() __builtin_amdgcn_sched_barrier(0)
; DEVINL void pv_psm(f32x16* o, const VFrag& f, const i32x8& pa, f32x16& lsum, const i32x8& ones8,
;                    f32x16& p0, f32x16& p1, float& m_reg, float& mn, float& alpha, int kvalid, int hi) {
;   constexpr float C = MLA_SCALE * 1.4426950408889634f;
;     ...
;   if (kvalid < 64) {
; #pragma unroll
;     for (int r = 0; r < 16; ++r) { if (crow(r, hi) >= kvalid) p0[r] = -1e30f; if (32 + crow(r, hi) >= kvalid) p1[r] = -1e30f; }
;   }
;   PVM(0);
;   float pmax = p0[0];
; #pragma unroll
;   for (int r = 1; r < 16; ++r) pmax = fmaxf(pmax, p0[r]);
;   SBAR();
;   PVM(1);
; #pragma unroll
;   for (int r = 0; r < 16; ++r) pmax = fmaxf(pmax, p1[r]);
;   { auto rr = __builtin_amdgcn_permlane32_swap(__float_as_uint(pmax), __float_as_uint(pmax), false, false);
;     pmax = fmaxf(__uint_as_float(rr[0]), __uint_as_float(rr[1])); }
;   SBAR();
;   PVM(2);
;   if (__builtin_expect(__all(pmax - m_reg <= THR / MLA_SCALE), 1)) { mn = m_reg; alpha = 1.f; }
;   else { mn = fmaxf(m_reg, pmax); alpha = __builtin_amdgcn_exp2f((m_reg - mn) * C); m_reg = mn; }
;   const float mnC = PSHIFT - mn * C;
;   const f32x2 C2 = {C, C}, M2 = {mnC, mnC};
; #pragma unroll
;   for (int r = 0; r < 16; r += 2) { f32x2 v = {p0[r], p0[r + 1]}; v = __builtin_elementwise_fma(v, C2, M2); p0[r] = v[0]; p0[r + 1] = v[1]; }
;   SBAR();
;   PVM(3);
; #pragma unroll
; DEVINL void mla_block(const Params& p, const bf16_t* __restrict__ Qn, const bf16_t* __restrict__ Qr, const char* __restrict__ K8, const char* __restrict__ Kp8,
;                       const char* __restrict__ V8, const bf16_t* __restrict__ Gb, bf16_t* __restrict__ Yb, char* lds, int pos0) {
;     ...
;   for (int j = 1; j + 1 < NT; j += 2) {
;     ISSUE_K(j + 2); ISSUE_K(j + 3); ISSUE_V(j + 1); ISSUE_V(j + 2); SBAR();
;     qkt<true>(pB0, pB1, KS(j), q8, r32, hi, pA1);
;     pv_load(vf, VS(j - 1), r32, hi); SBAR();
;     finishSM<true>(pA0, pA1, alA, l_reg, pa); SBAR();
;     pv_psm(o, vf, pa, lsum, ones8, pB0, pB1, m_reg, mnB, alB, 64, hi);
;     LUPD(alA); RESC(alB); SBAR();
;     qkt<true>(pA0, pA1, KS(j + 1), q8, r32, hi, pB1);
;     pv_load(vf, VS(j), r32, hi); SBAR();
;     finishSM<true>(pB0, pB1, alB, l_reg, pa); SBAR();
;     { const float alPrev = alB; pv_psm(o, vf, pa, lsum, ones8, pA0, pA1, m_reg, mnA, alA, L - (j + 1) * KVBLK, hi); LUPD(alPrev); }
;     TILE_SYNC(); RESC(alA);
.Lu1_dma_done:
	v_exp_f32_e32 v80, v80
	v_exp_f32_e32 v81, v81
	s_waitcnt lgkmcnt(6)
	v_mfma_scale_f32_32x32x64_f8f6f4 v[182:197], v[104:109], v[120:125], v[240:255], v162, v143 op_sel_hi:[0,0,0] cbsz:2 blgp:2
	v_exp_f32_e32 v82, v82
	v_exp_f32_e32 v83, v83
	v_exp_f32_e32 v84, v84
	v_exp_f32_e32 v85, v85
	v_mfma_scale_f32_32x32x64_f8f6f4 v[198:213], v[110:115], v[120:125], v[240:255], v162, v143 op_sel_hi:[0,0,0] cbsz:2 blgp:2
	ds_read_b128 v[104:107], v140 offset:20480
	ds_read_b128 v[108:111], v140 offset:20992
	ds_read_b128 v[112:115], v140 offset:22528
	ds_read_b128 v[116:119], v140 offset:23040
	v_exp_f32_e32 v86, v86
	s_waitcnt lgkmcnt(7)
	v_mfma_scale_f32_32x32x64_f8f6f4 v[182:197], v[148:153], v[126:131], v[182:197], v162, v143 op_sel_hi:[0,0,0] cbsz:2 blgp:2
	v_exp_f32_e32 v87, v87
	v_exp_f32_e32 v88, v88
	v_exp_f32_e32 v89, v89
	v_exp_f32_e32 v90, v90
	v_fma_f32 v180, v226, v180, v144
	v_mfma_scale_f32_32x32x64_f8f6f4 v[198:213], v[154:159], v[126:131], v[198:213], v162, v143 op_sel_hi:[0,0,0] cbsz:2 blgp:2
	ds_read_b128 v[148:151], v140 offset:24576
	ds_read_b128 v[152:155], v140 offset:25088
	v_exp_f32_e32 v91, v91
	v_exp_f32_e32 v92, v92
	s_waitcnt lgkmcnt(6)
	v_mfma_scale_f32_32x32x64_f8f6f4 v[182:197], v[214:219], v[132:137], v[182:197], v162, v143 op_sel_hi:[0,0,0] cbsz:2 blgp:2
	v_exp_f32_e32 v93, v93
	v_exp_f32_e32 v94, v94
	v_exp_f32_e32 v95, v95
	v_cvt_pk_fp8_f32 v96, v64, v65
	v_cvt_pk_fp8_f32 v97, v68, v69
	v_mfma_scale_f32_32x32x64_f8f6f4 v[198:213], v[220:225], v[132:137], v[198:213], v162, v143 op_sel_hi:[0,0,0] cbsz:2 blgp:2
	ds_read_b128 v[214:217], v140 offset:26624
	ds_read_b128 v[218:221], v140 offset:27136
	v_cvt_pk_fp8_f32 v98, v72, v73
	v_cvt_pk_fp8_f32 v99, v76, v77
	v_cvt_pk_fp8_f32 v96, v66, v67 op_sel:[0,0,1]
	v_cvt_pk_fp8_f32 v97, v70, v71 op_sel:[0,0,1]
	v_cvt_pk_fp8_f32 v98, v74, v75 op_sel:[0,0,1]
	v_cvt_pk_fp8_f32 v99, v78, v79 op_sel:[0,0,1]
	v_cvt_pk_fp8_f32 v100, v80, v81
	v_cvt_pk_fp8_f32 v101, v84, v85
	v_cvt_pk_fp8_f32 v102, v88, v89
	v_cvt_pk_fp8_f32 v103, v92, v93
	v_cvt_pk_fp8_f32 v100, v82, v83 op_sel:[0,0,1]
	v_cvt_pk_fp8_f32 v101, v86, v87 op_sel:[0,0,1]
	v_cvt_pk_fp8_f32 v102, v90, v91 op_sel:[0,0,1]
	v_cvt_pk_fp8_f32 v103, v94, v95 op_sel:[0,0,1]
	s_waitcnt lgkmcnt(2)
	s_nop 0
	v_mfma_f32_32x32x64_f8f6f4 v[0:15], v[96:103], v[104:111], v[0:15]
	v_max_f32_e32 v229, v182, v183
	v_max3_f32 v229, v229, v184, v185
	v_max3_f32 v229, v229, v186, v187
	v_max3_f32 v229, v229, v188, v189
	v_max3_f32 v229, v229, v190, v191
	v_max3_f32 v229, v229, v192, v193
	v_max3_f32 v229, v229, v194, v195
	v_max3_f32 v229, v229, v196, v197
	v_mfma_f32_32x32x64_f8f6f4 v[48:63], v[96:103], v[112:119], v[48:63]
	v_max3_f32 v229, v229, v198, v199
	v_max3_f32 v229, v229, v200, v201
	v_max3_f32 v229, v229, v202, v203
	v_max3_f32 v229, v229, v204, v205
	v_max3_f32 v229, v229, v206, v207
	v_max3_f32 v229, v229, v208, v209
	v_max3_f32 v229, v229, v210, v211
	v_max3_f32 v229, v229, v212, v213
	v_mov_b32_e32 v160, v229
	s_nop 1
	v_permlane32_swap_b32_e32 v229, v160
	v_max_f32_e32 v229, v229, v160
	v_cmp_ge_f32_e32 vcc, s69, v229
	s_cmp_eq_u64 vcc, exec
	v_mov_b32_e32 v226, 1.0
	s_cbranch_scc0 .Lslow_a1
	ds_read_b128 v[104:107], v173 offset:0
	ds_read_b128 v[108:111], v176 offset:0
	ds_read_b128 v[112:115], v173 offset:512
	v_mfma_f32_32x32x64_f8f6f4 v[16:31], v[96:103], v[148:155], v[16:31]
	v_exp_f32_e32 v182, v182
	v_exp_f32_e32 v183, v183
	v_exp_f32_e32 v184, v184
	v_exp_f32_e32 v185, v185
	v_exp_f32_e32 v186, v186
	v_exp_f32_e32 v187, v187
	ds_read_b128 v[148:151], v173 offset:2048
	ds_read_b128 v[152:155], v176 offset:1024
	ds_read_b128 v[156:159], v173 offset:2560
	s_waitcnt lgkmcnt(6)
	v_mfma_f32_32x32x64_f8f6f4 v[32:47], v[96:103], v[214:221], v[32:47]
	v_exp_f32_e32 v188, v188
	v_exp_f32_e32 v189, v189
	v_exp_f32_e32 v190, v190
	v_exp_f32_e32 v191, v191
	v_exp_f32_e32 v192, v192
	v_exp_f32_e32 v193, v193
	ds_read_b128 v[214:217], v173 offset:6144
	ds_read_b128 v[218:221], v176 offset:4096
	ds_read_b128 v[222:225], v173 offset:6656
	v_mfma_f32_16x16x128_f8f6f4 v[144:147], v[232:239], v[96:103], 0
	v_exp_f32_e32 v194, v194
	v_exp_f32_e32 v195, v195
	v_exp_f32_e32 v196, v196
	v_exp_f32_e32 v197, v197
.Ljoin_a1:
	v_exp_f32_e32 v198, v198
	v_exp_f32_e32 v199, v199
	s_waitcnt lgkmcnt(6)
	v_mfma_scale_f32_32x32x64_f8f6f4 v[64:79], v[104:109], v[120:125], v[240:255], v162, v143 op_sel_hi:[0,0,0] cbsz:2 blgp:2
	v_exp_f32_e32 v200, v200
	v_exp_f32_e32 v201, v201
	v_exp_f32_e32 v202, v202
	v_exp_f32_e32 v203, v203
	v_mfma_scale_f32_32x32x64_f8f6f4 v[80:95], v[110:115], v[120:125], v[240:255], v162, v143 op_sel_hi:[0,0,0] cbsz:2 blgp:2
	ds_read_b128 v[104:107], v140 offset:28672
	ds_read_b128 v[108:111], v140 offset:29184
	ds_read_b128 v[112:115], v140 offset:30720
	ds_read_b128 v[116:119], v140 offset:31232
	v_exp_f32_e32 v204, v204
	s_waitcnt lgkmcnt(7)
	v_mfma_scale_f32_32x32x64_f8f6f4 v[64:79], v[148:153], v[126:131], v[64:79], v162, v143 op_sel_hi:[0,0,0] cbsz:2 blgp:2
	v_exp_f32_e32 v205, v205
	v_exp_f32_e32 v206, v206
	v_exp_f32_e32 v207, v207
	v_exp_f32_e32 v208, v208
	v_fma_f32 v180, v179, v180, v144
	v_mfma_scale_f32_32x32x64_f8f6f4 v[80:95], v[154:159], v[126:131], v[80:95], v162, v143 op_sel_hi:[0,0,0] cbsz:2 blgp:2
	ds_read_b128 v[148:151], v140 offset:32768
	ds_read_b128 v[152:155], v140 offset:33280
	v_exp_f32_e32 v209, v209
	v_exp_f32_e32 v210, v210
	s_waitcnt lgkmcnt(6)
	v_mfma_scale_f32_32x32x64_f8f6f4 v[64:79], v[214:219], v[132:137], v[64:79], v162, v143 op_sel_hi:[0,0,0] cbsz:2 blgp:2
	v_exp_f32_e32 v211, v211
	v_exp_f32_e32 v212, v212
	v_exp_f32_e32 v213, v213
	v_cvt_pk_fp8_f32 v96, v182, v183
	v_cvt_pk_fp8_f32 v97, v186, v187
	v_mfma_scale_f32_32x32x64_f8f6f4 v[80:95], v[220:225], v[132:137], v[80:95], v162, v143 op_sel_hi:[0,0,0] cbsz:2 blgp:2
	ds_read_b128 v[214:217], v140 offset:34816
	ds_read_b128 v[218:221], v140 offset:35328
	v_cvt_pk_fp8_f32 v98, v190, v191
	v_cvt_pk_fp8_f32 v99, v194, v195
	v_cvt_pk_fp8_f32 v96, v184, v185 op_sel:[0,0,1]
	v_cvt_pk_fp8_f32 v97, v188, v189 op_sel:[0,0,1]
	v_cvt_pk_fp8_f32 v98, v192, v193 op_sel:[0,0,1]
	v_cvt_pk_fp8_f32 v99, v196, v197 op_sel:[0,0,1]
	v_cvt_pk_fp8_f32 v100, v198, v199
	v_cvt_pk_fp8_f32 v101, v202, v203
	v_cvt_pk_fp8_f32 v102, v206, v207
	v_cvt_pk_fp8_f32 v103, v210, v211
	v_cvt_pk_fp8_f32 v100, v200, v201 op_sel:[0,0,1]
	v_cvt_pk_fp8_f32 v101, v204, v205 op_sel:[0,0,1]
	v_cvt_pk_fp8_f32 v102, v208, v209 op_sel:[0,0,1]
	v_cvt_pk_fp8_f32 v103, v212, v213 op_sel:[0,0,1]
	s_waitcnt lgkmcnt(2)
	s_nop 0
	v_mfma_f32_32x32x64_f8f6f4 v[0:15], v[96:103], v[104:111], v[0:15]
	s_cmpk_gt_u32 s53, 0x101
	s_cbranch_scc1 .Lmask_last
; #define SBAR() __builtin_amdgcn_sched_barrier(0)
; #define TILE_SYNC() do { asm volatile("s_waitcnt vmcnt(0)" ::: "memory"); __syncthreads(); } while (0)
; #define RESC(a) do { if (__any((a) < 1.f)) { if (hi == 0) al_l[r32] = (a); asm volatile("s_waitcnt lgkmcnt(0)" ::: "memory"); \
;     for (int d = 0; d < 4; ++d) for (int r = 0; r < 16; ++r) o[d][r] *= al_l[crow(r, hi)]; } } while (0)
; #define LUPD(al) do { l_reg = l_reg * (al) + lsum[0]; } while (0)
; DEVINL void mla_block(const Params& p, const bf16_t* __restrict__ Qn, const bf16_t* __restrict__ Qr, const char* __restrict__ K8, const char* __restrict__ Kp8,
;                       const char* __restrict__ V8, const bf16_t* __restrict__ Gb, bf16_t* __restrict__ Yb, char* lds, int pos0) {
;     ...
;     qkt<true>(pA0, pA1, KS(j + 1), q8, r32, hi, pB1);
;     pv_load(vf, VS(j), r32, hi); SBAR();
;     finishSM<true>(pB0, pB1, alB, l_reg, pa); SBAR();
;     { const float alPrev = alB; pv_psm(o, vf, pa, lsum, ones8, pA0, pA1, m_reg, mnA, alA, L - (j + 1) * KVBLK, hi); LUPD(alPrev); }
;     TILE_SYNC(); RESC(alA);
;   }
	.Lmask_ret:
	v_max_f32_e32 v229, v64, v65
	v_max3_f32 v229, v229, v66, v67
	v_max3_f32 v229, v229, v68, v69
	v_max3_f32 v229, v229, v70, v71
	v_max3_f32 v229, v229, v72, v73
	v_max3_f32 v229, v229, v74, v75
	v_max3_f32 v229, v229, v76, v77
	v_max3_f32 v229, v229, v78, v79
	v_mfma_f32_32x32x64_f8f6f4 v[48:63], v[96:103], v[112:119], v[48:63]
	v_max3_f32 v229, v229, v80, v81
	v_max3_f32 v229, v229, v82, v83
	v_max3_f32 v229, v229, v84, v85
	v_max3_f32 v229, v229, v86, v87
	v_max3_f32 v229, v229, v88, v89
	v_max3_f32 v229, v229, v90, v91
	v_max3_f32 v229, v229, v92, v93
	v_max3_f32 v229, v229, v94, v95
	v_mov_b32_e32 v160, v229
	s_nop 1
	v_permlane32_swap_b32_e32 v229, v160
	v_max_f32_e32 v229, v229, v160
	v_cmp_ge_f32_e32 vcc, s69, v229
	s_cmp_eq_u64 vcc, exec
	v_mov_b32_e32 v228, 1.0
	s_cbranch_scc0 .Lslow_b1
	s_waitcnt vmcnt(0) lgkmcnt(0)
	s_barrier
	ds_read_b128 v[104:107], v173 offset:9216
	ds_read_b128 v[108:111], v176 offset:9216
	ds_read_b128 v[112:115], v173 offset:9728
	v_mfma_f32_32x32x64_f8f6f4 v[16:31], v[96:103], v[148:155], v[16:31]
	v_exp_f32_e32 v64, v64
	v_exp_f32_e32 v65, v65
	v_exp_f32_e32 v66, v66
	v_exp_f32_e32 v67, v67
	v_exp_f32_e32 v68, v68
	v_exp_f32_e32 v69, v69
	ds_read_b128 v[148:151], v173 offset:11264
	ds_read_b128 v[152:155], v176 offset:10240
	ds_read_b128 v[156:159], v173 offset:11776
	v_mfma_f32_32x32x64_f8f6f4 v[32:47], v[96:103], v[214:221], v[32:47]
	v_exp_f32_e32 v70, v70
	v_exp_f32_e32 v71, v71
	v_exp_f32_e32 v72, v72
	v_exp_f32_e32 v73, v73
	v_exp_f32_e32 v74, v74
	v_exp_f32_e32 v75, v75
	ds_read_b128 v[214:217], v173 offset:15360
	ds_read_b128 v[218:221], v176 offset:13312
	ds_read_b128 v[222:225], v173 offset:15872
	v_mfma_f32_16x16x128_f8f6f4 v[144:147], v[232:239], v[96:103], 0
	v_exp_f32_e32 v76, v76
	v_exp_f32_e32 v77, v77
	v_exp_f32_e32 v78, v78
	v_exp_f32_e32 v79, v79
.Ljoin_b1:
	s_add_i32 s53, s53, 2
	s_cmpk_gt_u32 s53, 0x102
	s_cbranch_scc1 .Lexit_glue
	v_mov_b32_e32 v179, v228
	s_branch .LBB0_560
.Lslow_a0:
	v_mfma_f32_32x32x64_f8f6f4 v[16:31], v[96:103], v[148:155], v[16:31]
	s_waitcnt lgkmcnt(0)
	v_mfma_f32_32x32x64_f8f6f4 v[32:47], v[96:103], v[214:221], v[32:47]
	v_mfma_f32_16x16x128_f8f6f4 v[144:147], v[232:239], v[96:103], 0
	v_sub_f32_e32 v141, v229, v164
	v_max_f32_e32 v141, 0, v141
	v_exp_f32_e64 v226, -v141
	v_sub_f32_e32 v230, v230, v141
	v_mov_b32_e32 v240, v230
	v_mov_b32_e32 v241, v230
	v_mov_b32_e32 v242, v230
	v_mov_b32_e32 v243, v230
	v_mov_b32_e32 v244, v230
	v_mov_b32_e32 v245, v230
	v_mov_b32_e32 v246, v230
	v_mov_b32_e32 v247, v230
	v_mov_b32_e32 v248, v230
	v_mov_b32_e32 v249, v230
	v_mov_b32_e32 v250, v230
	v_mov_b32_e32 v251, v230
	v_mov_b32_e32 v252, v230
	v_mov_b32_e32 v253, v230
	v_mov_b32_e32 v254, v230
	v_mov_b32_e32 v255, v230
	v_sub_f32_e32 v182, v182, v141
	v_sub_f32_e32 v183, v183, v141
	v_sub_f32_e32 v184, v184, v141
	v_sub_f32_e32 v185, v185, v141
	v_sub_f32_e32 v186, v186, v141
	v_sub_f32_e32 v187, v187, v141
	v_sub_f32_e32 v188, v188, v141
	v_sub_f32_e32 v189, v189, v141
	v_sub_f32_e32 v190, v190, v141
	v_sub_f32_e32 v191, v191, v141
	v_sub_f32_e32 v192, v192, v141
	v_sub_f32_e32 v193, v193, v141
	v_sub_f32_e32 v194, v194, v141
	v_sub_f32_e32 v195, v195, v141
	v_sub_f32_e32 v196, v196, v141
	v_sub_f32_e32 v197, v197, v141
	v_sub_f32_e32 v198, v198, v141
	v_sub_f32_e32 v199, v199, v141
	v_sub_f32_e32 v200, v200, v141
	v_sub_f32_e32 v201, v201, v141
	v_sub_f32_e32 v202, v202, v141
	v_sub_f32_e32 v203, v203, v141
	v_sub_f32_e32 v204, v204, v141
	v_sub_f32_e32 v205, v205, v141
	v_sub_f32_e32 v206, v206, v141
	v_sub_f32_e32 v207, v207, v141
	v_sub_f32_e32 v208, v208, v141
	v_sub_f32_e32 v209, v209, v141
	v_sub_f32_e32 v210, v210, v141
	v_sub_f32_e32 v211, v211, v141
	v_sub_f32_e32 v212, v212, v141
	v_sub_f32_e32 v213, v213, v141
	s_and_saveexec_b64 s[16:17], s[6:7]
	ds_write_b32 v178, v226 offset:128
	s_or_b64 exec, exec, s[16:17]
	s_waitcnt lgkmcnt(0)
	v_add_u32_e32 v142, v171, v177
	ds_read_b128 v[104:107], v142 offset:224
	ds_read_b128 v[108:111], v142 offset:192
	ds_read_b128 v[112:115], v142 offset:160
	ds_read_b128 v[116:119], v142 offset:128
	s_waitcnt lgkmcnt(0)
	v_pk_mul_f32 v[12:13], v[12:13], v[104:105]
	v_pk_mul_f32 v[8:9], v[8:9], v[108:109]
	v_pk_mul_f32 v[4:5], v[4:5], v[112:113]
	v_pk_mul_f32 v[14:15], v[14:15], v[106:107]
	v_pk_mul_f32 v[10:11], v[10:11], v[110:111]
	v_pk_mul_f32 v[6:7], v[6:7], v[114:115]
	v_pk_mul_f32 v[2:3], v[2:3], v[118:119]
	v_pk_mul_f32 v[0:1], v[0:1], v[116:117]
	v_pk_mul_f32 v[60:61], v[60:61], v[104:105]
	v_pk_mul_f32 v[56:57], v[56:57], v[108:109]
	v_pk_mul_f32 v[52:53], v[52:53], v[112:113]
	v_pk_mul_f32 v[62:63], v[62:63], v[106:107]
	v_pk_mul_f32 v[58:59], v[58:59], v[110:111]
	v_pk_mul_f32 v[54:55], v[54:55], v[114:115]
	v_pk_mul_f32 v[50:51], v[50:51], v[118:119]
	v_pk_mul_f32 v[48:49], v[48:49], v[116:117]
	v_pk_mul_f32 v[28:29], v[28:29], v[104:105]
	v_pk_mul_f32 v[24:25], v[24:25], v[108:109]
	v_pk_mul_f32 v[20:21], v[20:21], v[112:113]
	v_pk_mul_f32 v[30:31], v[30:31], v[106:107]
	v_pk_mul_f32 v[26:27], v[26:27], v[110:111]
	v_pk_mul_f32 v[22:23], v[22:23], v[114:115]
	v_pk_mul_f32 v[18:19], v[18:19], v[118:119]
	v_pk_mul_f32 v[16:17], v[16:17], v[116:117]
	v_pk_mul_f32 v[44:45], v[44:45], v[104:105]
	v_pk_mul_f32 v[40:41], v[40:41], v[108:109]
	v_pk_mul_f32 v[36:37], v[36:37], v[112:113]
	v_pk_mul_f32 v[46:47], v[46:47], v[106:107]
	v_pk_mul_f32 v[42:43], v[42:43], v[110:111]
	v_pk_mul_f32 v[38:39], v[38:39], v[114:115]
	v_pk_mul_f32 v[34:35], v[34:35], v[118:119]
	v_pk_mul_f32 v[32:33], v[32:33], v[116:117]
	ds_read_b128 v[104:107], v173 offset:18432
	ds_read_b128 v[108:111], v176 offset:18432
	ds_read_b128 v[112:115], v173 offset:18944
	ds_read_b128 v[148:151], v173 offset:20480
	ds_read_b128 v[152:155], v176 offset:19456
	ds_read_b128 v[156:159], v173 offset:20992
	ds_read_b128 v[214:217], v173 offset:24576
	ds_read_b128 v[218:221], v176 offset:22528
	ds_read_b128 v[222:225], v173 offset:25088
	v_exp_f32_e32 v182, v182
	v_exp_f32_e32 v183, v183
	v_exp_f32_e32 v184, v184
	v_exp_f32_e32 v185, v185
	v_exp_f32_e32 v186, v186
	v_exp_f32_e32 v187, v187
	v_exp_f32_e32 v188, v188
	v_exp_f32_e32 v189, v189
	v_exp_f32_e32 v190, v190
	v_exp_f32_e32 v191, v191
	v_exp_f32_e32 v192, v192
	v_exp_f32_e32 v193, v193
	v_exp_f32_e32 v194, v194
	v_exp_f32_e32 v195, v195
	v_exp_f32_e32 v196, v196
	v_exp_f32_e32 v197, v197
	s_branch .Ljoin_a0
; #define SBAR() __builtin_amdgcn_sched_barrier(0)
; #define TILE_SYNC() do { asm volatile("s_waitcnt vmcnt(0)" ::: "memory"); __syncthreads(); } while (0)
; #define RESC(a) do { if (__any((a) < 1.f)) { if (hi == 0) al_l[r32] = (a); asm volatile("s_waitcnt lgkmcnt(0)" ::: "memory"); \
;     for (int d = 0; d < 4; ++d) for (int r = 0; r < 16; ++r) o[d][r] *= al_l[crow(r, hi)]; } } while (0)
; #define LUPD(al) do { l_reg = l_reg * (al) + lsum[0]; } while (0)
; DEVINL void mla_block(const Params& p, const bf16_t* __restrict__ Qn, const bf16_t* __restrict__ Qr, const char* __restrict__ K8, const char* __restrict__ Kp8,
;                       const char* __restrict__ V8, const bf16_t* __restrict__ Gb, bf16_t* __restrict__ Yb, char* lds, int pos0) {
;     ...
;     qkt<true>(pA0, pA1, KS(j + 1), q8, r32, hi, pB1);
;     pv_load(vf, VS(j), r32, hi); SBAR();
;     finishSM<true>(pB0, pB1, alB, l_reg, pa); SBAR();
;     { const float alPrev = alB; pv_psm(o, vf, pa, lsum, ones8, pA0, pA1, m_reg, mnA, alA, L - (j + 1) * KVBLK, hi); LUPD(alPrev); }
;     TILE_SYNC(); RESC(alA);
.Lslow_b0:
	v_mfma_f32_32x32x64_f8f6f4 v[16:31], v[96:103], v[148:155], v[16:31]
	s_waitcnt lgkmcnt(0)
	v_mfma_f32_32x32x64_f8f6f4 v[32:47], v[96:103], v[214:221], v[32:47]
	v_mfma_f32_16x16x128_f8f6f4 v[144:147], v[232:239], v[96:103], 0
	s_waitcnt vmcnt(0)
	s_barrier
	v_sub_f32_e32 v141, v229, v164
	v_max_f32_e32 v141, 0, v141
	v_exp_f32_e64 v228, -v141
	v_sub_f32_e32 v230, v230, v141
	v_mov_b32_e32 v240, v230
	v_mov_b32_e32 v241, v230
	v_mov_b32_e32 v242, v230
	v_mov_b32_e32 v243, v230
	v_mov_b32_e32 v244, v230
	v_mov_b32_e32 v245, v230
	v_mov_b32_e32 v246, v230
	v_mov_b32_e32 v247, v230
	v_mov_b32_e32 v248, v230
	v_mov_b32_e32 v249, v230
	v_mov_b32_e32 v250, v230
	v_mov_b32_e32 v251, v230
	v_mov_b32_e32 v252, v230
	v_mov_b32_e32 v253, v230
	v_mov_b32_e32 v254, v230
	v_mov_b32_e32 v255, v230
	v_sub_f32_e32 v64, v64, v141
	v_sub_f32_e32 v65, v65, v141
	v_sub_f32_e32 v66, v66, v141
	v_sub_f32_e32 v67, v67, v141
	v_sub_f32_e32 v68, v68, v141
	v_sub_f32_e32 v69, v69, v141
	v_sub_f32_e32 v70, v70, v141
	v_sub_f32_e32 v71, v71, v141
	v_sub_f32_e32 v72, v72, v141
	v_sub_f32_e32 v73, v73, v141
	v_sub_f32_e32 v74, v74, v141
	v_sub_f32_e32 v75, v75, v141
	v_sub_f32_e32 v76, v76, v141
	v_sub_f32_e32 v77, v77, v141
	v_sub_f32_e32 v78, v78, v141
	v_sub_f32_e32 v79, v79, v141
	v_sub_f32_e32 v80, v80, v141
	v_sub_f32_e32 v81, v81, v141
	v_sub_f32_e32 v82, v82, v141
	v_sub_f32_e32 v83, v83, v141
	v_sub_f32_e32 v84, v84, v141
	v_sub_f32_e32 v85, v85, v141
	v_sub_f32_e32 v86, v86, v141
	v_sub_f32_e32 v87, v87, v141
	v_sub_f32_e32 v88, v88, v141
	v_sub_f32_e32 v89, v89, v141
	v_sub_f32_e32 v90, v90, v141
	v_sub_f32_e32 v91, v91, v141
	v_sub_f32_e32 v92, v92, v141
	v_sub_f32_e32 v93, v93, v141
	v_sub_f32_e32 v94, v94, v141
	v_sub_f32_e32 v95, v95, v141
	s_and_saveexec_b64 s[16:17], s[6:7]
	ds_write_b32 v178, v228 offset:128
	s_or_b64 exec, exec, s[16:17]
	s_waitcnt lgkmcnt(0)
	v_add_u32_e32 v142, v171, v177
	ds_read_b128 v[104:107], v142 offset:224
	ds_read_b128 v[108:111], v142 offset:192
	ds_read_b128 v[112:115], v142 offset:160
	ds_read_b128 v[116:119], v142 offset:128
	s_waitcnt lgkmcnt(0)
	v_pk_mul_f32 v[12:13], v[12:13], v[104:105]
	v_pk_mul_f32 v[8:9], v[8:9], v[108:109]
	v_pk_mul_f32 v[4:5], v[4:5], v[112:113]
	v_pk_mul_f32 v[14:15], v[14:15], v[106:107]
	v_pk_mul_f32 v[10:11], v[10:11], v[110:111]
	v_pk_mul_f32 v[6:7], v[6:7], v[114:115]
	v_pk_mul_f32 v[2:3], v[2:3], v[118:119]
	v_pk_mul_f32 v[0:1], v[0:1], v[116:117]
	v_pk_mul_f32 v[60:61], v[60:61], v[104:105]
	v_pk_mul_f32 v[56:57], v[56:57], v[108:109]
	v_pk_mul_f32 v[52:53], v[52:53], v[112:113]
	v_pk_mul_f32 v[62:63], v[62:63], v[106:107]
	v_pk_mul_f32 v[58:59], v[58:59], v[110:111]
	v_pk_mul_f32 v[54:55], v[54:55], v[114:115]
	v_pk_mul_f32 v[50:51], v[50:51], v[118:119]
	v_pk_mul_f32 v[48:49], v[48:49], v[116:117]
	v_pk_mul_f32 v[28:29], v[28:29], v[104:105]
	v_pk_mul_f32 v[24:25], v[24:25], v[108:109]
	v_pk_mul_f32 v[20:21], v[20:21], v[112:113]
	v_pk_mul_f32 v[30:31], v[30:31], v[106:107]
	v_pk_mul_f32 v[26:27], v[26:27], v[110:111]
	v_pk_mul_f32 v[22:23], v[22:23], v[114:115]
	v_pk_mul_f32 v[18:19], v[18:19], v[118:119]
	v_pk_mul_f32 v[16:17], v[16:17], v[116:117]
	v_pk_mul_f32 v[44:45], v[44:45], v[104:105]
	v_pk_mul_f32 v[40:41], v[40:41], v[108:109]
	v_pk_mul_f32 v[36:37], v[36:37], v[112:113]
	v_pk_mul_f32 v[46:47], v[46:47], v[106:107]
	v_pk_mul_f32 v[42:43], v[42:43], v[110:111]
	v_pk_mul_f32 v[38:39], v[38:39], v[114:115]
	v_pk_mul_f32 v[34:35], v[34:35], v[118:119]
	v_pk_mul_f32 v[32:33], v[32:33], v[116:117]
	ds_read_b128 v[104:107], v173 offset:27648
	ds_read_b128 v[108:111], v176 offset:27648
	ds_read_b128 v[112:115], v173 offset:28160
	ds_read_b128 v[148:151], v173 offset:29696
	ds_read_b128 v[152:155], v176 offset:28672
	ds_read_b128 v[156:159], v173 offset:30208
	ds_read_b128 v[214:217], v173 offset:33792
	ds_read_b128 v[218:221], v176 offset:31744
	ds_read_b128 v[222:225], v173 offset:34304
	v_exp_f32_e32 v64, v64
	v_exp_f32_e32 v65, v65
	v_exp_f32_e32 v66, v66
	v_exp_f32_e32 v67, v67
	v_exp_f32_e32 v68, v68
	v_exp_f32_e32 v69, v69
	v_exp_f32_e32 v70, v70
	v_exp_f32_e32 v71, v71
	v_exp_f32_e32 v72, v72
	v_exp_f32_e32 v73, v73
	v_exp_f32_e32 v74, v74
	v_exp_f32_e32 v75, v75
	v_exp_f32_e32 v76, v76
	v_exp_f32_e32 v77, v77
	v_exp_f32_e32 v78, v78
	v_exp_f32_e32 v79, v79
	s_branch .Ljoin_b0
; #define SBAR() __builtin_amdgcn_sched_barrier(0)
; #define ISSUE_K(j) do { const int _t = (j) < NT ? (j) : NT - 1; char* _d = K_lds + ((j) & 3) * SHM_K8; if (wid < 6) GLDS(K8 + (size_t)_t * 6144 + t16u, _d + tid16); \
;     if (wid < 3) GLDS(Kp8 + (size_t)_t * 3072 + t16u, _d + 6144 + tid16); } while (0)
; #define ISSUE_V(j) do { const int _t = (j) < NT ? (j) : NT - 1; GLDS(V8 + (size_t)_t * 8192 + t16u, V_lds + ((j) & 3) * SHM_V8 + tid16); } while (0)
; #define RESC(a) do { if (__any((a) < 1.f)) { if (hi == 0) al_l[r32] = (a); asm volatile("s_waitcnt lgkmcnt(0)" ::: "memory"); \
;     for (int d = 0; d < 4; ++d) for (int r = 0; r < 16; ++r) o[d][r] *= al_l[crow(r, hi)]; } } while (0)
; #define LUPD(al) do { l_reg = l_reg * (al) + lsum[0]; } while (0)
; DEVINL void mla_block(const Params& p, const bf16_t* __restrict__ Qn, const bf16_t* __restrict__ Qr, const char* __restrict__ K8, const char* __restrict__ Kp8,
;                       const char* __restrict__ V8, const bf16_t* __restrict__ Gb, bf16_t* __restrict__ Yb, char* lds, int pos0) {
;     ...
;     ISSUE_K(j + 2); ISSUE_K(j + 3); ISSUE_V(j + 1); ISSUE_V(j + 2); SBAR();
;     qkt<true>(pB0, pB1, KS(j), q8, r32, hi, pA1);
;     pv_load(vf, VS(j - 1), r32, hi); SBAR();
;     finishSM<true>(pA0, pA1, alA, l_reg, pa); SBAR();
;     pv_psm(o, vf, pa, lsum, ones8, pB0, pB1, m_reg, mnB, alB, 64, hi);
;     LUPD(alA); RESC(alB); SBAR();
.Lslow_a1:
	v_mfma_f32_32x32x64_f8f6f4 v[16:31], v[96:103], v[148:155], v[16:31]
	s_waitcnt lgkmcnt(0)
	v_mfma_f32_32x32x64_f8f6f4 v[32:47], v[96:103], v[214:221], v[32:47]
	v_mfma_f32_16x16x128_f8f6f4 v[144:147], v[232:239], v[96:103], 0
	v_sub_f32_e32 v141, v229, v164
	v_max_f32_e32 v141, 0, v141
	v_exp_f32_e64 v226, -v141
	v_sub_f32_e32 v230, v230, v141
	v_mov_b32_e32 v240, v230
	v_mov_b32_e32 v241, v230
	v_mov_b32_e32 v242, v230
	v_mov_b32_e32 v243, v230
	v_mov_b32_e32 v244, v230
	v_mov_b32_e32 v245, v230
	v_mov_b32_e32 v246, v230
	v_mov_b32_e32 v247, v230
	v_mov_b32_e32 v248, v230
	v_mov_b32_e32 v249, v230
	v_mov_b32_e32 v250, v230
	v_mov_b32_e32 v251, v230
	v_mov_b32_e32 v252, v230
	v_mov_b32_e32 v253, v230
	v_mov_b32_e32 v254, v230
	v_mov_b32_e32 v255, v230
	v_sub_f32_e32 v182, v182, v141
	v_sub_f32_e32 v183, v183, v141
	v_sub_f32_e32 v184, v184, v141
	v_sub_f32_e32 v185, v185, v141
	v_sub_f32_e32 v186, v186, v141
	v_sub_f32_e32 v187, v187, v141
	v_sub_f32_e32 v188, v188, v141
	v_sub_f32_e32 v189, v189, v141
	v_sub_f32_e32 v190, v190, v141
	v_sub_f32_e32 v191, v191, v141
	v_sub_f32_e32 v192, v192, v141
	v_sub_f32_e32 v193, v193, v141
	v_sub_f32_e32 v194, v194, v141
	v_sub_f32_e32 v195, v195, v141
	v_sub_f32_e32 v196, v196, v141
	v_sub_f32_e32 v197, v197, v141
	v_sub_f32_e32 v198, v198, v141
	v_sub_f32_e32 v199, v199, v141
	v_sub_f32_e32 v200, v200, v141
	v_sub_f32_e32 v201, v201, v141
	v_sub_f32_e32 v202, v202, v141
	v_sub_f32_e32 v203, v203, v141
	v_sub_f32_e32 v204, v204, v141
	v_sub_f32_e32 v205, v205, v141
	v_sub_f32_e32 v206, v206, v141
	v_sub_f32_e32 v207, v207, v141
	v_sub_f32_e32 v208, v208, v141
	v_sub_f32_e32 v209, v209, v141
	v_sub_f32_e32 v210, v210, v141
	v_sub_f32_e32 v211, v211, v141
	v_sub_f32_e32 v212, v212, v141
	v_sub_f32_e32 v213, v213, v141
	s_and_saveexec_b64 s[16:17], s[6:7]
	ds_write_b32 v178, v226 offset:128
	s_or_b64 exec, exec, s[16:17]
	s_waitcnt lgkmcnt(0)
	v_add_u32_e32 v142, v171, v177
	ds_read_b128 v[104:107], v142 offset:224
	ds_read_b128 v[108:111], v142 offset:192
	ds_read_b128 v[112:115], v142 offset:160
	ds_read_b128 v[116:119], v142 offset:128
	s_waitcnt lgkmcnt(0)
	v_pk_mul_f32 v[12:13], v[12:13], v[104:105]
	v_pk_mul_f32 v[8:9], v[8:9], v[108:109]
	v_pk_mul_f32 v[4:5], v[4:5], v[112:113]
	v_pk_mul_f32 v[14:15], v[14:15], v[106:107]
	v_pk_mul_f32 v[10:11], v[10:11], v[110:111]
	v_pk_mul_f32 v[6:7], v[6:7], v[114:115]
	v_pk_mul_f32 v[2:3], v[2:3], v[118:119]
	v_pk_mul_f32 v[0:1], v[0:1], v[116:117]
	v_pk_mul_f32 v[60:61], v[60:61], v[104:105]
	v_pk_mul_f32 v[56:57], v[56:57], v[108:109]
	v_pk_mul_f32 v[52:53], v[52:53], v[112:113]
	v_pk_mul_f32 v[62:63], v[62:63], v[106:107]
	v_pk_mul_f32 v[58:59], v[58:59], v[110:111]
	v_pk_mul_f32 v[54:55], v[54:55], v[114:115]
	v_pk_mul_f32 v[50:51], v[50:51], v[118:119]
	v_pk_mul_f32 v[48:49], v[48:49], v[116:117]
	v_pk_mul_f32 v[28:29], v[28:29], v[104:105]
	v_pk_mul_f32 v[24:25], v[24:25], v[108:109]
	v_pk_mul_f32 v[20:21], v[20:21], v[112:113]
	v_pk_mul_f32 v[30:31], v[30:31], v[106:107]
	v_pk_mul_f32 v[26:27], v[26:27], v[110:111]
	v_pk_mul_f32 v[22:23], v[22:23], v[114:115]
	v_pk_mul_f32 v[18:19], v[18:19], v[118:119]
	v_pk_mul_f32 v[16:17], v[16:17], v[116:117]
	v_pk_mul_f32 v[44:45], v[44:45], v[104:105]
	v_pk_mul_f32 v[40:41], v[40:41], v[108:109]
	v_pk_mul_f32 v[36:37], v[36:37], v[112:113]
	v_pk_mul_f32 v[46:47], v[46:47], v[106:107]
	v_pk_mul_f32 v[42:43], v[42:43], v[110:111]
	v_pk_mul_f32 v[38:39], v[38:39], v[114:115]
	v_pk_mul_f32 v[34:35], v[34:35], v[118:119]
	v_pk_mul_f32 v[32:33], v[32:33], v[116:117]
	ds_read_b128 v[104:107], v173 offset:0
	ds_read_b128 v[108:111], v176 offset:0
	ds_read_b128 v[112:115], v173 offset:512
	ds_read_b128 v[148:151], v173 offset:2048
	ds_read_b128 v[152:155], v176 offset:1024
	ds_read_b128 v[156:159], v173 offset:2560
	ds_read_b128 v[214:217], v173 offset:6144
	ds_read_b128 v[218:221], v176 offset:4096
	ds_read_b128 v[222:225], v173 offset:6656
	v_exp_f32_e32 v182, v182
	v_exp_f32_e32 v183, v183
	v_exp_f32_e32 v184, v184
	v_exp_f32_e32 v185, v185
	v_exp_f32_e32 v186, v186
	v_exp_f32_e32 v187, v187
	v_exp_f32_e32 v188, v188
	v_exp_f32_e32 v189, v189
	v_exp_f32_e32 v190, v190
	v_exp_f32_e32 v191, v191
	v_exp_f32_e32 v192, v192
	v_exp_f32_e32 v193, v193
	v_exp_f32_e32 v194, v194
	v_exp_f32_e32 v195, v195
	v_exp_f32_e32 v196, v196
	v_exp_f32_e32 v197, v197
	s_branch .Ljoin_a1
; #define SBAR() __builtin_amdgcn_sched_barrier(0)
; #define TILE_SYNC() do { asm volatile("s_waitcnt vmcnt(0)" ::: "memory"); __syncthreads(); } while (0)
; #define RESC(a) do { if (__any((a) < 1.f)) { if (hi == 0) al_l[r32] = (a); asm volatile("s_waitcnt lgkmcnt(0)" ::: "memory"); \
;     for (int d = 0; d < 4; ++d) for (int r = 0; r < 16; ++r) o[d][r] *= al_l[crow(r, hi)]; } } while (0)
; #define LUPD(al) do { l_reg = l_reg * (al) + lsum[0]; } while (0)
; DEVINL void mla_block(const Params& p, const bf16_t* __restrict__ Qn, const bf16_t* __restrict__ Qr, const char* __restrict__ K8, const char* __restrict__ Kp8,
;                       const char* __restrict__ V8, const bf16_t* __restrict__ Gb, bf16_t* __restrict__ Yb, char* lds, int pos0) {
;     ...
;     qkt<true>(pA0, pA1, KS(j + 1), q8, r32, hi, pB1);
;     pv_load(vf, VS(j), r32, hi); SBAR();
;     finishSM<true>(pB0, pB1, alB, l_reg, pa); SBAR();
;     { const float alPrev = alB; pv_psm(o, vf, pa, lsum, ones8, pA0, pA1, m_reg, mnA, alA, L - (j + 1) * KVBLK, hi); LUPD(alPrev); }
;     TILE_SYNC(); RESC(alA);
.Lslow_b1:
	v_mfma_f32_32x32x64_f8f6f4 v[16:31], v[96:103], v[148:155], v[16:31]
	s_waitcnt lgkmcnt(0)
	v_mfma_f32_32x32x64_f8f6f4 v[32:47], v[96:103], v[214:221], v[32:47]
	v_mfma_f32_16x16x128_f8f6f4 v[144:147], v[232:239], v[96:103], 0
	s_waitcnt vmcnt(0)
	s_barrier
	v_sub_f32_e32 v141, v229, v164
	v_max_f32_e32 v141, 0, v141
	v_exp_f32_e64 v228, -v141
	v_sub_f32_e32 v230, v230, v141
	v_mov_b32_e32 v240, v230
	v_mov_b32_e32 v241, v230
	v_mov_b32_e32 v242, v230
	v_mov_b32_e32 v243, v230
	v_mov_b32_e32 v244, v230
	v_mov_b32_e32 v245, v230
	v_mov_b32_e32 v246, v230
	v_mov_b32_e32 v247, v230
	v_mov_b32_e32 v248, v230
	v_mov_b32_e32 v249, v230
	v_mov_b32_e32 v250, v230
	v_mov_b32_e32 v251, v230
	v_mov_b32_e32 v252, v230
	v_mov_b32_e32 v253, v230
	v_mov_b32_e32 v254, v230
	v_mov_b32_e32 v255, v230
	v_sub_f32_e32 v64, v64, v141
	v_sub_f32_e32 v65, v65, v141
	v_sub_f32_e32 v66, v66, v141
	v_sub_f32_e32 v67, v67, v141
	v_sub_f32_e32 v68, v68, v141
	v_sub_f32_e32 v69, v69, v141
	v_sub_f32_e32 v70, v70, v141
	v_sub_f32_e32 v71, v71, v141
	v_sub_f32_e32 v72, v72, v141
	v_sub_f32_e32 v73, v73, v141
	v_sub_f32_e32 v74, v74, v141
	v_sub_f32_e32 v75, v75, v141
	v_sub_f32_e32 v76, v76, v141
	v_sub_f32_e32 v77, v77, v141
	v_sub_f32_e32 v78, v78, v141
	v_sub_f32_e32 v79, v79, v141
	v_sub_f32_e32 v80, v80, v141
	v_sub_f32_e32 v81, v81, v141
	v_sub_f32_e32 v82, v82, v141
	v_sub_f32_e32 v83, v83, v141
	v_sub_f32_e32 v84, v84, v141
	v_sub_f32_e32 v85, v85, v141
	v_sub_f32_e32 v86, v86, v141
	v_sub_f32_e32 v87, v87, v141
	v_sub_f32_e32 v88, v88, v141
	v_sub_f32_e32 v89, v89, v141
	v_sub_f32_e32 v90, v90, v141
	v_sub_f32_e32 v91, v91, v141
	v_sub_f32_e32 v92, v92, v141
	v_sub_f32_e32 v93, v93, v141
	v_sub_f32_e32 v94, v94, v141
	v_sub_f32_e32 v95, v95, v141
	s_and_saveexec_b64 s[16:17], s[6:7]
	ds_write_b32 v178, v228 offset:128
	s_or_b64 exec, exec, s[16:17]
	s_waitcnt lgkmcnt(0)
	v_add_u32_e32 v142, v171, v177
	ds_read_b128 v[104:107], v142 offset:224
	ds_read_b128 v[108:111], v142 offset:192
	ds_read_b128 v[112:115], v142 offset:160
	ds_read_b128 v[116:119], v142 offset:128
	s_waitcnt lgkmcnt(0)
	v_pk_mul_f32 v[12:13], v[12:13], v[104:105]
	v_pk_mul_f32 v[8:9], v[8:9], v[108:109]
	v_pk_mul_f32 v[4:5], v[4:5], v[112:113]
	v_pk_mul_f32 v[14:15], v[14:15], v[106:107]
	v_pk_mul_f32 v[10:11], v[10:11], v[110:111]
	v_pk_mul_f32 v[6:7], v[6:7], v[114:115]
	v_pk_mul_f32 v[2:3], v[2:3], v[118:119]
	v_pk_mul_f32 v[0:1], v[0:1], v[116:117]
	v_pk_mul_f32 v[60:61], v[60:61], v[104:105]
	v_pk_mul_f32 v[56:57], v[56:57], v[108:109]
	v_pk_mul_f32 v[52:53], v[52:53], v[112:113]
	v_pk_mul_f32 v[62:63], v[62:63], v[106:107]
	v_pk_mul_f32 v[58:59], v[58:59], v[110:111]
	v_pk_mul_f32 v[54:55], v[54:55], v[114:115]
	v_pk_mul_f32 v[50:51], v[50:51], v[118:119]
	v_pk_mul_f32 v[48:49], v[48:49], v[116:117]
	v_pk_mul_f32 v[28:29], v[28:29], v[104:105]
	v_pk_mul_f32 v[24:25], v[24:25], v[108:109]
	v_pk_mul_f32 v[20:21], v[20:21], v[112:113]
	v_pk_mul_f32 v[30:31], v[30:31], v[106:107]
	v_pk_mul_f32 v[26:27], v[26:27], v[110:111]
	v_pk_mul_f32 v[22:23], v[22:23], v[114:115]
	v_pk_mul_f32 v[18:19], v[18:19], v[118:119]
	v_pk_mul_f32 v[16:17], v[16:17], v[116:117]
	v_pk_mul_f32 v[44:45], v[44:45], v[104:105]
	v_pk_mul_f32 v[40:41], v[40:41], v[108:109]
	v_pk_mul_f32 v[36:37], v[36:37], v[112:113]
	v_pk_mul_f32 v[46:47], v[46:47], v[106:107]
	v_pk_mul_f32 v[42:43], v[42:43], v[110:111]
	v_pk_mul_f32 v[38:39], v[38:39], v[114:115]
	v_pk_mul_f32 v[34:35], v[34:35], v[118:119]
	v_pk_mul_f32 v[32:33], v[32:33], v[116:117]
	ds_read_b128 v[104:107], v173 offset:9216
	ds_read_b128 v[108:111], v176 offset:9216
	ds_read_b128 v[112:115], v173 offset:9728
	ds_read_b128 v[148:151], v173 offset:11264
	ds_read_b128 v[152:155], v176 offset:10240
	ds_read_b128 v[156:159], v173 offset:11776
	ds_read_b128 v[214:217], v173 offset:15360
	ds_read_b128 v[218:221], v176 offset:13312
	ds_read_b128 v[222:225], v173 offset:15872
	v_exp_f32_e32 v64, v64
	v_exp_f32_e32 v65, v65
	v_exp_f32_e32 v66, v66
	v_exp_f32_e32 v67, v67
	v_exp_f32_e32 v68, v68
	v_exp_f32_e32 v69, v69
	v_exp_f32_e32 v70, v70
	v_exp_f32_e32 v71, v71
	v_exp_f32_e32 v72, v72
	v_exp_f32_e32 v73, v73
	v_exp_f32_e32 v74, v74
	v_exp_f32_e32 v75, v75
	v_exp_f32_e32 v76, v76
	v_exp_f32_e32 v77, v77
	v_exp_f32_e32 v78, v78
	v_exp_f32_e32 v79, v79
	s_branch .Ljoin_b1

; #define SBAR() __builtin_amdgcn_sched_barrier(0)
; #define LSUM() do { lsum = MFMA8(ones8, pa, (f32x16{})); } while (0)
; #define LUPD(al) do { l_reg = l_reg * (al) + lsum[0]; } while (0)
; DEVINL void mla_block(const Params& p, const bf16_t* __restrict__ Qn, const bf16_t* __restrict__ Qr, const char* __restrict__ K8, const char* __restrict__ Kp8,
;                       const char* __restrict__ V8, const bf16_t* __restrict__ Gb, bf16_t* __restrict__ Yb, char* lds, int pos0) {
;     ...
;   pv_load(vf, VS(NT - 1), r32, hi); SBAR();
;   finishSM<false>(pA0, pA1, alA, l_reg, pa); SBAR();
;   pv_mma(o, vf, pa); LSUM(); LUPD(alA);
.Lexit_glue:
	s_waitcnt lgkmcnt(0)
	s_nop 7
	v_fma_f32 v180, v226, v180, v144
	v_mov_b32_e32 v198, v228
	v_mov_b32_e32 v186, v79
	v_mov_b32_e32 v185, v78
	v_mov_b32_e32 v190, v77
	v_mov_b32_e32 v188, v76
	v_mov_b32_e32 v184, v75
	v_mov_b32_e32 v183, v74
	v_mov_b32_e32 v194, v73
	v_mov_b32_e32 v193, v72
	v_mov_b32_e32 v192, v71
	v_mov_b32_e32 v191, v70
	v_mov_b32_e32 v196, v69
	v_mov_b32_e32 v195, v68
	v_mov_b32_e32 v189, v67
	v_mov_b32_e32 v187, v66
	v_mov_b32_e32 v197, v65
	v_mov_b32_e32 v65, v64
	v_mov_b32_e32 v160, v80
	v_mov_b32_e32 v161, v81
	v_mov_b32_e32 v158, v82
	v_mov_b32_e32 v159, v83
	v_mov_b32_e32 v156, v86
	v_mov_b32_e32 v157, v87
	v_mov_b32_e32 v154, v88
	v_mov_b32_e32 v155, v89
	v_mov_b32_e32 v152, v90
	v_mov_b32_e32 v153, v91
	v_mov_b32_e32 v150, v92
	v_mov_b32_e32 v151, v93
	v_mov_b32_e32 v148, v94
	v_mov_b32_e32 v149, v95
	v_mov_b32_e32 v82, v84
	v_mov_b32_e32 v83, v85
